# attention: the 4 per-head sink values fetched once per phase by scalar loads (SGPRs) instead of a global_load_dword + vmcnt(0) inside each QK MFMA chain (8 sites)
# baseline (speedup 1.0000x reference)
; #define LAS __attribute__((address_space(3)))
; #define LAS __attribute__((address_space(3)))
; template <bool DO_SWA, bool DO_MEM>
; __device__ __forceinline__ void attn_unit(const Args& a, unsigned char* ws, LAS unsigned char* lds, int l, int tid_in, int lane_in, int wave, int unit) {
;     const bf16* UB = (const bf16*)(ws + WS_UB); const bf16* VTG = (const bf16*)(ws + WS_VTG);
;     const bf16* CWK = (const bf16*)(ws + WS_CWK); const bf16* CWVT = (const bf16*)(ws + WS_CWVT);
;     bf16* MIX = (bf16*)(ws + WS_MIX);
;     const int qs = wave & 3, g = wave >> 2;
;     LAS float* red_a = (LAS float*)(lds + A_RED); LAS float* red_m = red_a + 128;
;     {
;         int tid = tid_in, lane = lane_in;
;         asm volatile("" : "+v"(tid), "+v"(lane));
;         const int fr = lane & 15, fq = lane >> 4;
;         const bool is_s = unit >= 256;
;         const int bb = is_s ? 8 + (unit - 256) : (unit >> 5), c = is_s ? 0 : (unit & 31), sb = unit - 256;
;         const int row0 = is_s ? MP + sb * 64 : bb * SEQ + c * 64;
;     ...
;                 const float sk = a.in[12][l * 8 + h] * LOG2E;
.LBB0_251:
	s_and_b64 vcc, exec, s[0:1]
	s_cbranch_vccz .LBB0_443
	v_readlane_b32 s0, v255, 21
	s_cmp_gt_i32 s0, 0
	s_mov_b64 s[0:1], -1
	s_cbranch_scc0 .LBB0_441
	v_readlane_b32 s0, v251, 19
	v_readlane_b32 s1, v251, 20
	s_andn2_b64 vcc, exec, s[0:1]
	s_cbranch_vccnz .LBB0_294
	s_add_u32 s7, s48, 0x8800000
	s_addc_u32 s24, s49, 0
	s_add_u32 s26, s48, 0x9c00000
	s_addc_u32 s27, s49, 0
	s_add_u32 s38, s48, 0xbd00000
	s_addc_u32 s39, s49, 0
	s_add_u32 s16, s48, 0xb800000
	s_addc_u32 s17, s49, 0
	s_add_u32 s28, s48, 0xb000000
	s_addc_u32 s29, s49, 0
	s_add_u32 s30, s48, 0xb400000
	v_readlane_b32 s0, v255, 19
	s_addc_u32 s31, s49, 0
	s_mov_b32 s2, s0
	s_add_u32 s20, s48, 0xef00000
	v_readlane_b32 s1, v255, 20
	s_mul_i32 s25, s0, 40
	s_addc_u32 s21, s49, 0
	s_lshl_b32 s41, s0, 5
	s_mulk_i32 s0, 0x300
	s_lshl_b32 s2, s2, 3
	v_readlane_b32 s3, v251, 27
	s_mov_b64 s[94:95], s[54:55]
	s_ashr_i32 s1, s0, 31
	s_add_i32 s2, s2, s3
	s_mov_b64 s[92:93], s[52:53]
	v_readlane_b32 s44, v252, 3
	s_ashr_i32 s3, s2, 31
	s_lshl_b64 s[0:1], s[0:1], 2
	v_readlane_b32 s54, v252, 13
	v_readlane_b32 s55, v252, 14
	s_add_u32 s10, s54, s0
	v_readlane_b32 s52, v252, 11
	s_addc_u32 s11, s55, s1
	s_lshl_b64 s[0:1], s[2:3], 2
	v_readlane_b32 s48, v252, 7
	v_readlane_b32 s49, v252, 8
	v_readlane_b32 s53, v252, 12
	s_add_u32 s12, s52, s0
	v_readlane_b32 s56, v252, 15
	v_readlane_b32 s57, v252, 16
	v_readlane_b32 s58, v252, 17
	v_readlane_b32 s59, v252, 18
	v_readlane_b32 s48, v255, 23
	s_addc_u32 s13, s53, s1
	s_load_dwordx2 s[98:99], s[12:13], 0x0
	s_load_dwordx2 s[100:101], s[12:13], 0x8
	s_mov_b64 s[52:53], s[92:93]
	v_readlane_b32 s49, v255, 24
	v_readlane_b32 s57, v255, 15
	v_readlane_b32 s56, v255, 14
	v_readlane_b32 s59, v255, 10
	v_readlane_b32 s58, v255, 9
	s_mov_b64 s[54:55], s[94:95]
	s_add_i32 s40, s25, 0xfffffee8
	s_addk_i32 s41, 0xff00
	v_readlane_b32 s92, v254, 49
	v_readlane_b32 s93, v254, 29
	v_readlane_b32 s94, v251, 0
	v_readlane_b32 s45, v252, 4
	v_readlane_b32 s46, v252, 5
	v_readlane_b32 s47, v252, 6
	v_readlane_b32 s50, v252, 9
	v_readlane_b32 s51, v252, 10
	s_waitcnt lgkmcnt(0)
	s_branch .LBB0_257

; __device__ __forceinline__ unsigned pk2(float lo, float hi) { return pg8::cvt_pk_bf16(lo, hi); }
; template <bool DO_SWA, bool DO_MEM>
; __device__ __forceinline__ void attn_unit(const Args& a, unsigned char* ws, LAS unsigned char* lds, int l, int tid_in, int lane_in, int wave, int unit) {
;     ...
;             const bf16* ub = UB + (size_t)(row0 + t0) * UBW;
; #pragma unroll
;             for (int r = 0; r < 6; ++r) {
;                 if (r >= 2 || tg > 0 || !first) cu[r] = __builtin_nontemporal_load((const v4u*)(ub + (ptrdiff_t)(r - 2) * UBW + 896 + ch));
;                 else if (is_s) { const float* sp = a.in[5] + (size_t)(l * NBS + sb) * 512 + r * 256 + ch; const f32x4 s0 = *(const f32x4*)sp, s1 = *(const f32x4*)(sp + 4);
;                                  cu[r] = (v4u){pk2(s0[0], s0[1]), pk2(s0[2], s0[3]), pk2(s1[0], s1[1]), pk2(s1[2], s1[3])}; }
;                 else cu[r] = zero4;
;             }
; #pragma unroll
;             for (int i = 0; i < 4; ++i) ccb[i] = __builtin_nontemporal_load((const v4u*)(ub + (size_t)i * UBW + 640 + ch));
;         }
;         __builtin_amdgcn_sched_barrier(0);
;         if constexpr (DO_SWA) {
;             float w0[8], w1[8], w2[8];
; #pragma unroll
;             for (int j = 0; j < 4; ++j) { w0[j] = cwv[0][j]; w0[4 + j] = cwv[1][j]; w1[j] = cwv[2][j]; w1[4 + j] = cwv[3][j]; w2[j] = cwv[4][j]; w2[4 + j] = cwv[5][j]; }
; #pragma unroll
;             for (int i = 0; i < 4; ++i) {
;                 float ua[8], ub_[8], uc[8], cbv[8], cy[8];
;                 unpack8(cu[i], ua); unpack8(cu[i + 1], ub_); unpack8(cu[i + 2], uc); unpack8(ccb[i], cbv);
;                 float ss = 0.f;
; #pragma unroll
;                 for (int j = 0; j < 8; ++j) { const float y = ua[j] * w0[j] + ub_[j] * w1[j] + uc[j] * w2[j]; cy[j] = cbv[j] * y; ss += cy[j] * cy[j]; }
.LBB0_272:
	s_or_b64 exec, exec, s[2:3]
	v_lshl_add_u64 v[108:109], v[104:105], 0, v[184:185]
	s_movk_i32 s0, 0x1000
	v_add_co_u32_e32 v110, vcc, s0, v108
	s_movk_i32 s0, 0x2000
	s_nop 0
	v_addc_co_u32_e32 v111, vcc, 0, v109, vcc
	v_add_co_u32_e32 v150, vcc, s0, v108
	v_ashrrev_i32_e32 v169, 31, v168
	s_nop 0
	v_addc_co_u32_e32 v151, vcc, 0, v109, vcc
	global_load_dwordx4 v[104:107], v[110:111], off offset:3328 nt
	global_load_dwordx4 v[116:119], v[110:111], off offset:2816
	global_load_dwordx4 v[124:127], v[110:111], off offset:512 nt
	global_load_dwordx4 v[176:179], v[110:111], off
	global_load_dwordx4 v[180:183], v[108:109], off offset:1792 nt
	global_load_dwordx4 v[146:149], v[108:109], off offset:1280
	global_load_dwordx4 v[112:115], v[150:151], off offset:1536
	s_nop 0
	global_load_dwordx4 v[108:111], v[150:151], off offset:2048 nt
	s_waitcnt vmcnt(0)
	v_lshlrev_b32_e32 v173, 16, v180
	v_lshlrev_b32_e32 v172, 16, v128
	v_mov_b32_e32 v174, v92
	v_mov_b32_e32 v175, v100
	v_pk_mul_f32 v[198:199], v[174:175], v[172:173]
	v_lshlrev_b32_e32 v155, 16, v182
	v_and_b32_e32 v151, 0xffff0000, v182
	v_lshlrev_b32_e32 v182, 16, v120
	v_lshlrev_b64 v[214:215], 11, v[168:169]
	v_fma_f32 v168, v96, v182, v198
	v_lshlrev_b32_e32 v190, 16, v146
	v_lshlrev_b32_e32 v217, 16, v147
	v_and_b32_e32 v220, 0xffff0000, v147
	v_lshlrev_b32_e32 v162, 16, v129
	v_and_b32_e32 v158, 0xffff0000, v129
	v_lshlrev_b32_e32 v147, 16, v183
	v_and_b32_e32 v129, 0xffff0000, v183
	v_lshlrev_b32_e32 v183, 16, v124
	v_add_f32_e32 v168, v168, v199
	v_and_b32_e32 v167, 0xffff0000, v180
	v_and_b32_e32 v166, 0xffff0000, v128
	v_mov_b32_e32 v170, v93
	v_mov_b32_e32 v171, v101
	v_mul_f32_e32 v190, v168, v190
	v_pk_mul_f32 v[168:169], v[174:175], v[182:183]
	v_and_b32_e32 v191, 0xffff0000, v146
	v_lshlrev_b32_e32 v223, 16, v148
	v_and_b32_e32 v224, 0xffff0000, v148
	v_lshlrev_b32_e32 v225, 16, v149
	v_and_b32_e32 v226, 0xffff0000, v149
	v_pk_mul_f32 v[200:201], v[170:171], v[166:167]
	v_lshlrev_b32_e32 v146, 16, v131
	v_mov_b32_e32 v148, v82
	v_mov_b32_e32 v149, v90
	v_fma_f32 v168, v96, v173, v168
	v_and_b32_e32 v180, 0xffff0000, v120
	v_lshlrev_b32_e32 v163, 16, v181
	v_and_b32_e32 v159, 0xffff0000, v181
	v_pk_mul_f32 v[210:211], v[148:149], v[146:147]
	v_lshlrev_b32_e32 v146, 16, v176
	v_add_f32_e32 v168, v168, v169
	v_and_b32_e32 v181, 0xffff0000, v124
	v_fma_f32 v120, v97, v180, v200
	v_mul_f32_e32 v146, v168, v146
	v_add_f32_e32 v120, v120, v201
	v_pk_mul_f32 v[168:169], v[170:171], v[180:181]
	v_mov_b32_e32 v164, v94
	v_mov_b32_e32 v165, v102
	v_lshlrev_b32_e32 v154, 16, v130
	v_mov_b32_e32 v156, v80
	v_mov_b32_e32 v157, v88
	v_mul_f32_e32 v182, v120, v191
	v_fma_f32 v120, v97, v167, v168
	v_pk_mul_f32 v[202:203], v[164:165], v[162:163]
	v_pk_mul_f32 v[206:207], v[156:157], v[154:155]
	v_and_b32_e32 v154, 0xffff0000, v176
	v_lshlrev_b32_e32 v227, 16, v178
	v_and_b32_e32 v228, 0xffff0000, v178
	v_add_f32_e32 v120, v120, v169
	v_lshlrev_b32_e32 v178, 16, v121
	v_lshlrev_b32_e32 v229, 16, v179
	v_and_b32_e32 v230, 0xffff0000, v179
	v_mul_f32_e32 v154, v120, v154
	v_lshlrev_b32_e32 v179, 16, v125
	v_fma_f32 v120, v98, v178, v202
	v_add_f32_e32 v120, v120, v203
	v_pk_mul_f32 v[168:169], v[164:165], v[178:179]
	v_mov_b32_e32 v160, v95
	v_mov_b32_e32 v161, v103
	v_mul_f32_e32 v200, v120, v217
	v_fma_f32 v120, v98, v163, v168
	v_pk_mul_f32 v[204:205], v[160:161], v[158:159]
	v_lshlrev_b32_e32 v162, 16, v177
	v_add_f32_e32 v120, v120, v169
	v_and_b32_e32 v176, 0xffff0000, v121
	v_mul_f32_e32 v162, v120, v162
	v_fma_f32 v120, v99, v176, v204
	v_add_f32_e32 v120, v120, v205
	v_lshlrev_b32_e32 v124, 16, v122
	v_and_b32_e32 v150, 0xffff0000, v130
	v_mov_b32_e32 v152, v81
	v_mov_b32_e32 v153, v89
	v_mul_f32_e32 v178, v120, v220
	v_fma_f32 v120, v84, v124, v206
	v_pk_mul_f32 v[208:209], v[152:153], v[150:151]
	v_and_b32_e32 v172, 0xffff0000, v177
	v_and_b32_e32 v177, 0xffff0000, v125
	v_add_f32_e32 v120, v120, v207
	v_and_b32_e32 v122, 0xffff0000, v122
	v_pk_mul_f32 v[198:199], v[160:161], v[176:177]
	v_mul_f32_e32 v176, v120, v223
	v_fma_f32 v120, v85, v122, v208
	v_mul_f32_e32 v191, v182, v182
	v_add_f32_e32 v120, v120, v209
	v_lshlrev_b32_e32 v168, 16, v123
	v_fmac_f32_e32 v191, v190, v190
	v_mul_f32_e32 v201, v120, v224
	v_fma_f32 v120, v86, v168, v210
	v_and_b32_e32 v128, 0xffff0000, v131
	v_mov_b32_e32 v130, v83
	v_mov_b32_e32 v131, v91
	v_fmac_f32_e32 v191, v200, v200
	v_add_f32_e32 v120, v120, v211
	v_and_b32_e32 v137, 64, v222
	v_pk_mul_f32 v[212:213], v[130:131], v[128:129]
	v_fmac_f32_e32 v191, v178, v178
	v_mul_f32_e32 v202, v120, v225
	v_and_b32_e32 v120, 0xffff0000, v123
	v_xor_b32_e32 v135, 1, v222
	v_add_u32_e32 v137, 64, v137
	v_fmac_f32_e32 v191, v176, v176
	v_fma_f32 v121, v87, v120, v212
	v_cmp_lt_i32_e32 vcc, v135, v137
	v_fmac_f32_e32 v191, v201, v201
	v_add_f32_e32 v121, v121, v213
	v_cndmask_b32_e32 v135, v222, v135, vcc
	v_fmac_f32_e32 v191, v202, v202
	v_mul_f32_e32 v203, v121, v226
	v_lshlrev_b32_e32 v145, 2, v135
	v_fmac_f32_e32 v191, v203, v203
	ds_bpermute_b32 v121, v145, v191
	v_xor_b32_e32 v135, 2, v222
	v_cmp_lt_i32_e32 vcc, v135, v137
	v_fma_f32 v123, v99, v159, v198
	v_add_f32_e32 v123, v123, v199
	v_cndmask_b32_e32 v135, v222, v135, vcc
	v_lshlrev_b32_e32 v143, 2, v135
	s_waitcnt lgkmcnt(0)
	v_add_f32_e32 v121, v191, v121
	v_mul_f32_e32 v172, v123, v172
	ds_bpermute_b32 v123, v143, v121
	v_xor_b32_e32 v135, 4, v222
	v_cmp_lt_i32_e32 vcc, v135, v137
	v_lshlrev_b32_e32 v125, 16, v126
	v_pk_mul_f32 v[198:199], v[156:157], v[124:125]
	v_cndmask_b32_e32 v135, v222, v135, vcc
	v_lshlrev_b32_e32 v141, 2, v135
	s_waitcnt lgkmcnt(0)
; __device__ __forceinline__ unsigned pk2(float lo, float hi) { return pg8::cvt_pk_bf16(lo, hi); }
; template <bool DO_SWA, bool DO_MEM>
; __device__ __forceinline__ void attn_unit(const Args& a, unsigned char* ws, LAS unsigned char* lds, int l, int tid_in, int lane_in, int wave, int unit) {
;     ...
; #pragma unroll
;             for (int i = 0; i < 4; ++i) {
;                 float ua[8], ub_[8], uc[8], cbv[8], cy[8];
;                 unpack8(cu[i], ua); unpack8(cu[i + 1], ub_); unpack8(cu[i + 2], uc); unpack8(ccb[i], cbv);
;                 float ss = 0.f;
; #pragma unroll
;                 for (int j = 0; j < 8; ++j) { const float y = ua[j] * w0[j] + ub_[j] * w1[j] + uc[j] * w2[j]; cy[j] = cbv[j] * y; ss += cy[j] * cy[j]; }
;                 ss += __shfl_xor(ss, 1); ss += __shfl_xor(ss, 2); ss += __shfl_xor(ss, 4); ss += __shfl_xor(ss, 8); ss += __shfl_xor(ss, 16);
;                 const float rs = 1.0f / sqrtf(ss * (1.0f / 256.0f) + EPS);
;                 v4u o; o.x = pk2(cy[0] * rs, cy[1] * rs); o.y = pk2(cy[2] * rs, cy[3] * rs); o.z = pk2(cy[4] * rs, cy[5] * rs); o.w = pk2(cy[6] * rs, cy[7] * rs);
;                 *(v4u*)(MIX + (size_t)(row0 + t0 + i) * D + 512 + ch) = o;
	v_add_f32_e32 v121, v121, v123
	ds_bpermute_b32 v169, v141, v121
	v_xor_b32_e32 v135, 8, v222
	v_cmp_lt_i32_e32 vcc, v135, v137
	v_fma_f32 v124, v84, v155, v198
	v_and_b32_e32 v123, 0xffff0000, v126
	v_cndmask_b32_e32 v135, v222, v135, vcc
	v_lshlrev_b32_e32 v139, 2, v135
	s_waitcnt lgkmcnt(0)
	v_add_f32_e32 v121, v121, v169
	v_add_f32_e32 v124, v124, v199
	v_pk_mul_f32 v[198:199], v[152:153], v[122:123]
	ds_bpermute_b32 v122, v139, v121
	v_xor_b32_e32 v135, 16, v222
	v_cmp_lt_i32_e32 vcc, v135, v137
	s_mov_b32 s2, 0xf800000
	v_fma_f32 v126, v85, v151, v198
	v_cndmask_b32_e32 v135, v222, v135, vcc
	v_lshlrev_b32_e32 v135, 2, v135
	s_waitcnt lgkmcnt(0)
	v_add_f32_e32 v121, v121, v122
	ds_bpermute_b32 v122, v135, v121
	v_lshlrev_b32_e32 v169, 16, v127
	v_add_f32_e32 v126, v126, v199
	v_pk_mul_f32 v[198:199], v[148:149], v[168:169]
	v_mul_f32_e32 v191, v126, v228
	s_waitcnt lgkmcnt(0)
	v_add_f32_e32 v121, v121, v122
	v_fmamk_f32 v121, v121, 0x3b800000, v218
	v_mul_f32_e32 v122, 0x4f800000, v121
	v_cmp_gt_f32_e32 vcc, s2, v121
	v_fma_f32 v126, v86, v147, v198
	v_add_f32_e32 v126, v126, v199
	v_cndmask_b32_e32 v122, v121, v122, vcc
	v_sqrt_f32_e32 v168, v122
	v_mul_f32_e32 v204, v126, v229
	v_and_b32_e32 v121, 0xffff0000, v127
	v_mul_f32_e32 v180, v154, v154
	v_add_u32_e32 v126, -1, v168
	v_fma_f32 v127, -v126, v168, v122
	v_cmp_ge_f32_e64 s[0:1], 0, v127
	v_add_u32_e32 v127, 1, v168
	v_fmac_f32_e32 v180, v146, v146
	v_cndmask_b32_e64 v126, v168, v126, s[0:1]
	v_fma_f32 v168, -v127, v168, v122
	v_cmp_lt_f32_e64 s[0:1], 0, v168
	v_fmac_f32_e32 v180, v162, v162
	v_fmac_f32_e32 v180, v172, v172
	v_cndmask_b32_e64 v126, v126, v127, s[0:1]
	v_mul_f32_e32 v127, 0x37800000, v126
	v_cndmask_b32_e32 v126, v126, v127, vcc
	v_cmp_class_f32_e32 vcc, v122, v219
	v_mul_f32_e32 v124, v124, v227
	v_fmac_f32_e32 v180, v124, v124
	v_cndmask_b32_e32 v122, v126, v122, vcc
	v_pk_mul_f32 v[126:127], v[130:131], v[120:121]
	v_fmac_f32_e32 v180, v191, v191
	v_fma_f32 v120, v87, v129, v126
	v_add_f32_e32 v120, v120, v127
	v_fmac_f32_e32 v180, v204, v204
	v_mul_f32_e32 v120, v120, v230
	v_fmac_f32_e32 v180, v120, v120
	ds_bpermute_b32 v199, v145, v180
	v_div_scale_f32 v168, s[0:1], v122, v122, 1.0
	v_rcp_f32_e32 v198, v168
	v_lshl_add_u64 v[126:127], s[20:21], 0, v[214:215]
	s_waitcnt lgkmcnt(0)
	v_add_f32_e32 v180, v180, v199
	ds_bpermute_b32 v199, v143, v180
	v_fma_f32 v205, -v168, v198, 1.0
	v_fmac_f32_e32 v198, v205, v198
	v_div_scale_f32 v205, vcc, 1.0, v122, 1.0
	s_waitcnt lgkmcnt(0)
	v_add_f32_e32 v180, v180, v199
	ds_bpermute_b32 v199, v141, v180
	v_mul_f32_e32 v206, v205, v198
	v_fma_f32 v207, -v168, v206, v205
	v_fmac_f32_e32 v206, v207, v198
	v_fma_f32 v168, -v168, v206, v205
	s_waitcnt lgkmcnt(0)
	v_add_f32_e32 v180, v180, v199
	ds_bpermute_b32 v199, v139, v180
	v_div_fmas_f32 v168, v168, v198, v206
	v_div_fixup_f32 v122, v168, v122, 1.0
	v_mul_f32_e32 v168, v190, v122
	v_mul_f32_e32 v182, v182, v122
	v_cvt_pk_bf16_f32 v198, v168, v182
	s_waitcnt lgkmcnt(0)
	v_add_f32_e32 v168, v180, v199
	ds_bpermute_b32 v180, v135, v168
	v_mul_f32_e32 v178, v178, v122
	v_mul_f32_e32 v182, v200, v122
	v_cvt_pk_bf16_f32 v199, v182, v178
	v_mul_f32_e32 v176, v176, v122
	s_waitcnt lgkmcnt(0)
	v_add_f32_e32 v168, v168, v180
	v_fmamk_f32 v168, v168, 0x3b800000, v218
	v_mul_f32_e32 v178, 0x4f800000, v168
	v_cmp_gt_f32_e32 vcc, s2, v168
	v_mul_f32_e32 v180, v201, v122
	v_cvt_pk_bf16_f32 v200, v176, v180
	v_mul_f32_e32 v176, v202, v122
	v_cndmask_b32_e32 v168, v168, v178, vcc
	v_sqrt_f32_e32 v178, v168
	v_mul_f32_e32 v122, v203, v122
	v_cvt_pk_bf16_f32 v201, v176, v122
	v_lshl_add_u64 v[126:127], v[126:127], 0, v[184:185]
	v_add_u32_e32 v180, -1, v178
	v_fma_f32 v182, -v180, v178, v168
	v_cmp_ge_f32_e64 s[0:1], 0, v182
	v_add_u32_e32 v182, 1, v178
	global_store_dwordx4 v[126:127], v[198:201], off offset:1024
	v_cndmask_b32_e64 v180, v178, v180, s[0:1]
	v_fma_f32 v178, -v182, v178, v168
	v_cmp_lt_f32_e64 s[0:1], 0, v178
	v_lshlrev_b32_e32 v176, 16, v114
	s_movk_i32 s3, 0x190
	v_cndmask_b32_e64 v178, v180, v182, s[0:1]
	v_mul_f32_e32 v180, 0x37800000, v178
	v_cndmask_b32_e32 v178, v178, v180, vcc
	v_cmp_class_f32_e32 vcc, v168, v219
	v_and_b32_e32 v182, 0xffff0000, v115
	s_nop 0
	v_cndmask_b32_e32 v168, v178, v168, vcc
	v_div_scale_f32 v178, s[0:1], v168, v168, 1.0
	v_rcp_f32_e32 v180, v178
	s_nop 0
	v_fma_f32 v122, -v178, v180, 1.0
	v_fmac_f32_e32 v180, v122, v180
	v_div_scale_f32 v122, vcc, 1.0, v168, 1.0
	v_mul_f32_e32 v126, v122, v180
	v_fma_f32 v127, -v178, v126, v122
	v_fmac_f32_e32 v126, v127, v180
	v_fma_f32 v122, -v178, v126, v122
	v_div_fmas_f32 v122, v122, v180, v126
	v_div_fixup_f32 v122, v122, v168, 1.0
	v_mul_f32_e32 v126, v146, v122
	v_mul_f32_e32 v127, v154, v122
	v_cvt_pk_bf16_f32 v198, v126, v127
	v_mul_f32_e32 v126, v162, v122
	v_mul_f32_e32 v127, v172, v122
	v_lshlrev_b32_e32 v154, 16, v112
	v_and_b32_e32 v162, 0xffff0000, v112
	v_lshlrev_b32_e32 v168, 16, v113
	v_and_b32_e32 v172, 0xffff0000, v113
	v_lshlrev_b32_e32 v112, 16, v104
	v_lshlrev_b32_e32 v113, 16, v108
	v_and_b32_e32 v178, 0xffff0000, v114
	v_lshlrev_b32_e32 v180, 16, v115
	v_pk_mov_b32 v[114:115], v[172:173], v[112:113] op_sel:[1,0]
	v_mul_f32_e32 v124, v124, v122
	v_pk_mul_f32 v[114:115], v[174:175], v[114:115]
	v_mul_f32_e32 v120, v120, v122
	v_fma_f32 v114, v96, v183, v114
	v_cvt_pk_bf16_f32 v199, v126, v127
	v_mul_f32_e32 v126, v191, v122
	v_cvt_pk_bf16_f32 v200, v124, v126
	v_mul_f32_e32 v124, v204, v122
	v_cvt_pk_bf16_f32 v201, v124, v120
	v_lshlrev_b32_e32 v120, 16, v116
	v_add_f32_e32 v114, v114, v115
	v_mul_f32_e32 v120, v114, v120
	v_mov_b32_e32 v114, v96
	v_mov_b32_e32 v115, v100
; __device__ __forceinline__ unsigned pk2(float lo, float hi) { return pg8::cvt_pk_bf16(lo, hi); }
; template <bool DO_SWA, bool DO_MEM>
; __device__ __forceinline__ void attn_unit(const Args& a, unsigned char* ws, LAS unsigned char* lds, int l, int tid_in, int lane_in, int wave, int unit) {
;     ...
; #pragma unroll
;             for (int i = 0; i < 4; ++i) {
;                 float ua[8], ub_[8], uc[8], cbv[8], cy[8];
;                 unpack8(cu[i], ua); unpack8(cu[i + 1], ub_); unpack8(cu[i + 2], uc); unpack8(ccb[i], cbv);
;                 float ss = 0.f;
; #pragma unroll
;                 for (int j = 0; j < 8; ++j) { const float y = ua[j] * w0[j] + ub_[j] * w1[j] + uc[j] * w2[j]; cy[j] = cbv[j] * y; ss += cy[j] * cy[j]; }
;                 ss += __shfl_xor(ss, 1); ss += __shfl_xor(ss, 2); ss += __shfl_xor(ss, 4); ss += __shfl_xor(ss, 8); ss += __shfl_xor(ss, 16);
;                 const float rs = 1.0f / sqrtf(ss * (1.0f / 256.0f) + EPS);
;                 v4u o; o.x = pk2(cy[0] * rs, cy[1] * rs); o.y = pk2(cy[2] * rs, cy[3] * rs); o.z = pk2(cy[4] * rs, cy[5] * rs); o.w = pk2(cy[6] * rs, cy[7] * rs);
;                 *(v4u*)(MIX + (size_t)(row0 + t0 + i) * D + 512 + ch) = o;
	v_pk_mul_f32 v[112:113], v[114:115], v[112:113]
	v_mov_b32_e32 v100, v97
	v_fma_f32 v92, v92, v183, v112
	v_add_f32_e32 v92, v92, v113
	v_and_b32_e32 v113, 0xffff0000, v108
	v_and_b32_e32 v112, 0xffff0000, v104
	v_pk_mov_b32 v[114:115], v[166:167], v[112:113] op_sel:[1,0]
	v_mul_f32_e32 v154, v92, v154
	v_pk_mul_f32 v[114:115], v[170:171], v[114:115]
	v_and_b32_e32 v122, 0xffff0000, v116
	v_fma_f32 v92, v97, v181, v114
	v_add_f32_e32 v92, v92, v115
	v_pk_mul_f32 v[96:97], v[100:101], v[112:113]
	v_mul_f32_e32 v104, v92, v122
	v_fma_f32 v92, v93, v181, v96
	v_add_f32_e32 v92, v92, v97
	v_mul_f32_e32 v112, v92, v162
	v_lshlrev_b32_e32 v92, 16, v105
	v_lshlrev_b32_e32 v93, 16, v109
	v_pk_mov_b32 v[96:97], v[162:163], v[92:93] op_sel:[1,0]
	v_lshlrev_b32_e32 v124, 16, v117
	v_pk_mul_f32 v[96:97], v[164:165], v[96:97]
	v_add_u32_e32 v126, -2, v144
	v_fma_f32 v96, v98, v179, v96
	v_add_f32_e32 v96, v96, v97
	v_mul_f32_e32 v114, v96, v124
	v_mov_b32_e32 v96, v98
	v_mov_b32_e32 v97, v102
	v_pk_mul_f32 v[92:93], v[96:97], v[92:93]
	v_ashrrev_i32_e32 v127, 31, v126
	v_fma_f32 v92, v94, v179, v92
	v_add_f32_e32 v92, v92, v93
	v_mul_f32_e32 v115, v92, v168
	v_and_b32_e32 v93, 0xffff0000, v109
	v_and_b32_e32 v92, 0xffff0000, v105
	v_lshlrev_b64 v[126:127], 11, v[126:127]
	v_pk_mov_b32 v[96:97], v[158:159], v[92:93] op_sel:[1,0]
	v_lshl_add_u64 v[126:127], s[20:21], 0, v[126:127]
	v_pk_mul_f32 v[96:97], v[160:161], v[96:97]
	v_lshl_add_u64 v[126:127], v[126:127], 0, v[184:185]
	v_fma_f32 v94, v99, v177, v96
	v_mov_b32_e32 v102, v99
	global_store_dwordx4 v[126:127], v[198:201], off offset:1024
	v_and_b32_e32 v126, 0xffff0000, v117
	v_add_f32_e32 v94, v94, v97
	v_pk_mul_f32 v[92:93], v[102:103], v[92:93]
	v_mul_f32_e32 v105, v94, v126
	v_fma_f32 v92, v95, v177, v92
	v_lshlrev_b32_e32 v94, 16, v106
	v_lshlrev_b32_e32 v95, 16, v110
	v_pk_mov_b32 v[96:97], v[154:155], v[94:95] op_sel:[1,0]
	v_lshlrev_b32_e32 v127, 16, v118
	v_pk_mul_f32 v[96:97], v[156:157], v[96:97]
	v_and_b32_e32 v118, 0xffff0000, v118
	v_fma_f32 v96, v84, v125, v96
	v_add_f32_e32 v96, v96, v97
	v_mul_f32_e32 v109, v96, v127
	v_and_b32_e32 v97, 0xffff0000, v110
	v_and_b32_e32 v96, 0xffff0000, v106
	v_pk_mov_b32 v[98:99], v[150:151], v[96:97] op_sel:[1,0]
	v_lshlrev_b32_e32 v146, 16, v119
	v_pk_mul_f32 v[98:99], v[152:153], v[98:99]
	v_mul_f32_e32 v108, v104, v104
	v_fma_f32 v98, v85, v123, v98
	v_add_f32_e32 v98, v98, v99
	v_mul_f32_e32 v106, v98, v118
	v_lshlrev_b32_e32 v98, 16, v107
	v_lshlrev_b32_e32 v99, 16, v111
	v_pk_mov_b32 v[100:101], v[146:147], v[98:99] op_sel:[1,0]
	v_fmac_f32_e32 v108, v120, v120
	v_pk_mul_f32 v[100:101], v[148:149], v[100:101]
	v_fmac_f32_e32 v108, v114, v114
	v_fma_f32 v100, v86, v169, v100
	v_add_f32_e32 v100, v100, v101
	v_mul_f32_e32 v110, v100, v146
	v_and_b32_e32 v101, 0xffff0000, v111
	v_and_b32_e32 v100, 0xffff0000, v107
	v_pk_mov_b32 v[102:103], v[128:129], v[100:101] op_sel:[1,0]
	v_fmac_f32_e32 v108, v105, v105
	v_pk_mul_f32 v[102:103], v[130:131], v[102:103]
	v_fmac_f32_e32 v108, v109, v109
	v_fma_f32 v102, v87, v121, v102
	v_and_b32_e32 v119, 0xffff0000, v119
	v_fmac_f32_e32 v108, v106, v106
	v_add_f32_e32 v102, v102, v103
	v_fmac_f32_e32 v108, v110, v110
	v_mul_f32_e32 v102, v102, v119
	v_fmac_f32_e32 v108, v102, v102
	ds_bpermute_b32 v103, v145, v108
	v_add_f32_e32 v92, v92, v93
	v_mul_f32_e32 v107, v92, v172
	v_mov_b32_e32 v92, v84
	v_mov_b32_e32 v93, v88
	s_waitcnt lgkmcnt(0)
	v_add_f32_e32 v84, v108, v103
	ds_bpermute_b32 v103, v143, v84
	v_pk_mul_f32 v[92:93], v[92:93], v[94:95]
	v_mov_b32_e32 v88, v85
	v_fma_f32 v80, v80, v125, v92
	v_add_f32_e32 v80, v80, v93
	s_waitcnt lgkmcnt(0)
	v_add_f32_e32 v92, v84, v103
	ds_bpermute_b32 v93, v141, v92
	v_mul_f32_e32 v94, v80, v176
	v_pk_mul_f32 v[84:85], v[88:89], v[96:97]
	v_mul_f32_e32 v113, v112, v112
	v_fma_f32 v81, v81, v123, v84
	s_waitcnt lgkmcnt(0)
	v_add_f32_e32 v80, v92, v93
	ds_bpermute_b32 v88, v139, v80
	v_add_f32_e32 v81, v81, v85
	v_mul_f32_e32 v89, v81, v178
	v_mov_b32_e32 v81, v90
	v_fmac_f32_e32 v113, v154, v154
	s_waitcnt lgkmcnt(0)
	v_add_f32_e32 v84, v80, v88
	ds_bpermute_b32 v85, v135, v84
	v_mov_b32_e32 v80, v86
	v_pk_mul_f32 v[80:81], v[80:81], v[98:99]
	v_fmac_f32_e32 v113, v115, v115
	v_fma_f32 v80, v82, v169, v80
	s_waitcnt lgkmcnt(0)
	v_add_f32_e32 v82, v84, v85
	v_fmamk_f32 v82, v82, 0x3b800000, v218
	v_mul_f32_e32 v84, 0x4f800000, v82
	v_cmp_gt_f32_e32 vcc, s2, v82
	v_add_f32_e32 v80, v80, v81
	v_mul_f32_e32 v86, v80, v180
	v_cndmask_b32_e32 v82, v82, v84, vcc
	v_sqrt_f32_e32 v84, v82
	v_mov_b32_e32 v90, v87
	v_fmac_f32_e32 v113, v107, v107
	v_fmac_f32_e32 v113, v94, v94
	v_add_u32_e32 v80, -1, v84
	v_fma_f32 v81, -v80, v84, v82
	v_cmp_ge_f32_e64 s[0:1], 0, v81
	v_add_u32_e32 v81, 1, v84
	v_fmac_f32_e32 v113, v89, v89
	v_cndmask_b32_e64 v80, v84, v80, s[0:1]
	v_fma_f32 v84, -v81, v84, v82
	v_cmp_lt_f32_e64 s[0:1], 0, v84
	v_fmac_f32_e32 v113, v86, v86
	v_add_u32_e32 v116, -1, v144
	v_cndmask_b32_e64 v80, v80, v81, s[0:1]
	v_mul_f32_e32 v81, 0x37800000, v80
	v_cndmask_b32_e32 v80, v80, v81, vcc
	v_cmp_class_f32_e32 vcc, v82, v219
	v_ashrrev_i32_e32 v117, 31, v116
	v_lshlrev_b64 v[116:117], 11, v[116:117]
	v_cndmask_b32_e32 v82, v80, v82, vcc
	v_pk_mul_f32 v[80:81], v[90:91], v[100:101]
	v_div_scale_f32 v88, s[0:1], v82, v82, 1.0
	v_fma_f32 v80, v83, v121, v80
	v_add_f32_e32 v80, v80, v81
	v_mul_f32_e32 v87, v80, v182
	v_fmac_f32_e32 v113, v87, v87
	v_rcp_f32_e32 v92, v88
	ds_bpermute_b32 v83, v145, v113
	v_lshl_add_u64 v[80:81], s[20:21], 0, v[116:117]
	v_lshl_add_u64 v[84:85], v[80:81], 0, v[184:185]
	v_fma_f32 v80, -v88, v92, 1.0
	v_fmac_f32_e32 v92, v80, v92
	s_waitcnt lgkmcnt(0)
; #define LAS __attribute__((address_space(3)))
; #define LAS __attribute__((address_space(3)))
; __device__ __forceinline__ unsigned pk2(float lo, float hi) { return pg8::cvt_pk_bf16(lo, hi); }
; __device__ __forceinline__ f32x4 mfma16(bf16x8 a, bf16x8 b, f32x4 c) { return __builtin_amdgcn_mfma_f32_16x16x32_bf16(a, b, c, 0, 0, 0); }
; template <int NKT, int VSTR, bool SINK>
; __device__ __forceinline__ void attn_core(LAS const unsigned char* kb_, LAS const unsigned char* vb_, bf16x8 q0, bf16x8 q1, float sk, unsigned mskbits, int fr, f32x4 (&o)[4]) {
;     ...
;     for (int kt = 0; kt < NKT; ++kt) {
;         const int key = (kt >> 1) * 32 + ((kt & 1) << 2) + krow;
;         LAS const unsigned char* kp = kb_ + key * 144;
;         const bf16x8 a0 = *(LAS const bf16x8*)kp, a1 = *(LAS const bf16x8*)(kp + 64);
;         const float bias = ((mskbits >> (kt >> 2)) & 1u) ? -1e30f : 0.f;
;         f32x4 s = mfma16(a0, q0, (f32x4){bias, bias, bias, bias});
;         s = mfma16(a1, q1, s);
; template <bool DO_SWA, bool DO_MEM>
; __device__ __forceinline__ void attn_unit(const Args& a, unsigned char* ws, LAS unsigned char* lds, int l, int tid_in, int lane_in, int wave, int unit) {
;     ...
;                 for (int j = 0; j < 8; ++j) { const float y = ua[j] * w0[j] + ub_[j] * w1[j] + uc[j] * w2[j]; cy[j] = cbv[j] * y; ss += cy[j] * cy[j]; }
;                 ss += __shfl_xor(ss, 1); ss += __shfl_xor(ss, 2); ss += __shfl_xor(ss, 4); ss += __shfl_xor(ss, 8); ss += __shfl_xor(ss, 16);
;                 const float rs = 1.0f / sqrtf(ss * (1.0f / 256.0f) + EPS);
;                 v4u o; o.x = pk2(cy[0] * rs, cy[1] * rs); o.y = pk2(cy[2] * rs, cy[3] * rs); o.z = pk2(cy[4] * rs, cy[5] * rs); o.w = pk2(cy[6] * rs, cy[7] * rs);
;                 *(v4u*)(MIX + (size_t)(row0 + t0 + i) * D + 512 + ch) = o;
;             }
;         }
;         if constexpr (DO_SWA)
; #pragma unroll
;         for (int i = 0; i < 6; ++i) {
;             const int s = i >> 1, rem = tid + 512 * (i & 1);
;             { const int key = rem >> 4, c16 = rem & 15; *(LAS v4u*)(lds + A_KS + ((c16 >> 3) * 192 + s * 64 + key) * 144 + (c16 & 7) * 16) = kst[i]; }
;             { const int col = rem >> 3, kc = rem & 7; *(LAS v4u*)(lds + A_VT1 + col * 400 + (s * 64 + kc * 8) * 2) = vst[i]; }
;         }
	v_add_f32_e32 v80, v113, v83
	ds_bpermute_b32 v81, v143, v80
	v_div_scale_f32 v83, vcc, 1.0, v82, 1.0
	v_mul_f32_e32 v90, v83, v92
	v_fma_f32 v91, -v88, v90, v83
	s_waitcnt lgkmcnt(0)
	v_add_f32_e32 v80, v80, v81
	ds_bpermute_b32 v81, v141, v80
	v_fmac_f32_e32 v90, v91, v92
	v_fma_f32 v83, -v88, v90, v83
	v_div_fmas_f32 v83, v83, v92, v90
	v_div_fixup_f32 v83, v83, v82, 1.0
	s_waitcnt lgkmcnt(0)
	v_add_f32_e32 v81, v80, v81
	ds_bpermute_b32 v88, v139, v81
	v_mul_f32_e32 v80, v120, v83
	v_mul_f32_e32 v82, v104, v83
	v_cvt_pk_bf16_f32 v80, v80, v82
	v_mul_f32_e32 v90, v105, v83
	s_waitcnt lgkmcnt(0)
	v_add_f32_e32 v82, v81, v88
	ds_bpermute_b32 v88, v135, v82
	v_mul_f32_e32 v81, v114, v83
	v_cvt_pk_bf16_f32 v81, v81, v90
	v_mul_f32_e32 v90, v109, v83
	v_ashrrev_i32_e32 v145, 31, v144
	s_waitcnt lgkmcnt(0)
	v_add_f32_e32 v82, v82, v88
	v_fmamk_f32 v82, v82, 0x3b800000, v218
	v_mul_f32_e32 v88, 0x4f800000, v82
	v_cmp_gt_f32_e32 vcc, s2, v82
	s_movk_i32 s2, 0x90
	s_nop 0
	v_cndmask_b32_e32 v88, v82, v88, vcc
	v_sqrt_f32_e32 v91, v88
	v_mul_f32_e32 v82, v106, v83
	v_cvt_pk_bf16_f32 v82, v90, v82
	v_mul_f32_e32 v90, v110, v83
	v_add_u32_e32 v92, -1, v91
	v_fma_f32 v93, -v92, v91, v88
	v_cmp_ge_f32_e64 s[0:1], 0, v93
	v_add_u32_e32 v93, 1, v91
	v_mul_f32_e32 v83, v102, v83
	v_cndmask_b32_e64 v92, v91, v92, s[0:1]
	v_fma_f32 v91, -v93, v91, v88
	v_cmp_lt_f32_e64 s[0:1], 0, v91
	v_cvt_pk_bf16_f32 v83, v90, v83
	global_store_dwordx4 v[84:85], v[80:83], off offset:1024
	s_nop 0
	v_cndmask_b32_e64 v91, v92, v93, s[0:1]
	v_mul_f32_e32 v92, 0x37800000, v91
	v_cndmask_b32_e32 v91, v91, v92, vcc
	v_cmp_class_f32_e32 vcc, v88, v219
	s_nop 1
	v_cndmask_b32_e32 v88, v91, v88, vcc
	v_div_scale_f32 v91, s[0:1], v88, v88, 1.0
	v_rcp_f32_e32 v92, v91
	s_nop 0
	v_fma_f32 v80, -v91, v92, 1.0
	v_fmac_f32_e32 v92, v80, v92
	v_div_scale_f32 v80, vcc, 1.0, v88, 1.0
	v_mul_f32_e32 v81, v80, v92
	v_fma_f32 v82, -v91, v81, v80
	v_fmac_f32_e32 v81, v82, v92
	v_fma_f32 v80, -v91, v81, v80
	v_div_fmas_f32 v80, v80, v92, v81
	v_div_fixup_f32 v83, v80, v88, 1.0
	v_mul_f32_e32 v80, v154, v83
	v_mul_f32_e32 v81, v112, v83
	v_cvt_pk_bf16_f32 v80, v80, v81
	v_mul_f32_e32 v81, v115, v83
	v_mul_f32_e32 v82, v107, v83
	v_cvt_pk_bf16_f32 v81, v81, v82
	v_mul_f32_e32 v82, v94, v83
	v_mul_f32_e32 v84, v89, v83
	v_cvt_pk_bf16_f32 v82, v82, v84
	v_mul_f32_e32 v84, v86, v83
	v_mul_f32_e32 v83, v87, v83
	v_cvt_pk_bf16_f32 v83, v84, v83
	v_lshlrev_b64 v[84:85], 11, v[144:145]
	v_lshl_add_u64 v[84:85], s[20:21], 0, v[84:85]
	v_lshl_add_u64 v[84:85], v[84:85], 0, v[184:185]
	global_store_dwordx4 v[84:85], v[80:83], off offset:1024
	s_nop 1
	v_bfe_i32 v80, v196, 3, 1
	v_and_b32_e32 v81, 0xc0, v80
	v_and_b32_e32 v80, 0x70, v197
	v_add_u32_e32 v80, 0, v80
	v_add_u32_e32 v82, v81, v134
	v_mad_u64_u32 v[82:83], s[0:1], v82, s2, v[80:81]
	ds_write_b128 v82, v[36:39]
	v_mul_lo_u32 v36, v140, s3
	v_add3_u32 v36, 0, v36, v138
	ds_write_b128 v36, v[32:35] offset:55296
	v_add_u32_e32 v32, v81, v136
	v_mad_u64_u32 v[32:33], s[0:1], v32, s2, v[80:81]
	ds_write_b128 v32, v[56:59]
	v_mul_lo_u32 v32, v142, s3
	v_add_u32_e32 v35, 64, v81
	v_add3_u32 v34, 0, v32, v138
	v_add_u32_e32 v32, v35, v134
	v_mad_u64_u32 v[32:33], s[0:1], v32, s2, v[80:81]
	ds_write_b128 v34, v[68:71] offset:55296
	ds_write_b128 v32, v[52:55]
	ds_write_b128 v36, v[40:43] offset:55424
	v_add_u32_e32 v32, v35, v136
	v_mad_u64_u32 v[32:33], s[0:1], v32, s2, v[80:81]
	v_add_u32_e32 v35, 0x80, v81
	ds_write_b128 v32, v[44:47]
	ds_write_b128 v34, v[48:51] offset:55424
	v_add_u32_e32 v32, v35, v134
	v_mad_u64_u32 v[32:33], s[0:1], v32, s2, v[80:81]
	ds_write_b128 v32, v[60:63]
	ds_write_b128 v36, v[64:67] offset:55552
	v_add_u32_e32 v32, v35, v136
	v_mad_u64_u32 v[32:33], s[0:1], v32, s2, v[80:81]
	ds_write_b128 v32, v[72:75]
	ds_write_b128 v34, v[76:79] offset:55552
	v_readlane_b32 s0, v251, 22
	v_and_b32_e32 v32, -16, v133
	v_and_b32_e32 v34, 3, v133
	v_or_b32_e32 v33, s0, v195
	v_mul_lo_u32 v33, v33, s3
	v_add3_u32 v78, 0, v33, v32
	v_lshlrev_b32_e32 v33, 1, v195
	v_and_or_b32 v33, v33, 24, v34
	v_mul_u32_u24_e32 v33, 0x90, v33
	v_readlane_b32 s0, v251, 24
	s_waitcnt lgkmcnt(0)
	s_barrier
	v_add3_u32 v79, s0, v32, v33
	v_xor_b32_e32 v32, 32, v222
	v_cmp_lt_i32_e32 vcc, v32, v137
	v_mov_b32_e32 v80, s98
	s_nop 0
	v_cndmask_b32_e32 v32, v222, v32, vcc
	v_lshlrev_b32_e32 v76, 2, v32
	s_waitcnt lgkmcnt(0)
	ds_read_b128 v[92:95], v79
	ds_read_b128 v[196:199], v79 offset:64
	ds_read_b128 v[200:203], v79 offset:576
	ds_read_b128 v[204:207], v79 offset:640
	ds_read_b128 v[208:211], v79 offset:4608
	ds_read_b128 v[212:215], v79 offset:4672
	ds_read_b128 v[228:231], v79 offset:5184
	ds_read_b128 v[232:235], v79 offset:5248
	ds_read_b128 v[236:239], v79 offset:9216
	ds_read_b128 v[240:243], v79 offset:9280
	ds_read_b128 v[244:247], v79 offset:9792
	s_waitcnt lgkmcnt(10)
	v_mfma_f32_16x16x32_bf16 v[32:35], v[92:95], v[24:27], 0
	s_mov_b32 s2, 0x3fb8aa3b
	v_add_u32_e32 v77, 0xd800, v78

; #define LAS __attribute__((address_space(3)))
; #define LAS __attribute__((address_space(3)))
; __device__ __forceinline__ f32x4 mfma16(bf16x8 a, bf16x8 b, f32x4 c) { return __builtin_amdgcn_mfma_f32_16x16x32_bf16(a, b, c, 0, 0, 0); }
; template <int NKT, int VSTR, bool SINK>
; __device__ __forceinline__ void attn_core(LAS const unsigned char* kb_, LAS const unsigned char* vb_, bf16x8 q0, bf16x8 q1, float sk, unsigned mskbits, int fr, f32x4 (&o)[4]) {
;     ...
;     for (int kt = 0; kt < NKT; ++kt) {
;         const int key = (kt >> 1) * 32 + ((kt & 1) << 2) + krow;
;         LAS const unsigned char* kp = kb_ + key * 144;
;         const bf16x8 a0 = *(LAS const bf16x8*)kp, a1 = *(LAS const bf16x8*)(kp + 64);
;         const float bias = ((mskbits >> (kt >> 2)) & 1u) ? -1e30f : 0.f;
;         f32x4 s = mfma16(a0, q0, (f32x4){bias, bias, bias, bias});
;         s = mfma16(a1, q1, s);
;         S[kt] = s;
;     }
;     float mx = S[0][0];
; #pragma unroll
;     for (int kt = 0; kt < NKT; ++kt) mx = fmaxf(fmaxf(mx, fmaxf(S[kt][0], S[kt][1])), fmaxf(S[kt][2], S[kt][3]));
;     mx = fmaxf(mx, __shfl_xor(mx, 16)); mx = fmaxf(mx, __shfl_xor(mx, 32));
	v_mul_f32_e32 v81, 0x3fb8aa3b, v80
	s_waitcnt lgkmcnt(9)
	v_mfma_f32_16x16x32_bf16 v[72:75], v[196:199], v[28:31], v[32:35]
	ds_read_b128 v[92:95], v79 offset:9856
	ds_read_b128 v[196:199], v79 offset:13824
	s_waitcnt lgkmcnt(10)
	v_mfma_f32_16x16x32_bf16 v[32:35], v[200:203], v[24:27], 0
	s_waitcnt lgkmcnt(9)
	v_mfma_f32_16x16x32_bf16 v[68:71], v[204:207], v[28:31], v[32:35]
	ds_read_b128 v[200:203], v79 offset:13888
	ds_read_b128 v[204:207], v79 offset:14400
	s_waitcnt lgkmcnt(10)
	v_mfma_f32_16x16x32_bf16 v[32:35], v[208:211], v[24:27], 0
	s_waitcnt lgkmcnt(9)
	v_mfma_f32_16x16x32_bf16 v[64:67], v[212:215], v[28:31], v[32:35]
	ds_read_b128 v[208:211], v79 offset:14464
	ds_read_b128 v[212:215], v79 offset:18432
	s_waitcnt lgkmcnt(10)
	v_mfma_f32_16x16x32_bf16 v[32:35], v[228:231], v[24:27], 0
	s_waitcnt lgkmcnt(9)
	v_mfma_f32_16x16x32_bf16 v[60:63], v[232:235], v[28:31], v[32:35]
	ds_read_b128 v[228:231], v79 offset:18496
	ds_read_b128 v[232:235], v79 offset:19008
	s_waitcnt lgkmcnt(10)
	v_mfma_f32_16x16x32_bf16 v[32:35], v[236:239], v[24:27], 0
	s_waitcnt lgkmcnt(9)
	v_mfma_f32_16x16x32_bf16 v[56:59], v[240:243], v[28:31], v[32:35]
	ds_read_b128 v[236:239], v79 offset:19072
	ds_read_b128 v[240:243], v79 offset:23040
	s_waitcnt lgkmcnt(10)
	v_mfma_f32_16x16x32_bf16 v[32:35], v[244:247], v[24:27], 0
	s_waitcnt lgkmcnt(9)
	v_mfma_f32_16x16x32_bf16 v[52:55], v[92:95], v[28:31], v[32:35]
	ds_read_b128 v[244:247], v79 offset:23104
	ds_read_b128 v[92:95], v79 offset:23616
	s_waitcnt lgkmcnt(10)
	v_mfma_f32_16x16x32_bf16 v[32:35], v[196:199], v[24:27], 0
	s_waitcnt lgkmcnt(9)
	v_mfma_f32_16x16x32_bf16 v[48:51], v[200:203], v[28:31], v[32:35]
	ds_read_b128 v[196:199], v79 offset:23680
	s_waitcnt lgkmcnt(9)
	v_mfma_f32_16x16x32_bf16 v[32:35], v[204:207], v[24:27], 0
	s_waitcnt lgkmcnt(8)
	v_mfma_f32_16x16x32_bf16 v[44:47], v[208:211], v[28:31], v[32:35]
	s_waitcnt lgkmcnt(7)
	v_mfma_f32_16x16x32_bf16 v[32:35], v[212:215], v[24:27], 0
	s_waitcnt lgkmcnt(6)
	v_mfma_f32_16x16x32_bf16 v[40:43], v[228:231], v[28:31], v[32:35]
	s_waitcnt lgkmcnt(5)
	v_mfma_f32_16x16x32_bf16 v[32:35], v[232:235], v[24:27], 0
	s_waitcnt lgkmcnt(4)
	v_mfma_f32_16x16x32_bf16 v[36:39], v[236:239], v[28:31], v[32:35]
	s_waitcnt lgkmcnt(3)
	v_mfma_f32_16x16x32_bf16 v[32:35], v[240:243], v[24:27], 0
	s_waitcnt lgkmcnt(2)
	v_mfma_f32_16x16x32_bf16 v[32:35], v[244:247], v[28:31], v[32:35]
	s_waitcnt lgkmcnt(1)
	v_mfma_f32_16x16x32_bf16 v[24:27], v[92:95], v[24:27], 0
	s_waitcnt lgkmcnt(0)
	v_mfma_f32_16x16x32_bf16 v[24:27], v[196:199], v[28:31], v[24:27]
	v_max_f32_e32 v28, v75, v75
	v_max_f32_e32 v29, v74, v74
	v_max_f32_e32 v28, v29, v28
	v_max_f32_e32 v29, v69, v69
	v_max_f32_e32 v30, v68, v68
	v_max_f32_e32 v29, v30, v29
	v_max_f32_e32 v30, v71, v71
	v_max_f32_e32 v31, v70, v70
	v_max3_f32 v28, v72, v73, v28
	v_max_f32_e32 v30, v31, v30
	v_max3_f32 v28, v28, v29, v30
	v_max_f32_e32 v29, v65, v65
	v_max_f32_e32 v30, v64, v64
	v_max_f32_e32 v29, v30, v29
	v_max_f32_e32 v30, v67, v67
	v_max_f32_e32 v31, v66, v66
	v_max_f32_e32 v30, v31, v30
	v_max3_f32 v28, v28, v29, v30
	v_max_f32_e32 v29, v61, v61
	v_max_f32_e32 v30, v60, v60
	v_max_f32_e32 v29, v30, v29
	v_max_f32_e32 v30, v63, v63
	v_max_f32_e32 v31, v62, v62
	v_max_f32_e32 v30, v31, v30
	v_max3_f32 v28, v28, v29, v30
	v_max_f32_e32 v29, v57, v57
	v_max_f32_e32 v30, v56, v56
	v_max_f32_e32 v29, v30, v29
	v_max_f32_e32 v30, v59, v59
	v_max_f32_e32 v31, v58, v58
	v_max_f32_e32 v30, v31, v30
	v_max3_f32 v28, v28, v29, v30
	v_max_f32_e32 v29, v53, v53
	v_max_f32_e32 v30, v52, v52
	v_max_f32_e32 v29, v30, v29
	v_max_f32_e32 v30, v55, v55
	v_max_f32_e32 v31, v54, v54
	v_max_f32_e32 v30, v31, v30
	v_max3_f32 v28, v28, v29, v30
	v_max_f32_e32 v29, v49, v49
	v_max_f32_e32 v30, v48, v48
	v_max_f32_e32 v29, v30, v29
	v_max_f32_e32 v30, v51, v51
	v_max_f32_e32 v31, v50, v50
	v_max_f32_e32 v30, v31, v30
	v_max3_f32 v28, v28, v29, v30
	v_max_f32_e32 v29, v45, v45
	v_max_f32_e32 v30, v44, v44
	v_max_f32_e32 v29, v30, v29
	v_max_f32_e32 v30, v47, v47
	v_max_f32_e32 v31, v46, v46
	v_max_f32_e32 v30, v31, v30
	v_max3_f32 v28, v28, v29, v30
	v_max_f32_e32 v29, v41, v41
	v_max_f32_e32 v30, v40, v40
	v_max_f32_e32 v29, v30, v29
	v_max_f32_e32 v30, v43, v43
	v_max_f32_e32 v31, v42, v42
	v_max_f32_e32 v30, v31, v30
	v_max3_f32 v28, v28, v29, v30
	v_max_f32_e32 v29, v37, v37
	v_max_f32_e32 v30, v36, v36
	v_max_f32_e32 v29, v30, v29
	v_max_f32_e32 v30, v39, v39
	v_max_f32_e32 v31, v38, v38
	v_max_f32_e32 v30, v31, v30
	v_max3_f32 v28, v28, v29, v30
	v_max_f32_e32 v29, v33, v33
	v_max_f32_e32 v30, v32, v32
	v_max_f32_e32 v29, v30, v29
	v_max_f32_e32 v30, v35, v35
	v_max_f32_e32 v31, v34, v34
	v_max_f32_e32 v30, v31, v30
	v_max3_f32 v28, v28, v29, v30
	v_max_f32_e32 v29, v25, v25
	v_max_f32_e32 v30, v24, v24
	v_max_f32_e32 v29, v30, v29
	v_max_f32_e32 v30, v27, v27
	v_max_f32_e32 v31, v26, v26
	v_max_f32_e32 v30, v31, v30
	v_max3_f32 v28, v28, v29, v30
	ds_bpermute_b32 v29, v135, v28
	s_waitcnt lgkmcnt(0)
	v_max_f32_e32 v29, v29, v29
	v_max_f32_e32 v28, v28, v29
	ds_bpermute_b32 v29, v76, v28
	s_waitcnt lgkmcnt(0)
; __device__ __forceinline__ unsigned pk2(float lo, float hi) { return pg8::cvt_pk_bf16(lo, hi); }
; template <int NKT, int VSTR, bool SINK>
; __device__ __forceinline__ void attn_core(LAS const unsigned char* kb_, LAS const unsigned char* vb_, bf16x8 q0, bf16x8 q1, float sk, unsigned mskbits, int fr, f32x4 (&o)[4]) {
;     ...
;     for (int kt = 0; kt < NKT; ++kt) mx = fmaxf(fmaxf(mx, fmaxf(S[kt][0], S[kt][1])), fmaxf(S[kt][2], S[kt][3]));
;     mx = fmaxf(mx, __shfl_xor(mx, 16)); mx = fmaxf(mx, __shfl_xor(mx, 32));
;     if (SINK) mx = fmaxf(mx, sk);
;     float sum = 0.f;
; #pragma unroll
;     for (int kt = 0; kt < NKT; ++kt)
; #pragma unroll
;         for (int r = 0; r < 4; ++r) { const float p = __builtin_amdgcn_exp2f(S[kt][r] - mx); S[kt][r] = p; sum += p; }
;     sum += __shfl_xor(sum, 16); sum += __shfl_xor(sum, 32);
;     if (SINK) sum += __builtin_amdgcn_exp2f(sk - mx);
;     const float inv = 1.0f / sum;
;     bf16x8 pf[NKT / 2];
; #pragma unroll
;     for (int kb = 0; kb < NKT / 2; ++kb) {
;         v4u w; w.x = pk2(S[2 * kb][0], S[2 * kb][1]); w.y = pk2(S[2 * kb][2], S[2 * kb][3]); w.z = pk2(S[2 * kb + 1][0], S[2 * kb + 1][1]); w.w = pk2(S[2 * kb + 1][2], S[2 * kb + 1][3]);
;         pf[kb] = __builtin_bit_cast(bf16x8, w);
;     }
	v_max3_f32 v28, v28, v29, v81
	v_sub_f32_e32 v29, v72, v28
	v_exp_f32_e32 v29, v29
	v_sub_f32_e32 v31, v73, v28
	v_exp_f32_e32 v31, v31
	v_sub_f32_e32 v72, v74, v28
	v_exp_f32_e32 v72, v72
	v_sub_f32_e32 v73, v75, v28
	v_exp_f32_e32 v73, v73
	v_sub_f32_e32 v68, v68, v28
	v_add_f32_e32 v30, 0, v29
	v_exp_f32_e32 v68, v68
	v_sub_f32_e32 v69, v69, v28
	v_add_f32_e32 v30, v31, v30
	v_exp_f32_e32 v69, v69
	v_sub_f32_e32 v70, v70, v28
	v_add_f32_e32 v30, v72, v30
	v_exp_f32_e32 v70, v70
	v_sub_f32_e32 v71, v71, v28
	v_add_f32_e32 v30, v73, v30
	v_exp_f32_e32 v71, v71
	v_sub_f32_e32 v64, v64, v28
	v_add_f32_e32 v30, v68, v30
	v_exp_f32_e32 v64, v64
	v_sub_f32_e32 v65, v65, v28
	v_add_f32_e32 v30, v69, v30
	v_exp_f32_e32 v65, v65
	v_sub_f32_e32 v66, v66, v28
	v_add_f32_e32 v30, v70, v30
	v_exp_f32_e32 v66, v66
	v_sub_f32_e32 v67, v67, v28
	v_add_f32_e32 v30, v71, v30
	v_exp_f32_e32 v67, v67
	v_sub_f32_e32 v60, v60, v28
	v_add_f32_e32 v30, v64, v30
	v_exp_f32_e32 v60, v60
	v_sub_f32_e32 v61, v61, v28
	v_add_f32_e32 v30, v65, v30
	v_exp_f32_e32 v61, v61
	v_sub_f32_e32 v62, v62, v28
	v_add_f32_e32 v30, v66, v30
	v_exp_f32_e32 v62, v62
	v_sub_f32_e32 v63, v63, v28
	v_add_f32_e32 v30, v67, v30
	v_exp_f32_e32 v63, v63
	v_sub_f32_e32 v56, v56, v28
	v_add_f32_e32 v30, v60, v30
	v_exp_f32_e32 v56, v56
	v_sub_f32_e32 v57, v57, v28
	v_add_f32_e32 v30, v61, v30
	v_exp_f32_e32 v57, v57
	v_sub_f32_e32 v58, v58, v28
	v_add_f32_e32 v30, v62, v30
	v_exp_f32_e32 v58, v58
	v_sub_f32_e32 v59, v59, v28
	v_add_f32_e32 v30, v63, v30
	v_exp_f32_e32 v59, v59
	v_sub_f32_e32 v52, v52, v28
	v_add_f32_e32 v30, v56, v30
	v_exp_f32_e32 v52, v52
	v_sub_f32_e32 v53, v53, v28
	v_add_f32_e32 v30, v57, v30
	v_exp_f32_e32 v53, v53
	v_sub_f32_e32 v54, v54, v28
	v_add_f32_e32 v30, v58, v30
	v_exp_f32_e32 v54, v54
	v_sub_f32_e32 v55, v55, v28
	v_add_f32_e32 v30, v59, v30
	v_exp_f32_e32 v55, v55
	v_sub_f32_e32 v48, v48, v28
	v_add_f32_e32 v30, v52, v30
	v_exp_f32_e32 v48, v48
	v_sub_f32_e32 v49, v49, v28
	v_add_f32_e32 v30, v53, v30
	v_exp_f32_e32 v49, v49
	v_sub_f32_e32 v50, v50, v28
	v_add_f32_e32 v30, v54, v30
	v_exp_f32_e32 v50, v50
	v_sub_f32_e32 v51, v51, v28
	v_add_f32_e32 v30, v55, v30
	v_exp_f32_e32 v51, v51
	v_sub_f32_e32 v44, v44, v28
	v_add_f32_e32 v30, v48, v30
	v_exp_f32_e32 v74, v44
	v_sub_f32_e32 v44, v45, v28
	v_add_f32_e32 v30, v49, v30
	v_exp_f32_e32 v75, v44
	v_sub_f32_e32 v44, v46, v28
	v_add_f32_e32 v30, v50, v30
	v_exp_f32_e32 v81, v44
	v_sub_f32_e32 v44, v47, v28
	v_add_f32_e32 v30, v51, v30
	v_exp_f32_e32 v82, v44
	v_sub_f32_e32 v40, v40, v28
	v_add_f32_e32 v30, v74, v30
	v_exp_f32_e32 v83, v40
	v_sub_f32_e32 v40, v41, v28
	v_add_f32_e32 v30, v75, v30
	v_exp_f32_e32 v84, v40
	v_sub_f32_e32 v40, v42, v28
	v_add_f32_e32 v30, v81, v30
	v_exp_f32_e32 v85, v40
	v_sub_f32_e32 v40, v43, v28
	v_add_f32_e32 v30, v82, v30
	v_exp_f32_e32 v86, v40
	v_sub_f32_e32 v36, v36, v28
	v_add_f32_e32 v30, v83, v30
	v_exp_f32_e32 v87, v36
	v_sub_f32_e32 v36, v37, v28
	v_add_f32_e32 v30, v84, v30
	v_exp_f32_e32 v88, v36
	v_sub_f32_e32 v36, v38, v28
	v_add_f32_e32 v30, v85, v30
	v_exp_f32_e32 v89, v36
	v_sub_f32_e32 v36, v39, v28
	v_add_f32_e32 v30, v86, v30
	v_exp_f32_e32 v90, v36
	v_sub_f32_e32 v32, v32, v28
	v_add_f32_e32 v30, v87, v30
	v_exp_f32_e32 v91, v32
	v_sub_f32_e32 v32, v33, v28
	v_add_f32_e32 v30, v88, v30
	v_exp_f32_e32 v92, v32
	v_sub_f32_e32 v32, v34, v28
	v_add_f32_e32 v30, v89, v30
	v_exp_f32_e32 v93, v32
	v_sub_f32_e32 v32, v35, v28
	v_add_f32_e32 v30, v90, v30
	v_exp_f32_e32 v94, v32
	v_sub_f32_e32 v24, v24, v28
	v_add_f32_e32 v30, v91, v30
	v_exp_f32_e32 v95, v24
	v_sub_f32_e32 v25, v25, v28
	v_add_f32_e32 v30, v92, v30
	v_exp_f32_e32 v96, v25
	v_sub_f32_e32 v25, v26, v28
	v_add_f32_e32 v30, v93, v30
	v_exp_f32_e32 v97, v25
	v_sub_f32_e32 v25, v27, v28
	v_add_f32_e32 v30, v94, v30
	v_exp_f32_e32 v27, v25
	v_add_f32_e32 v24, v95, v30
	v_add_f32_e32 v24, v96, v24
	v_add_f32_e32 v24, v97, v24
	v_add_f32_e32 v24, v27, v24
	ds_bpermute_b32 v25, v135, v24
	v_cvt_pk_bf16_f32 v44, v29, v31
	v_cvt_pk_bf16_f32 v45, v72, v73
	v_cvt_pk_bf16_f32 v46, v68, v69
	v_cvt_pk_bf16_f32 v47, v70, v71
	s_waitcnt lgkmcnt(0)
	v_add_f32_e32 v24, v24, v25
	ds_bpermute_b32 v25, v76, v24
	v_cvt_pk_bf16_f32 v40, v64, v65
	v_cvt_pk_bf16_f32 v41, v66, v67
	v_cvt_pk_bf16_f32 v42, v60, v61
	v_cvt_pk_bf16_f32 v43, v62, v63
	s_waitcnt lgkmcnt(0)
	v_add_f32_e32 v24, v24, v25
	v_fma_f32 v25, v80, s2, -v28
	v_exp_f32_e32 v25, v25
	v_cvt_pk_bf16_f32 v36, v56, v57
	v_cvt_pk_bf16_f32 v37, v58, v59
	v_cvt_pk_bf16_f32 v38, v52, v53
	v_cvt_pk_bf16_f32 v39, v54, v55
	v_cvt_pk_bf16_f32 v32, v48, v49
	s_nop 0
	v_add_f32_e32 v80, v25, v24
	v_div_scale_f32 v48, s[0:1], v80, v80, 1.0
	v_rcp_f32_e32 v49, v48
	v_cvt_pk_bf16_f32 v33, v50, v51
	v_cvt_pk_bf16_f32 v34, v74, v75
	v_cvt_pk_bf16_f32 v35, v81, v82
	v_cvt_pk_bf16_f32 v28, v83, v84
	v_cvt_pk_bf16_f32 v29, v85, v86
	s_nop 0
	v_fma_f32 v50, -v48, v49, 1.0
	v_fmac_f32_e32 v49, v50, v49
	v_div_scale_f32 v50, vcc, 1.0, v80, 1.0
	v_mul_f32_e32 v51, v50, v49
	v_fma_f32 v52, -v48, v51, v50
	v_fmac_f32_e32 v51, v52, v49
	v_fma_f32 v48, -v48, v51, v50
	v_cvt_pk_bf16_f32 v30, v87, v88
	v_cvt_pk_bf16_f32 v31, v89, v90
	v_cvt_pk_bf16_f32 v24, v91, v92
	v_cvt_pk_bf16_f32 v25, v93, v94
	v_cvt_pk_bf16_f32 v26, v95, v96
	v_cvt_pk_bf16_f32 v27, v97, v27
	v_div_fmas_f32 v48, v48, v49, v51
	s_waitcnt lgkmcnt(0)
; #define LAS __attribute__((address_space(3)))
; __device__ __forceinline__ float sq4(const f32x4 a) { return (a[0] * a[0] + a[1] * a[1]) + (a[2] * a[2] + a[3] * a[3]); }
; #define LAS __attribute__((address_space(3)))
; __device__ __forceinline__ unsigned pk2(float lo, float hi) { return pg8::cvt_pk_bf16(lo, hi); }
; __device__ __forceinline__ f32x4 mfma16(bf16x8 a, bf16x8 b, f32x4 c) { return __builtin_amdgcn_mfma_f32_16x16x32_bf16(a, b, c, 0, 0, 0); }
; template <int NKT, int VSTR, bool SINK>
; __device__ __forceinline__ void attn_core(LAS const unsigned char* kb_, LAS const unsigned char* vb_, bf16x8 q0, bf16x8 q1, float sk, unsigned mskbits, int fr, f32x4 (&o)[4]) {
;     ...
; #pragma unroll
;     for (int dt = 0; dt < 4; ++dt) {
;         f32x4 acc = (f32x4){0.f, 0.f, 0.f, 0.f};
; #pragma unroll
;         for (int kb = 0; kb < NKT / 2; ++kb) {
;             const bf16x8 vf = *(LAS const bf16x8*)(vb_ + dt * 16 * VSTR + kb * 64);
;             acc = mfma16(vf, pf[kb], acc);
;         }
;         o[dt] = acc * inv;
;     }
; template <bool DO_SWA, bool DO_MEM>
; __device__ __forceinline__ void attn_unit(const Args& a, unsigned char* ws, LAS unsigned char* lds, int l, int tid_in, int lane_in, int wave, int unit) {
;     ...
;                 const float sk = a.in[12][l * 8 + h] * LOG2E;
;                 f32x4 o[4];
;                 attn_core<12, 400, true>(lds + A_KS + g * 192 * 144 + fq * 16, lds + A_VT1 + (g * 64 + fr) * 400 + fq * 16, qsw[hh][0], qsw[hh][1], sk, mskbits, fr, o);
; #pragma unroll
;                 for (int dt = 0; dt < 4; ++dt) { ssq += pg8::sq4(o[dt]); osv[hh][dt] = (v2u){pk2(o[dt][0], o[dt][1]), pk2(o[dt][2], o[dt][3])}; }
	ds_read_b128 v[196:199], v78 offset:55296
	ds_read_b128 v[200:203], v78 offset:55360
	ds_read_b128 v[204:207], v78 offset:61760
	ds_read_b128 v[208:211], v77 offset:12864
	ds_read_b128 v[212:215], v78 offset:55424
	ds_read_b128 v[228:231], v78 offset:55488
	ds_read_b128 v[232:235], v78 offset:55552
	ds_read_b128 v[236:239], v78 offset:55616
	ds_read_b128 v[240:243], v78 offset:61696
	ds_read_b128 v[244:247], v78 offset:61824
	s_waitcnt lgkmcnt(9)
	v_mfma_f32_16x16x32_bf16 v[50:53], v[196:199], v[44:47], 0
	ds_read_b128 v[196:199], v78 offset:61888
	v_div_fixup_f32 v48, v48, v80, 1.0
	s_waitcnt lgkmcnt(9)
	v_mfma_f32_16x16x32_bf16 v[50:53], v[200:203], v[40:43], v[50:53]
	ds_read_b128 v[200:203], v78 offset:61952
	s_waitcnt lgkmcnt(7)
	v_mfma_f32_16x16x32_bf16 v[50:53], v[212:215], v[36:39], v[50:53]
	ds_read_b128 v[212:215], v78 offset:62016
	s_waitcnt lgkmcnt(7)
	v_mfma_f32_16x16x32_bf16 v[50:53], v[228:231], v[32:35], v[50:53]
	ds_read_b128 v[228:231], v77 offset:12800
	s_waitcnt lgkmcnt(7)
	v_mfma_f32_16x16x32_bf16 v[50:53], v[232:235], v[28:31], v[50:53]
	ds_read_b128 v[232:235], v77 offset:12928
	s_waitcnt lgkmcnt(7)
	v_mfma_f32_16x16x32_bf16 v[52:55], v[236:239], v[24:27], v[50:53]
	ds_read_b128 v[236:239], v77 offset:12992
	s_nop 7
	v_pk_mul_f32 v[50:51], v[54:55], v[48:49] op_sel_hi:[1,0]
	s_waitcnt lgkmcnt(7)
	v_mfma_f32_16x16x32_bf16 v[54:57], v[240:243], v[44:47], 0
	ds_read_b128 v[240:243], v77 offset:13056
	v_mul_f32_e64 v52, v52, v48
	v_mul_f32_e64 v53, v53, v48
	v_mfma_f32_16x16x32_bf16 v[54:57], v[204:207], v[40:43], v[54:57]
	ds_read_b128 v[204:207], v77 offset:13120
	s_waitcnt lgkmcnt(8)
	v_mfma_f32_16x16x32_bf16 v[54:57], v[244:247], v[36:39], v[54:57]
	ds_read_b128 v[244:247], v77 offset:19200
	s_waitcnt lgkmcnt(8)
	v_mfma_f32_16x16x32_bf16 v[54:57], v[196:199], v[32:35], v[54:57]
	ds_read_b128 v[196:199], v77 offset:19264
	s_waitcnt lgkmcnt(8)
	v_mfma_f32_16x16x32_bf16 v[54:57], v[200:203], v[28:31], v[54:57]
	ds_read_b128 v[200:203], v77 offset:19328
	s_waitcnt lgkmcnt(8)
	v_mfma_f32_16x16x32_bf16 v[56:59], v[212:215], v[24:27], v[54:57]
	s_nop 7
	v_pk_mul_f32 v[54:55], v[58:59], v[48:49] op_sel_hi:[1,0]
	ds_read_b128 v[212:215], v77 offset:19392
	s_waitcnt lgkmcnt(8)
	v_mfma_f32_16x16x32_bf16 v[58:61], v[228:231], v[44:47], 0
	v_mul_f32_e64 v56, v56, v48
	v_mul_f32_e64 v57, v57, v48
	v_mfma_f32_16x16x32_bf16 v[58:61], v[208:211], v[40:43], v[58:61]
	ds_read_b128 v[228:231], v77 offset:19456
	s_waitcnt lgkmcnt(8)
	v_mfma_f32_16x16x32_bf16 v[58:61], v[232:235], v[36:39], v[58:61]
	ds_read_b128 v[208:211], v77 offset:19520
	s_waitcnt lgkmcnt(8)
	v_mfma_f32_16x16x32_bf16 v[58:61], v[236:239], v[32:35], v[58:61]
	s_waitcnt lgkmcnt(7)
	v_mfma_f32_16x16x32_bf16 v[58:61], v[240:243], v[28:31], v[58:61]
	s_waitcnt lgkmcnt(6)
	v_mfma_f32_16x16x32_bf16 v[60:63], v[204:207], v[24:27], v[58:61]
	s_nop 7
	v_pk_mul_f32 v[58:59], v[48:49], v[62:63] op_sel_hi:[0,1]
	s_waitcnt lgkmcnt(5)
	v_mfma_f32_16x16x32_bf16 v[44:47], v[244:247], v[44:47], 0
	v_pk_mul_f32 v[60:61], v[48:49], v[60:61] op_sel_hi:[0,1]
	s_waitcnt lgkmcnt(4)
	v_mfma_f32_16x16x32_bf16 v[40:43], v[196:199], v[40:43], v[44:47]
	s_waitcnt lgkmcnt(3)
	v_mfma_f32_16x16x32_bf16 v[36:39], v[200:203], v[36:39], v[40:43]
	s_waitcnt lgkmcnt(2)
	v_mfma_f32_16x16x32_bf16 v[32:35], v[212:215], v[32:35], v[36:39]
	s_waitcnt lgkmcnt(1)
	v_mfma_f32_16x16x32_bf16 v[28:31], v[228:231], v[28:31], v[32:35]
	v_cvt_pk_bf16_f32 v69, v52, v53
	v_cvt_pk_bf16_f32 v68, v50, v51
	s_waitcnt lgkmcnt(0)
	v_mfma_f32_16x16x32_bf16 v[24:27], v[208:211], v[24:27], v[28:31]
	s_nop 2
	v_mul_f32_e32 v28, v53, v53
	v_mul_f32_e32 v29, v51, v51
	v_fmac_f32_e32 v28, v52, v52
	v_fmac_f32_e32 v29, v50, v50
	v_add_f32_e32 v28, v28, v29
	v_mul_f32_e32 v29, v57, v57
	v_mul_f32_e32 v30, v55, v55
	v_fmac_f32_e32 v29, v56, v56
	v_fmac_f32_e32 v30, v54, v54
	v_add_f32_e32 v29, v29, v30
	v_add_f32_e32 v28, v28, v29
	v_mul_f32_e32 v29, v61, v61
	v_mul_f32_e32 v30, v59, v59
	v_fmac_f32_e32 v29, v60, v60
	v_fmac_f32_e32 v30, v58, v58
	v_pk_mul_f32 v[26:27], v[48:49], v[26:27] op_sel_hi:[0,1]
	v_pk_mul_f32 v[24:25], v[48:49], v[24:25] op_sel_hi:[0,1]
	v_add_f32_e32 v29, v29, v30
	v_add_f32_e32 v28, v29, v28
	v_mul_f32_e32 v29, v25, v25
	v_mul_f32_e32 v30, v27, v27
	v_fmac_f32_e32 v29, v24, v24
	v_fmac_f32_e32 v30, v26, v26
	v_add_f32_e32 v29, v29, v30
	v_cvt_pk_bf16_f32 v71, v56, v57
	v_cvt_pk_bf16_f32 v70, v54, v55
	v_cvt_pk_bf16_f32 v73, v60, v61
	v_cvt_pk_bf16_f32 v72, v58, v59
	v_add_f32_e32 v80, v28, v29
	v_cvt_pk_bf16_f32 v75, v24, v25
	v_cvt_pk_bf16_f32 v74, v26, v27
	v_mov_b32_e32 v81, s99
	s_waitcnt lgkmcnt(0)
	ds_read_b128 v[92:95], v79
	ds_read_b128 v[196:199], v79 offset:64
	ds_read_b128 v[200:203], v79 offset:576
	ds_read_b128 v[204:207], v79 offset:640
	ds_read_b128 v[208:211], v79 offset:4608
	ds_read_b128 v[212:215], v79 offset:4672
	ds_read_b128 v[228:231], v79 offset:5184
	ds_read_b128 v[232:235], v79 offset:5248
	ds_read_b128 v[236:239], v79 offset:9216
	ds_read_b128 v[240:243], v79 offset:9280
	ds_read_b128 v[244:247], v79 offset:9792
	s_waitcnt lgkmcnt(10)
	v_mfma_f32_16x16x32_bf16 v[24:27], v[92:95], v[20:23], 0

; #define LAS __attribute__((address_space(3)))
; #define LAS __attribute__((address_space(3)))
; __device__ __forceinline__ f32x4 mfma16(bf16x8 a, bf16x8 b, f32x4 c) { return __builtin_amdgcn_mfma_f32_16x16x32_bf16(a, b, c, 0, 0, 0); }
; template <int NKT, int VSTR, bool SINK>
; __device__ __forceinline__ void attn_core(LAS const unsigned char* kb_, LAS const unsigned char* vb_, bf16x8 q0, bf16x8 q1, float sk, unsigned mskbits, int fr, f32x4 (&o)[4]) {
;     ...
;     for (int kt = 0; kt < NKT; ++kt) {
;         const int key = (kt >> 1) * 32 + ((kt & 1) << 2) + krow;
;         LAS const unsigned char* kp = kb_ + key * 144;
;         const bf16x8 a0 = *(LAS const bf16x8*)kp, a1 = *(LAS const bf16x8*)(kp + 64);
;         const float bias = ((mskbits >> (kt >> 2)) & 1u) ? -1e30f : 0.f;
;         f32x4 s = mfma16(a0, q0, (f32x4){bias, bias, bias, bias});
;         s = mfma16(a1, q1, s);
;         S[kt] = s;
;     }
;     float mx = S[0][0];
; #pragma unroll
;     for (int kt = 0; kt < NKT; ++kt) mx = fmaxf(fmaxf(mx, fmaxf(S[kt][0], S[kt][1])), fmaxf(S[kt][2], S[kt][3]));
;     mx = fmaxf(mx, __shfl_xor(mx, 16)); mx = fmaxf(mx, __shfl_xor(mx, 32));
	v_mul_f32_e32 v90, 0x3fb8aa3b, v81
	s_waitcnt lgkmcnt(9)
	v_mfma_f32_16x16x32_bf16 v[64:67], v[196:199], v[16:19], v[24:27]
	ds_read_b128 v[92:95], v79 offset:9856
	ds_read_b128 v[196:199], v79 offset:13824
	s_waitcnt lgkmcnt(10)
	v_mfma_f32_16x16x32_bf16 v[24:27], v[200:203], v[20:23], 0
	s_waitcnt lgkmcnt(9)
	v_mfma_f32_16x16x32_bf16 v[60:63], v[204:207], v[16:19], v[24:27]
	ds_read_b128 v[200:203], v79 offset:13888
	ds_read_b128 v[204:207], v79 offset:14400
	s_waitcnt lgkmcnt(10)
	v_mfma_f32_16x16x32_bf16 v[24:27], v[208:211], v[20:23], 0
	s_waitcnt lgkmcnt(9)
	v_mfma_f32_16x16x32_bf16 v[56:59], v[212:215], v[16:19], v[24:27]
	ds_read_b128 v[208:211], v79 offset:14464
	ds_read_b128 v[212:215], v79 offset:18432
	s_waitcnt lgkmcnt(10)
	v_mfma_f32_16x16x32_bf16 v[24:27], v[228:231], v[20:23], 0
	s_waitcnt lgkmcnt(9)
	v_mfma_f32_16x16x32_bf16 v[52:55], v[232:235], v[16:19], v[24:27]
	ds_read_b128 v[228:231], v79 offset:18496
	ds_read_b128 v[232:235], v79 offset:19008
	s_waitcnt lgkmcnt(10)
	v_mfma_f32_16x16x32_bf16 v[24:27], v[236:239], v[20:23], 0
	s_waitcnt lgkmcnt(9)
	v_mfma_f32_16x16x32_bf16 v[48:51], v[240:243], v[16:19], v[24:27]
	ds_read_b128 v[236:239], v79 offset:19072
	ds_read_b128 v[240:243], v79 offset:23040
	s_waitcnt lgkmcnt(10)
	v_mfma_f32_16x16x32_bf16 v[24:27], v[244:247], v[20:23], 0
	s_waitcnt lgkmcnt(9)
	v_mfma_f32_16x16x32_bf16 v[44:47], v[92:95], v[16:19], v[24:27]
	ds_read_b128 v[244:247], v79 offset:23104
	ds_read_b128 v[92:95], v79 offset:23616
	s_waitcnt lgkmcnt(10)
	v_mfma_f32_16x16x32_bf16 v[24:27], v[196:199], v[20:23], 0
	s_waitcnt lgkmcnt(9)
	v_mfma_f32_16x16x32_bf16 v[40:43], v[200:203], v[16:19], v[24:27]
	ds_read_b128 v[196:199], v79 offset:23680
	s_waitcnt lgkmcnt(9)
	v_mfma_f32_16x16x32_bf16 v[24:27], v[204:207], v[20:23], 0
	s_waitcnt lgkmcnt(8)
	v_mfma_f32_16x16x32_bf16 v[36:39], v[208:211], v[16:19], v[24:27]
	s_waitcnt lgkmcnt(7)
	v_mfma_f32_16x16x32_bf16 v[24:27], v[212:215], v[20:23], 0
	s_waitcnt lgkmcnt(6)
	v_mfma_f32_16x16x32_bf16 v[32:35], v[228:231], v[16:19], v[24:27]
	s_waitcnt lgkmcnt(5)
	v_mfma_f32_16x16x32_bf16 v[24:27], v[232:235], v[20:23], 0
	s_waitcnt lgkmcnt(4)
	v_mfma_f32_16x16x32_bf16 v[28:31], v[236:239], v[16:19], v[24:27]
	s_waitcnt lgkmcnt(3)
	v_mfma_f32_16x16x32_bf16 v[24:27], v[240:243], v[20:23], 0
	s_waitcnt lgkmcnt(2)
	v_mfma_f32_16x16x32_bf16 v[24:27], v[244:247], v[16:19], v[24:27]
	s_waitcnt lgkmcnt(1)
	v_mfma_f32_16x16x32_bf16 v[20:23], v[92:95], v[20:23], 0
	s_waitcnt lgkmcnt(0)
	v_mfma_f32_16x16x32_bf16 v[16:19], v[196:199], v[16:19], v[20:23]
	s_nop 5
	v_max_f32_e32 v20, v67, v67
	v_max_f32_e32 v21, v66, v66
	v_max_f32_e32 v20, v21, v20
	v_max_f32_e32 v21, v61, v61
	v_max_f32_e32 v22, v60, v60
	v_max_f32_e32 v21, v22, v21
	v_max_f32_e32 v22, v63, v63
	v_max_f32_e32 v23, v62, v62
	v_max3_f32 v20, v64, v65, v20
	v_max_f32_e32 v22, v23, v22
	v_max3_f32 v20, v20, v21, v22
	v_max_f32_e32 v21, v57, v57
	v_max_f32_e32 v22, v56, v56
	v_max_f32_e32 v21, v22, v21
	v_max_f32_e32 v22, v59, v59
	v_max_f32_e32 v23, v58, v58
	v_max_f32_e32 v22, v23, v22
	v_max3_f32 v20, v20, v21, v22
	v_max_f32_e32 v21, v53, v53
	v_max_f32_e32 v22, v52, v52
	v_max_f32_e32 v21, v22, v21
	v_max_f32_e32 v22, v55, v55
	v_max_f32_e32 v23, v54, v54
	v_max_f32_e32 v22, v23, v22
	v_max3_f32 v20, v20, v21, v22
	v_max_f32_e32 v21, v49, v49
	v_max_f32_e32 v22, v48, v48
	v_max_f32_e32 v21, v22, v21
	v_max_f32_e32 v22, v51, v51
	v_max_f32_e32 v23, v50, v50
	v_max_f32_e32 v22, v23, v22
	v_max3_f32 v20, v20, v21, v22
	v_max_f32_e32 v21, v45, v45
	v_max_f32_e32 v22, v44, v44
	v_max_f32_e32 v21, v22, v21
	v_max_f32_e32 v22, v47, v47
	v_max_f32_e32 v23, v46, v46
	v_max_f32_e32 v22, v23, v22
	v_max3_f32 v20, v20, v21, v22
	v_max_f32_e32 v21, v41, v41
	v_max_f32_e32 v22, v40, v40
	v_max_f32_e32 v21, v22, v21
	v_max_f32_e32 v22, v43, v43
	v_max_f32_e32 v23, v42, v42
	v_max_f32_e32 v22, v23, v22
	v_max3_f32 v20, v20, v21, v22
	v_max_f32_e32 v21, v37, v37
	v_max_f32_e32 v22, v36, v36
	v_max_f32_e32 v21, v22, v21
	v_max_f32_e32 v22, v39, v39
	v_max_f32_e32 v23, v38, v38
	v_max_f32_e32 v22, v23, v22
	v_max3_f32 v20, v20, v21, v22
	v_max_f32_e32 v21, v33, v33
	v_max_f32_e32 v22, v32, v32
	v_max_f32_e32 v21, v22, v21
	v_max_f32_e32 v22, v35, v35
	v_max_f32_e32 v23, v34, v34
	v_max_f32_e32 v22, v23, v22
	v_max3_f32 v20, v20, v21, v22
	v_max_f32_e32 v21, v29, v29
	v_max_f32_e32 v22, v28, v28
	v_max_f32_e32 v21, v22, v21
	v_max_f32_e32 v22, v31, v31
	v_max_f32_e32 v23, v30, v30
	v_max_f32_e32 v22, v23, v22
	v_max3_f32 v20, v20, v21, v22
	v_max_f32_e32 v21, v25, v25
	v_max_f32_e32 v22, v24, v24
	v_max_f32_e32 v21, v22, v21
	v_max_f32_e32 v22, v27, v27
	v_max_f32_e32 v23, v26, v26
	v_max_f32_e32 v22, v23, v22
	v_max3_f32 v20, v20, v21, v22
	v_max_f32_e32 v21, v17, v17
	v_max_f32_e32 v22, v16, v16
	v_max_f32_e32 v21, v22, v21
	v_max_f32_e32 v22, v19, v19
	v_max_f32_e32 v23, v18, v18
	v_max_f32_e32 v22, v23, v22
	v_max3_f32 v20, v20, v21, v22
	ds_bpermute_b32 v21, v135, v20
	s_waitcnt lgkmcnt(0)
	v_max_f32_e32 v21, v21, v21
	v_max_f32_e32 v20, v20, v21
	ds_bpermute_b32 v21, v76, v20
	s_waitcnt lgkmcnt(0)
; __device__ __forceinline__ unsigned pk2(float lo, float hi) { return pg8::cvt_pk_bf16(lo, hi); }
; template <int NKT, int VSTR, bool SINK>
; __device__ __forceinline__ void attn_core(LAS const unsigned char* kb_, LAS const unsigned char* vb_, bf16x8 q0, bf16x8 q1, float sk, unsigned mskbits, int fr, f32x4 (&o)[4]) {
;     ...
;     for (int kt = 0; kt < NKT; ++kt) mx = fmaxf(fmaxf(mx, fmaxf(S[kt][0], S[kt][1])), fmaxf(S[kt][2], S[kt][3]));
;     mx = fmaxf(mx, __shfl_xor(mx, 16)); mx = fmaxf(mx, __shfl_xor(mx, 32));
;     if (SINK) mx = fmaxf(mx, sk);
;     float sum = 0.f;
; #pragma unroll
;     for (int kt = 0; kt < NKT; ++kt)
; #pragma unroll
;         for (int r = 0; r < 4; ++r) { const float p = __builtin_amdgcn_exp2f(S[kt][r] - mx); S[kt][r] = p; sum += p; }
;     sum += __shfl_xor(sum, 16); sum += __shfl_xor(sum, 32);
;     if (SINK) sum += __builtin_amdgcn_exp2f(sk - mx);
;     const float inv = 1.0f / sum;
;     bf16x8 pf[NKT / 2];
; #pragma unroll
;     for (int kb = 0; kb < NKT / 2; ++kb) {
;         v4u w; w.x = pk2(S[2 * kb][0], S[2 * kb][1]); w.y = pk2(S[2 * kb][2], S[2 * kb][3]); w.z = pk2(S[2 * kb + 1][0], S[2 * kb + 1][1]); w.w = pk2(S[2 * kb + 1][2], S[2 * kb + 1][3]);
;         pf[kb] = __builtin_bit_cast(bf16x8, w);
;     }
	v_max3_f32 v20, v20, v21, v90
	v_sub_f32_e32 v21, v64, v20
	v_exp_f32_e32 v21, v21
	v_sub_f32_e32 v23, v65, v20
	v_exp_f32_e32 v23, v23
	v_sub_f32_e32 v64, v66, v20
	v_exp_f32_e32 v64, v64
	v_sub_f32_e32 v65, v67, v20
	v_exp_f32_e32 v65, v65
	v_sub_f32_e32 v60, v60, v20
	v_add_f32_e32 v22, 0, v21
	v_exp_f32_e32 v60, v60
	v_sub_f32_e32 v61, v61, v20
	v_add_f32_e32 v22, v23, v22
	v_exp_f32_e32 v61, v61
	v_sub_f32_e32 v62, v62, v20
	v_add_f32_e32 v22, v64, v22
	v_exp_f32_e32 v62, v62
	v_sub_f32_e32 v63, v63, v20
	v_add_f32_e32 v22, v65, v22
	v_exp_f32_e32 v63, v63
	v_sub_f32_e32 v56, v56, v20
	v_add_f32_e32 v22, v60, v22
	v_exp_f32_e32 v56, v56
	v_sub_f32_e32 v57, v57, v20
	v_add_f32_e32 v22, v61, v22
	v_exp_f32_e32 v57, v57
	v_sub_f32_e32 v58, v58, v20
	v_add_f32_e32 v22, v62, v22
	v_exp_f32_e32 v58, v58
	v_sub_f32_e32 v59, v59, v20
	v_add_f32_e32 v22, v63, v22
	v_exp_f32_e32 v59, v59
	v_sub_f32_e32 v52, v52, v20
	v_add_f32_e32 v22, v56, v22
	v_exp_f32_e32 v52, v52
	v_sub_f32_e32 v53, v53, v20
	v_add_f32_e32 v22, v57, v22
	v_exp_f32_e32 v53, v53
	v_sub_f32_e32 v54, v54, v20
	v_add_f32_e32 v22, v58, v22
	v_exp_f32_e32 v54, v54
	v_sub_f32_e32 v55, v55, v20
	v_add_f32_e32 v22, v59, v22
	v_exp_f32_e32 v55, v55
	v_sub_f32_e32 v48, v48, v20
	v_add_f32_e32 v22, v52, v22
	v_exp_f32_e32 v48, v48
	v_sub_f32_e32 v49, v49, v20
	v_add_f32_e32 v22, v53, v22
	v_exp_f32_e32 v49, v49
	v_sub_f32_e32 v50, v50, v20
	v_add_f32_e32 v22, v54, v22
	v_exp_f32_e32 v50, v50
	v_sub_f32_e32 v51, v51, v20
	v_add_f32_e32 v22, v55, v22
	v_exp_f32_e32 v51, v51
	v_sub_f32_e32 v44, v44, v20
	v_add_f32_e32 v22, v48, v22
	v_exp_f32_e32 v44, v44
	v_sub_f32_e32 v45, v45, v20
	v_add_f32_e32 v22, v49, v22
	v_exp_f32_e32 v45, v45
	v_sub_f32_e32 v46, v46, v20
	v_add_f32_e32 v22, v50, v22
	v_exp_f32_e32 v46, v46
	v_sub_f32_e32 v47, v47, v20
	v_add_f32_e32 v22, v51, v22
	v_exp_f32_e32 v47, v47
	v_sub_f32_e32 v40, v40, v20
	v_add_f32_e32 v22, v44, v22
	v_exp_f32_e32 v40, v40
	v_sub_f32_e32 v41, v41, v20
	v_add_f32_e32 v22, v45, v22
	v_exp_f32_e32 v41, v41
	v_sub_f32_e32 v42, v42, v20
	v_add_f32_e32 v22, v46, v22
	v_exp_f32_e32 v42, v42
	v_sub_f32_e32 v43, v43, v20
	v_add_f32_e32 v22, v47, v22
	v_exp_f32_e32 v43, v43
	v_sub_f32_e32 v36, v36, v20
	v_add_f32_e32 v22, v40, v22
	v_exp_f32_e32 v66, v36
	v_sub_f32_e32 v36, v37, v20
	v_add_f32_e32 v22, v41, v22
	v_exp_f32_e32 v67, v36
	v_sub_f32_e32 v36, v38, v20
	v_add_f32_e32 v22, v42, v22
	v_exp_f32_e32 v82, v36
	v_sub_f32_e32 v36, v39, v20
	v_add_f32_e32 v22, v43, v22
	v_exp_f32_e32 v83, v36
	v_sub_f32_e32 v32, v32, v20
	v_add_f32_e32 v22, v66, v22
	v_exp_f32_e32 v84, v32
	v_sub_f32_e32 v32, v33, v20
	v_add_f32_e32 v22, v67, v22
	v_exp_f32_e32 v85, v32
	v_sub_f32_e32 v32, v34, v20
	v_add_f32_e32 v22, v82, v22
	v_exp_f32_e32 v86, v32
	v_sub_f32_e32 v32, v35, v20
	v_add_f32_e32 v22, v83, v22
	v_exp_f32_e32 v87, v32
	v_sub_f32_e32 v28, v28, v20
	v_add_f32_e32 v22, v84, v22
	v_exp_f32_e32 v88, v28
	v_sub_f32_e32 v28, v29, v20
	v_add_f32_e32 v22, v85, v22
	v_exp_f32_e32 v89, v28
	v_sub_f32_e32 v28, v30, v20
	v_add_f32_e32 v22, v86, v22
	v_exp_f32_e32 v90, v28
	v_sub_f32_e32 v28, v31, v20
	v_add_f32_e32 v22, v87, v22
	v_exp_f32_e32 v91, v28
	v_sub_f32_e32 v24, v24, v20
	v_add_f32_e32 v22, v88, v22
	v_exp_f32_e32 v92, v24
	v_sub_f32_e32 v24, v25, v20
	v_add_f32_e32 v22, v89, v22
	v_exp_f32_e32 v93, v24
	v_sub_f32_e32 v24, v26, v20
	v_add_f32_e32 v22, v90, v22
	v_exp_f32_e32 v94, v24
	v_sub_f32_e32 v24, v27, v20
	v_add_f32_e32 v22, v91, v22
	v_exp_f32_e32 v95, v24
	v_sub_f32_e32 v16, v16, v20
	v_add_f32_e32 v22, v92, v22
	v_exp_f32_e32 v96, v16
	v_sub_f32_e32 v17, v17, v20
	v_add_f32_e32 v22, v93, v22
	v_exp_f32_e32 v97, v17
	v_sub_f32_e32 v17, v18, v20
	v_add_f32_e32 v22, v94, v22
	v_exp_f32_e32 v98, v17
	v_sub_f32_e32 v17, v19, v20
	v_add_f32_e32 v22, v95, v22
	v_exp_f32_e32 v19, v17
	v_add_f32_e32 v16, v96, v22
	v_add_f32_e32 v16, v97, v16
	v_add_f32_e32 v16, v98, v16
	v_add_f32_e32 v16, v19, v16
	ds_bpermute_b32 v17, v135, v16
	v_cvt_pk_bf16_f32 v36, v21, v23
	v_cvt_pk_bf16_f32 v37, v64, v65
	v_cvt_pk_bf16_f32 v38, v60, v61
	v_cvt_pk_bf16_f32 v39, v62, v63
	s_waitcnt lgkmcnt(0)
	v_add_f32_e32 v16, v16, v17
	ds_bpermute_b32 v17, v76, v16
	v_cvt_pk_bf16_f32 v32, v56, v57
	v_cvt_pk_bf16_f32 v33, v58, v59
	v_cvt_pk_bf16_f32 v34, v52, v53
	v_cvt_pk_bf16_f32 v35, v54, v55
	s_waitcnt lgkmcnt(0)
	v_add_f32_e32 v16, v16, v17
	v_fma_f32 v17, v81, s2, -v20
	v_exp_f32_e32 v17, v17
	v_cvt_pk_bf16_f32 v28, v48, v49
	v_cvt_pk_bf16_f32 v29, v50, v51
	v_cvt_pk_bf16_f32 v30, v44, v45
	v_cvt_pk_bf16_f32 v31, v46, v47
	v_cvt_pk_bf16_f32 v24, v40, v41
	s_nop 0
	v_add_f32_e32 v81, v17, v16
	v_div_scale_f32 v40, s[0:1], v81, v81, 1.0
	v_rcp_f32_e32 v41, v40
	v_cvt_pk_bf16_f32 v25, v42, v43
	v_cvt_pk_bf16_f32 v26, v66, v67
	v_cvt_pk_bf16_f32 v27, v82, v83
	v_cvt_pk_bf16_f32 v20, v84, v85
	v_cvt_pk_bf16_f32 v21, v86, v87
	s_nop 0
	v_fma_f32 v42, -v40, v41, 1.0
	v_fmac_f32_e32 v41, v42, v41
	v_div_scale_f32 v42, vcc, 1.0, v81, 1.0
	v_mul_f32_e32 v43, v42, v41
	v_fma_f32 v44, -v40, v43, v42
	v_fmac_f32_e32 v43, v44, v41
	v_fma_f32 v40, -v40, v43, v42
	v_cvt_pk_bf16_f32 v22, v88, v89
	v_cvt_pk_bf16_f32 v23, v90, v91
	v_cvt_pk_bf16_f32 v16, v92, v93
	v_cvt_pk_bf16_f32 v17, v94, v95
	v_cvt_pk_bf16_f32 v18, v96, v97
	v_cvt_pk_bf16_f32 v19, v98, v19
	v_div_fmas_f32 v40, v40, v41, v43
	s_waitcnt lgkmcnt(0)
; #define LAS __attribute__((address_space(3)))
; __device__ __forceinline__ float sq4(const f32x4 a) { return (a[0] * a[0] + a[1] * a[1]) + (a[2] * a[2] + a[3] * a[3]); }
; #define LAS __attribute__((address_space(3)))
; __device__ __forceinline__ unsigned pk2(float lo, float hi) { return pg8::cvt_pk_bf16(lo, hi); }
; __device__ __forceinline__ f32x4 mfma16(bf16x8 a, bf16x8 b, f32x4 c) { return __builtin_amdgcn_mfma_f32_16x16x32_bf16(a, b, c, 0, 0, 0); }
; template <int NKT, int VSTR, bool SINK>
; __device__ __forceinline__ void attn_core(LAS const unsigned char* kb_, LAS const unsigned char* vb_, bf16x8 q0, bf16x8 q1, float sk, unsigned mskbits, int fr, f32x4 (&o)[4]) {
;     ...
; #pragma unroll
;     for (int dt = 0; dt < 4; ++dt) {
;         f32x4 acc = (f32x4){0.f, 0.f, 0.f, 0.f};
; #pragma unroll
;         for (int kb = 0; kb < NKT / 2; ++kb) {
;             const bf16x8 vf = *(LAS const bf16x8*)(vb_ + dt * 16 * VSTR + kb * 64);
;             acc = mfma16(vf, pf[kb], acc);
;         }
;         o[dt] = acc * inv;
;     }
; template <bool DO_SWA, bool DO_MEM>
; __device__ __forceinline__ void attn_unit(const Args& a, unsigned char* ws, LAS unsigned char* lds, int l, int tid_in, int lane_in, int wave, int unit) {
;     ...
;                 const float sk = a.in[12][l * 8 + h] * LOG2E;
;                 f32x4 o[4];
;                 attn_core<12, 400, true>(lds + A_KS + g * 192 * 144 + fq * 16, lds + A_VT1 + (g * 64 + fr) * 400 + fq * 16, qsw[hh][0], qsw[hh][1], sk, mskbits, fr, o);
; #pragma unroll
;                 for (int dt = 0; dt < 4; ++dt) { ssq += pg8::sq4(o[dt]); osv[hh][dt] = (v2u){pk2(o[dt][0], o[dt][1]), pk2(o[dt][2], o[dt][3])}; }
	ds_read_b128 v[196:199], v78 offset:55296
	ds_read_b128 v[200:203], v78 offset:55360
	ds_read_b128 v[204:207], v78 offset:61760
	ds_read_b128 v[208:211], v77 offset:12864
	ds_read_b128 v[212:215], v78 offset:55424
	ds_read_b128 v[228:231], v78 offset:55488
	ds_read_b128 v[232:235], v78 offset:55552
	ds_read_b128 v[236:239], v78 offset:55616
	ds_read_b128 v[240:243], v78 offset:61696
	ds_read_b128 v[244:247], v78 offset:61824
	s_waitcnt lgkmcnt(9)
	v_mfma_f32_16x16x32_bf16 v[42:45], v[196:199], v[36:39], 0
	ds_read_b128 v[196:199], v78 offset:61888
	v_div_fixup_f32 v40, v40, v81, 1.0
	s_waitcnt lgkmcnt(9)
	v_mfma_f32_16x16x32_bf16 v[42:45], v[200:203], v[32:35], v[42:45]
	ds_read_b128 v[200:203], v78 offset:61952
	s_waitcnt lgkmcnt(7)
	v_mfma_f32_16x16x32_bf16 v[42:45], v[212:215], v[28:31], v[42:45]
	ds_read_b128 v[212:215], v78 offset:62016
	s_waitcnt lgkmcnt(7)
	v_mfma_f32_16x16x32_bf16 v[42:45], v[228:231], v[24:27], v[42:45]
	ds_read_b128 v[228:231], v77 offset:12800
	s_waitcnt lgkmcnt(7)
	v_mfma_f32_16x16x32_bf16 v[42:45], v[232:235], v[20:23], v[42:45]
	ds_read_b128 v[232:235], v77 offset:12928
	s_waitcnt lgkmcnt(7)
	v_mfma_f32_16x16x32_bf16 v[44:47], v[236:239], v[16:19], v[42:45]
	ds_read_b128 v[236:239], v77 offset:12992
	s_nop 7
	v_pk_mul_f32 v[42:43], v[46:47], v[40:41] op_sel_hi:[1,0]
	s_waitcnt lgkmcnt(7)
	v_mfma_f32_16x16x32_bf16 v[46:49], v[240:243], v[36:39], 0
	ds_read_b128 v[240:243], v77 offset:13056
	v_mul_f32_e64 v44, v44, v40
	v_mul_f32_e64 v45, v45, v40
	v_mfma_f32_16x16x32_bf16 v[46:49], v[204:207], v[32:35], v[46:49]
	ds_read_b128 v[204:207], v77 offset:13120
	s_waitcnt lgkmcnt(8)
	v_mfma_f32_16x16x32_bf16 v[46:49], v[244:247], v[28:31], v[46:49]
	ds_read_b128 v[244:247], v77 offset:19200
	s_waitcnt lgkmcnt(8)
	v_mfma_f32_16x16x32_bf16 v[46:49], v[196:199], v[24:27], v[46:49]
	ds_read_b128 v[196:199], v77 offset:19264
	s_waitcnt lgkmcnt(8)
	v_mfma_f32_16x16x32_bf16 v[46:49], v[200:203], v[20:23], v[46:49]
	ds_read_b128 v[200:203], v77 offset:19328
	s_waitcnt lgkmcnt(8)
	v_mfma_f32_16x16x32_bf16 v[48:51], v[212:215], v[16:19], v[46:49]
	s_nop 7
	v_pk_mul_f32 v[46:47], v[50:51], v[40:41] op_sel_hi:[1,0]
	ds_read_b128 v[212:215], v77 offset:19392
	s_waitcnt lgkmcnt(8)
	v_mfma_f32_16x16x32_bf16 v[50:53], v[228:231], v[36:39], 0
	v_mul_f32_e64 v48, v48, v40
	v_mul_f32_e64 v49, v49, v40
	v_mfma_f32_16x16x32_bf16 v[50:53], v[208:211], v[32:35], v[50:53]
	ds_read_b128 v[228:231], v77 offset:19456
	s_waitcnt lgkmcnt(8)
	v_mfma_f32_16x16x32_bf16 v[50:53], v[232:235], v[28:31], v[50:53]
	ds_read_b128 v[208:211], v77 offset:19520
	s_waitcnt lgkmcnt(8)
	v_mfma_f32_16x16x32_bf16 v[50:53], v[236:239], v[24:27], v[50:53]
	s_waitcnt lgkmcnt(7)
	v_mfma_f32_16x16x32_bf16 v[50:53], v[240:243], v[20:23], v[50:53]
	s_waitcnt lgkmcnt(6)
	v_mfma_f32_16x16x32_bf16 v[52:55], v[204:207], v[16:19], v[50:53]
	s_nop 7
	v_pk_mul_f32 v[50:51], v[40:41], v[54:55] op_sel_hi:[0,1]
	s_waitcnt lgkmcnt(5)
	v_mfma_f32_16x16x32_bf16 v[36:39], v[244:247], v[36:39], 0
	v_pk_mul_f32 v[52:53], v[40:41], v[52:53] op_sel_hi:[0,1]
	s_waitcnt lgkmcnt(4)
	v_mfma_f32_16x16x32_bf16 v[32:35], v[196:199], v[32:35], v[36:39]
	s_waitcnt lgkmcnt(3)
	v_mfma_f32_16x16x32_bf16 v[28:31], v[200:203], v[28:31], v[32:35]
	s_waitcnt lgkmcnt(2)
	v_mfma_f32_16x16x32_bf16 v[24:27], v[212:215], v[24:27], v[28:31]
	s_waitcnt lgkmcnt(1)
	v_mfma_f32_16x16x32_bf16 v[20:23], v[228:231], v[20:23], v[24:27]
	v_cvt_pk_bf16_f32 v61, v44, v45
	v_cvt_pk_bf16_f32 v60, v42, v43
	s_waitcnt lgkmcnt(0)
	v_mfma_f32_16x16x32_bf16 v[16:19], v[208:211], v[16:19], v[20:23]
	s_nop 2
	v_mul_f32_e32 v20, v45, v45
	v_mul_f32_e32 v21, v43, v43
	v_fmac_f32_e32 v20, v44, v44
	v_fmac_f32_e32 v21, v42, v42
	v_add_f32_e32 v20, v20, v21
	v_mul_f32_e32 v21, v49, v49
	v_mul_f32_e32 v22, v47, v47
	v_fmac_f32_e32 v21, v48, v48
	v_fmac_f32_e32 v22, v46, v46
	v_add_f32_e32 v20, v80, v20
	v_add_f32_e32 v21, v21, v22
	v_add_f32_e32 v20, v21, v20
	v_mul_f32_e32 v21, v53, v53
	v_mul_f32_e32 v22, v51, v51
	v_fmac_f32_e32 v21, v52, v52
	v_fmac_f32_e32 v22, v50, v50
	v_pk_mul_f32 v[18:19], v[40:41], v[18:19] op_sel_hi:[0,1]
	v_pk_mul_f32 v[16:17], v[40:41], v[16:17] op_sel_hi:[0,1]
	v_add_f32_e32 v21, v21, v22
	v_add_f32_e32 v20, v21, v20
	v_mul_f32_e32 v21, v17, v17
	v_mul_f32_e32 v22, v19, v19
	v_fmac_f32_e32 v21, v16, v16
	v_fmac_f32_e32 v22, v18, v18
	v_add_f32_e32 v21, v21, v22
	v_cvt_pk_bf16_f32 v63, v48, v49
	v_cvt_pk_bf16_f32 v62, v46, v47
	v_cvt_pk_bf16_f32 v65, v52, v53
	v_cvt_pk_bf16_f32 v64, v50, v51
	v_add_f32_e32 v80, v20, v21
	v_cvt_pk_bf16_f32 v67, v16, v17
	v_cvt_pk_bf16_f32 v66, v18, v19
	v_mov_b32_e32 v81, s100
	s_waitcnt lgkmcnt(0)
	ds_read_b128 v[92:95], v79
	ds_read_b128 v[196:199], v79 offset:64
	ds_read_b128 v[200:203], v79 offset:576
	ds_read_b128 v[204:207], v79 offset:640
	ds_read_b128 v[208:211], v79 offset:4608
	ds_read_b128 v[212:215], v79 offset:4672
	ds_read_b128 v[228:231], v79 offset:5184
	ds_read_b128 v[232:235], v79 offset:5248
	ds_read_b128 v[236:239], v79 offset:9216
	ds_read_b128 v[240:243], v79 offset:9280
	ds_read_b128 v[244:247], v79 offset:9792
	s_waitcnt lgkmcnt(10)
	v_mfma_f32_16x16x32_bf16 v[16:19], v[92:95], v[12:15], 0

; #define LAS __attribute__((address_space(3)))
; #define LAS __attribute__((address_space(3)))
; __device__ __forceinline__ f32x4 mfma16(bf16x8 a, bf16x8 b, f32x4 c) { return __builtin_amdgcn_mfma_f32_16x16x32_bf16(a, b, c, 0, 0, 0); }
; template <int NKT, int VSTR, bool SINK>
; __device__ __forceinline__ void attn_core(LAS const unsigned char* kb_, LAS const unsigned char* vb_, bf16x8 q0, bf16x8 q1, float sk, unsigned mskbits, int fr, f32x4 (&o)[4]) {
;     ...
;     for (int kt = 0; kt < NKT; ++kt) {
;         const int key = (kt >> 1) * 32 + ((kt & 1) << 2) + krow;
;         LAS const unsigned char* kp = kb_ + key * 144;
;         const bf16x8 a0 = *(LAS const bf16x8*)kp, a1 = *(LAS const bf16x8*)(kp + 64);
;         const float bias = ((mskbits >> (kt >> 2)) & 1u) ? -1e30f : 0.f;
;         f32x4 s = mfma16(a0, q0, (f32x4){bias, bias, bias, bias});
;         s = mfma16(a1, q1, s);
;         S[kt] = s;
;     }
;     float mx = S[0][0];
; #pragma unroll
;     for (int kt = 0; kt < NKT; ++kt) mx = fmaxf(fmaxf(mx, fmaxf(S[kt][0], S[kt][1])), fmaxf(S[kt][2], S[kt][3]));
;     mx = fmaxf(mx, __shfl_xor(mx, 16)); mx = fmaxf(mx, __shfl_xor(mx, 32));
	v_mul_f32_e32 v90, 0x3fb8aa3b, v81
	s_waitcnt lgkmcnt(9)
	v_mfma_f32_16x16x32_bf16 v[56:59], v[196:199], v[8:11], v[16:19]
	ds_read_b128 v[92:95], v79 offset:9856
	ds_read_b128 v[196:199], v79 offset:13824
	s_waitcnt lgkmcnt(10)
	v_mfma_f32_16x16x32_bf16 v[16:19], v[200:203], v[12:15], 0
	s_waitcnt lgkmcnt(9)
	v_mfma_f32_16x16x32_bf16 v[52:55], v[204:207], v[8:11], v[16:19]
	ds_read_b128 v[200:203], v79 offset:13888
	ds_read_b128 v[204:207], v79 offset:14400
	s_waitcnt lgkmcnt(10)
	v_mfma_f32_16x16x32_bf16 v[16:19], v[208:211], v[12:15], 0
	s_waitcnt lgkmcnt(9)
	v_mfma_f32_16x16x32_bf16 v[48:51], v[212:215], v[8:11], v[16:19]
	ds_read_b128 v[208:211], v79 offset:14464
	ds_read_b128 v[212:215], v79 offset:18432
	s_waitcnt lgkmcnt(10)
	v_mfma_f32_16x16x32_bf16 v[16:19], v[228:231], v[12:15], 0
	s_waitcnt lgkmcnt(9)
	v_mfma_f32_16x16x32_bf16 v[44:47], v[232:235], v[8:11], v[16:19]
	ds_read_b128 v[228:231], v79 offset:18496
	ds_read_b128 v[232:235], v79 offset:19008
	s_waitcnt lgkmcnt(10)
	v_mfma_f32_16x16x32_bf16 v[16:19], v[236:239], v[12:15], 0
	s_waitcnt lgkmcnt(9)
	v_mfma_f32_16x16x32_bf16 v[40:43], v[240:243], v[8:11], v[16:19]
	ds_read_b128 v[236:239], v79 offset:19072
	ds_read_b128 v[240:243], v79 offset:23040
	s_waitcnt lgkmcnt(10)
	v_mfma_f32_16x16x32_bf16 v[16:19], v[244:247], v[12:15], 0
	s_waitcnt lgkmcnt(9)
	v_mfma_f32_16x16x32_bf16 v[36:39], v[92:95], v[8:11], v[16:19]
	ds_read_b128 v[244:247], v79 offset:23104
	ds_read_b128 v[92:95], v79 offset:23616
	s_waitcnt lgkmcnt(10)
	v_mfma_f32_16x16x32_bf16 v[16:19], v[196:199], v[12:15], 0
	s_waitcnt lgkmcnt(9)
	v_mfma_f32_16x16x32_bf16 v[32:35], v[200:203], v[8:11], v[16:19]
	ds_read_b128 v[196:199], v79 offset:23680
	s_waitcnt lgkmcnt(9)
	v_mfma_f32_16x16x32_bf16 v[16:19], v[204:207], v[12:15], 0
	s_waitcnt lgkmcnt(8)
	v_mfma_f32_16x16x32_bf16 v[28:31], v[208:211], v[8:11], v[16:19]
	s_waitcnt lgkmcnt(7)
	v_mfma_f32_16x16x32_bf16 v[16:19], v[212:215], v[12:15], 0
	s_waitcnt lgkmcnt(6)
	v_mfma_f32_16x16x32_bf16 v[24:27], v[228:231], v[8:11], v[16:19]
	s_waitcnt lgkmcnt(5)
	v_mfma_f32_16x16x32_bf16 v[16:19], v[232:235], v[12:15], 0
	s_waitcnt lgkmcnt(4)
	v_mfma_f32_16x16x32_bf16 v[20:23], v[236:239], v[8:11], v[16:19]
	s_waitcnt lgkmcnt(3)
	v_mfma_f32_16x16x32_bf16 v[16:19], v[240:243], v[12:15], 0
	s_waitcnt lgkmcnt(2)
	v_mfma_f32_16x16x32_bf16 v[16:19], v[244:247], v[8:11], v[16:19]
	s_waitcnt lgkmcnt(1)
	v_mfma_f32_16x16x32_bf16 v[12:15], v[92:95], v[12:15], 0
	s_waitcnt lgkmcnt(0)
	v_mfma_f32_16x16x32_bf16 v[8:11], v[196:199], v[8:11], v[12:15]
	s_nop 5
	v_max_f32_e32 v12, v59, v59
	v_max_f32_e32 v13, v58, v58
	v_max_f32_e32 v12, v13, v12
	v_max_f32_e32 v13, v53, v53
	v_max_f32_e32 v14, v52, v52
	v_max_f32_e32 v13, v14, v13
	v_max_f32_e32 v14, v55, v55
	v_max_f32_e32 v15, v54, v54
	v_max3_f32 v12, v56, v57, v12
	v_max_f32_e32 v14, v15, v14
	v_max3_f32 v12, v12, v13, v14
	v_max_f32_e32 v13, v49, v49
	v_max_f32_e32 v14, v48, v48
	v_max_f32_e32 v13, v14, v13
	v_max_f32_e32 v14, v51, v51
	v_max_f32_e32 v15, v50, v50
	v_max_f32_e32 v14, v15, v14
	v_max3_f32 v12, v12, v13, v14
	v_max_f32_e32 v13, v45, v45
	v_max_f32_e32 v14, v44, v44
	v_max_f32_e32 v13, v14, v13
	v_max_f32_e32 v14, v47, v47
	v_max_f32_e32 v15, v46, v46
	v_max_f32_e32 v14, v15, v14
	v_max3_f32 v12, v12, v13, v14
	v_max_f32_e32 v13, v41, v41
	v_max_f32_e32 v14, v40, v40
	v_max_f32_e32 v13, v14, v13
	v_max_f32_e32 v14, v43, v43
	v_max_f32_e32 v15, v42, v42
	v_max_f32_e32 v14, v15, v14
	v_max3_f32 v12, v12, v13, v14
	v_max_f32_e32 v13, v37, v37
	v_max_f32_e32 v14, v36, v36
	v_max_f32_e32 v13, v14, v13
	v_max_f32_e32 v14, v39, v39
	v_max_f32_e32 v15, v38, v38
	v_max_f32_e32 v14, v15, v14
	v_max3_f32 v12, v12, v13, v14
	v_max_f32_e32 v13, v33, v33
	v_max_f32_e32 v14, v32, v32
	v_max_f32_e32 v13, v14, v13
	v_max_f32_e32 v14, v35, v35
	v_max_f32_e32 v15, v34, v34
	v_max_f32_e32 v14, v15, v14
	v_max3_f32 v12, v12, v13, v14
	v_max_f32_e32 v13, v29, v29
	v_max_f32_e32 v14, v28, v28
	v_max_f32_e32 v13, v14, v13
	v_max_f32_e32 v14, v31, v31
	v_max_f32_e32 v15, v30, v30
	v_max_f32_e32 v14, v15, v14
	v_max3_f32 v12, v12, v13, v14
	v_max_f32_e32 v13, v25, v25
	v_max_f32_e32 v14, v24, v24
	v_max_f32_e32 v13, v14, v13
	v_max_f32_e32 v14, v27, v27
	v_max_f32_e32 v15, v26, v26
	v_max_f32_e32 v14, v15, v14
	v_max3_f32 v12, v12, v13, v14
	v_max_f32_e32 v13, v21, v21
	v_max_f32_e32 v14, v20, v20
	v_max_f32_e32 v13, v14, v13
	v_max_f32_e32 v14, v23, v23
	v_max_f32_e32 v15, v22, v22
	v_max_f32_e32 v14, v15, v14
	v_max3_f32 v12, v12, v13, v14
	v_max_f32_e32 v13, v17, v17
	v_max_f32_e32 v14, v16, v16
	v_max_f32_e32 v13, v14, v13
	v_max_f32_e32 v14, v19, v19
	v_max_f32_e32 v15, v18, v18
	v_max_f32_e32 v14, v15, v14
	v_max3_f32 v12, v12, v13, v14
	v_max_f32_e32 v13, v9, v9
	v_max_f32_e32 v14, v8, v8
	v_max_f32_e32 v13, v14, v13
	v_max_f32_e32 v14, v11, v11
	v_max_f32_e32 v15, v10, v10
	v_max_f32_e32 v14, v15, v14
	v_max3_f32 v12, v12, v13, v14
	ds_bpermute_b32 v13, v135, v12
	s_waitcnt lgkmcnt(0)
	v_max_f32_e32 v13, v13, v13
	v_max_f32_e32 v12, v12, v13
	ds_bpermute_b32 v13, v76, v12
	s_waitcnt lgkmcnt(0)
; __device__ __forceinline__ unsigned pk2(float lo, float hi) { return pg8::cvt_pk_bf16(lo, hi); }
; template <int NKT, int VSTR, bool SINK>
; __device__ __forceinline__ void attn_core(LAS const unsigned char* kb_, LAS const unsigned char* vb_, bf16x8 q0, bf16x8 q1, float sk, unsigned mskbits, int fr, f32x4 (&o)[4]) {
;     ...
;     for (int kt = 0; kt < NKT; ++kt) mx = fmaxf(fmaxf(mx, fmaxf(S[kt][0], S[kt][1])), fmaxf(S[kt][2], S[kt][3]));
;     mx = fmaxf(mx, __shfl_xor(mx, 16)); mx = fmaxf(mx, __shfl_xor(mx, 32));
;     if (SINK) mx = fmaxf(mx, sk);
;     float sum = 0.f;
; #pragma unroll
;     for (int kt = 0; kt < NKT; ++kt)
; #pragma unroll
;         for (int r = 0; r < 4; ++r) { const float p = __builtin_amdgcn_exp2f(S[kt][r] - mx); S[kt][r] = p; sum += p; }
;     sum += __shfl_xor(sum, 16); sum += __shfl_xor(sum, 32);
;     if (SINK) sum += __builtin_amdgcn_exp2f(sk - mx);
;     const float inv = 1.0f / sum;
;     bf16x8 pf[NKT / 2];
; #pragma unroll
;     for (int kb = 0; kb < NKT / 2; ++kb) {
;         v4u w; w.x = pk2(S[2 * kb][0], S[2 * kb][1]); w.y = pk2(S[2 * kb][2], S[2 * kb][3]); w.z = pk2(S[2 * kb + 1][0], S[2 * kb + 1][1]); w.w = pk2(S[2 * kb + 1][2], S[2 * kb + 1][3]);
;         pf[kb] = __builtin_bit_cast(bf16x8, w);
;     }
	v_max3_f32 v12, v12, v13, v90
	v_sub_f32_e32 v13, v56, v12
	v_exp_f32_e32 v13, v13
	v_sub_f32_e32 v15, v57, v12
	v_exp_f32_e32 v15, v15
	v_sub_f32_e32 v56, v58, v12
	v_exp_f32_e32 v56, v56
	v_sub_f32_e32 v57, v59, v12
	v_exp_f32_e32 v57, v57
	v_sub_f32_e32 v52, v52, v12
	v_add_f32_e32 v14, 0, v13
	v_exp_f32_e32 v52, v52
	v_sub_f32_e32 v53, v53, v12
	v_add_f32_e32 v14, v15, v14
	v_exp_f32_e32 v53, v53
	v_sub_f32_e32 v54, v54, v12
	v_add_f32_e32 v14, v56, v14
	v_exp_f32_e32 v54, v54
	v_sub_f32_e32 v55, v55, v12
	v_add_f32_e32 v14, v57, v14
	v_exp_f32_e32 v55, v55
	v_sub_f32_e32 v48, v48, v12
	v_add_f32_e32 v14, v52, v14
	v_exp_f32_e32 v48, v48
	v_sub_f32_e32 v49, v49, v12
	v_add_f32_e32 v14, v53, v14
	v_exp_f32_e32 v49, v49
	v_sub_f32_e32 v50, v50, v12
	v_add_f32_e32 v14, v54, v14
	v_exp_f32_e32 v50, v50
	v_sub_f32_e32 v51, v51, v12
	v_add_f32_e32 v14, v55, v14
	v_exp_f32_e32 v51, v51
	v_sub_f32_e32 v44, v44, v12
	v_add_f32_e32 v14, v48, v14
	v_exp_f32_e32 v44, v44
	v_sub_f32_e32 v45, v45, v12
	v_add_f32_e32 v14, v49, v14
	v_exp_f32_e32 v45, v45
	v_sub_f32_e32 v46, v46, v12
	v_add_f32_e32 v14, v50, v14
	v_exp_f32_e32 v46, v46
	v_sub_f32_e32 v47, v47, v12
	v_add_f32_e32 v14, v51, v14
	v_exp_f32_e32 v47, v47
	v_sub_f32_e32 v40, v40, v12
	v_add_f32_e32 v14, v44, v14
	v_exp_f32_e32 v40, v40
	v_sub_f32_e32 v41, v41, v12
	v_add_f32_e32 v14, v45, v14
	v_exp_f32_e32 v41, v41
	v_sub_f32_e32 v42, v42, v12
	v_add_f32_e32 v14, v46, v14
	v_exp_f32_e32 v42, v42
	v_sub_f32_e32 v43, v43, v12
	v_add_f32_e32 v14, v47, v14
	v_exp_f32_e32 v43, v43
	v_sub_f32_e32 v36, v36, v12
	v_add_f32_e32 v14, v40, v14
	v_exp_f32_e32 v36, v36
	v_sub_f32_e32 v37, v37, v12
	v_add_f32_e32 v14, v41, v14
	v_exp_f32_e32 v37, v37
	v_sub_f32_e32 v38, v38, v12
	v_add_f32_e32 v14, v42, v14
	v_exp_f32_e32 v38, v38
	v_sub_f32_e32 v39, v39, v12
	v_add_f32_e32 v14, v43, v14
	v_exp_f32_e32 v39, v39
	v_sub_f32_e32 v32, v32, v12
	v_add_f32_e32 v14, v36, v14
	v_exp_f32_e32 v32, v32
	v_sub_f32_e32 v33, v33, v12
	v_add_f32_e32 v14, v37, v14
	v_exp_f32_e32 v33, v33
	v_sub_f32_e32 v34, v34, v12
	v_add_f32_e32 v14, v38, v14
	v_exp_f32_e32 v34, v34
	v_sub_f32_e32 v35, v35, v12
	v_add_f32_e32 v14, v39, v14
	v_exp_f32_e32 v35, v35
	v_sub_f32_e32 v28, v28, v12
	v_add_f32_e32 v14, v32, v14
	v_exp_f32_e32 v58, v28
	v_sub_f32_e32 v28, v29, v12
	v_add_f32_e32 v14, v33, v14
	v_exp_f32_e32 v59, v28
	v_sub_f32_e32 v28, v30, v12
	v_add_f32_e32 v14, v34, v14
	v_exp_f32_e32 v82, v28
	v_sub_f32_e32 v28, v31, v12
	v_add_f32_e32 v14, v35, v14
	v_exp_f32_e32 v83, v28
	v_sub_f32_e32 v24, v24, v12
	v_add_f32_e32 v14, v58, v14
	v_exp_f32_e32 v84, v24
	v_sub_f32_e32 v24, v25, v12
	v_add_f32_e32 v14, v59, v14
	v_exp_f32_e32 v85, v24
	v_sub_f32_e32 v24, v26, v12
	v_add_f32_e32 v14, v82, v14
	v_exp_f32_e32 v86, v24
	v_sub_f32_e32 v24, v27, v12
	v_add_f32_e32 v14, v83, v14
	v_exp_f32_e32 v87, v24
	v_sub_f32_e32 v20, v20, v12
	v_add_f32_e32 v14, v84, v14
	v_exp_f32_e32 v88, v20
	v_sub_f32_e32 v20, v21, v12
	v_add_f32_e32 v14, v85, v14
	v_exp_f32_e32 v89, v20
	v_sub_f32_e32 v20, v22, v12
	v_add_f32_e32 v14, v86, v14
	v_exp_f32_e32 v90, v20
	v_sub_f32_e32 v20, v23, v12
	v_add_f32_e32 v14, v87, v14
	v_exp_f32_e32 v91, v20
	v_sub_f32_e32 v16, v16, v12
	v_add_f32_e32 v14, v88, v14
	v_exp_f32_e32 v92, v16
	v_sub_f32_e32 v16, v17, v12
	v_add_f32_e32 v14, v89, v14
	v_exp_f32_e32 v93, v16
	v_sub_f32_e32 v16, v18, v12
	v_add_f32_e32 v14, v90, v14
	v_exp_f32_e32 v94, v16
	v_sub_f32_e32 v16, v19, v12
	v_add_f32_e32 v14, v91, v14
	v_exp_f32_e32 v95, v16
	v_sub_f32_e32 v8, v8, v12
	v_add_f32_e32 v14, v92, v14
	v_exp_f32_e32 v96, v8
	v_sub_f32_e32 v9, v9, v12
	v_add_f32_e32 v14, v93, v14
	v_exp_f32_e32 v97, v9
	v_sub_f32_e32 v9, v10, v12
	v_add_f32_e32 v14, v94, v14
	v_exp_f32_e32 v98, v9
	v_sub_f32_e32 v9, v11, v12
	v_add_f32_e32 v14, v95, v14
	v_exp_f32_e32 v11, v9
	v_add_f32_e32 v8, v96, v14
	v_add_f32_e32 v8, v97, v8
	v_add_f32_e32 v8, v98, v8
	v_add_f32_e32 v8, v11, v8
	ds_bpermute_b32 v9, v135, v8
	v_cvt_pk_bf16_f32 v28, v13, v15
	v_cvt_pk_bf16_f32 v29, v56, v57
	v_cvt_pk_bf16_f32 v30, v52, v53
	v_cvt_pk_bf16_f32 v31, v54, v55
	s_waitcnt lgkmcnt(0)
	v_add_f32_e32 v8, v8, v9
	ds_bpermute_b32 v9, v76, v8
	v_cvt_pk_bf16_f32 v24, v48, v49
	v_cvt_pk_bf16_f32 v25, v50, v51
	v_cvt_pk_bf16_f32 v26, v44, v45
	v_cvt_pk_bf16_f32 v27, v46, v47
	s_waitcnt lgkmcnt(0)
	v_add_f32_e32 v8, v8, v9
	v_fma_f32 v9, v81, s2, -v12
	v_exp_f32_e32 v9, v9
	v_cvt_pk_bf16_f32 v20, v40, v41
	v_cvt_pk_bf16_f32 v21, v42, v43
	v_cvt_pk_bf16_f32 v22, v36, v37
	v_cvt_pk_bf16_f32 v23, v38, v39
	v_cvt_pk_bf16_f32 v16, v32, v33
	s_nop 0
	v_add_f32_e32 v81, v9, v8
	v_div_scale_f32 v32, s[0:1], v81, v81, 1.0
	v_rcp_f32_e32 v33, v32
	v_cvt_pk_bf16_f32 v17, v34, v35
	v_cvt_pk_bf16_f32 v18, v58, v59
	v_cvt_pk_bf16_f32 v19, v82, v83
	v_cvt_pk_bf16_f32 v12, v84, v85
	v_cvt_pk_bf16_f32 v13, v86, v87
	s_nop 0
	v_fma_f32 v34, -v32, v33, 1.0
	v_fmac_f32_e32 v33, v34, v33
	v_div_scale_f32 v34, vcc, 1.0, v81, 1.0
	v_mul_f32_e32 v35, v34, v33
	v_fma_f32 v36, -v32, v35, v34
	v_fmac_f32_e32 v35, v36, v33
	v_fma_f32 v32, -v32, v35, v34
	v_cvt_pk_bf16_f32 v14, v88, v89
	v_cvt_pk_bf16_f32 v15, v90, v91
	v_cvt_pk_bf16_f32 v8, v92, v93
	v_cvt_pk_bf16_f32 v9, v94, v95
	v_cvt_pk_bf16_f32 v10, v96, v97
	v_cvt_pk_bf16_f32 v11, v98, v11
	v_div_fmas_f32 v32, v32, v33, v35
	s_waitcnt lgkmcnt(0)
; #define LAS __attribute__((address_space(3)))
; __device__ __forceinline__ float sq4(const f32x4 a) { return (a[0] * a[0] + a[1] * a[1]) + (a[2] * a[2] + a[3] * a[3]); }
; #define LAS __attribute__((address_space(3)))
; __device__ __forceinline__ unsigned pk2(float lo, float hi) { return pg8::cvt_pk_bf16(lo, hi); }
; __device__ __forceinline__ f32x4 mfma16(bf16x8 a, bf16x8 b, f32x4 c) { return __builtin_amdgcn_mfma_f32_16x16x32_bf16(a, b, c, 0, 0, 0); }
; template <int NKT, int VSTR, bool SINK>
; __device__ __forceinline__ void attn_core(LAS const unsigned char* kb_, LAS const unsigned char* vb_, bf16x8 q0, bf16x8 q1, float sk, unsigned mskbits, int fr, f32x4 (&o)[4]) {
;     ...
; #pragma unroll
;     for (int dt = 0; dt < 4; ++dt) {
;         f32x4 acc = (f32x4){0.f, 0.f, 0.f, 0.f};
; #pragma unroll
;         for (int kb = 0; kb < NKT / 2; ++kb) {
;             const bf16x8 vf = *(LAS const bf16x8*)(vb_ + dt * 16 * VSTR + kb * 64);
;             acc = mfma16(vf, pf[kb], acc);
;         }
;         o[dt] = acc * inv;
;     }
; template <bool DO_SWA, bool DO_MEM>
; __device__ __forceinline__ void attn_unit(const Args& a, unsigned char* ws, LAS unsigned char* lds, int l, int tid_in, int lane_in, int wave, int unit) {
;     ...
;                 const float sk = a.in[12][l * 8 + h] * LOG2E;
;                 f32x4 o[4];
;                 attn_core<12, 400, true>(lds + A_KS + g * 192 * 144 + fq * 16, lds + A_VT1 + (g * 64 + fr) * 400 + fq * 16, qsw[hh][0], qsw[hh][1], sk, mskbits, fr, o);
; #pragma unroll
;                 for (int dt = 0; dt < 4; ++dt) { ssq += pg8::sq4(o[dt]); osv[hh][dt] = (v2u){pk2(o[dt][0], o[dt][1]), pk2(o[dt][2], o[dt][3])}; }
	ds_read_b128 v[196:199], v78 offset:55296
	ds_read_b128 v[200:203], v78 offset:55360
	ds_read_b128 v[204:207], v78 offset:61760
	ds_read_b128 v[208:211], v77 offset:12864
	ds_read_b128 v[212:215], v78 offset:55424
	ds_read_b128 v[228:231], v78 offset:55488
	ds_read_b128 v[232:235], v78 offset:55552
	ds_read_b128 v[236:239], v78 offset:55616
	ds_read_b128 v[240:243], v78 offset:61696
	ds_read_b128 v[244:247], v78 offset:61824
	s_waitcnt lgkmcnt(9)
	v_mfma_f32_16x16x32_bf16 v[34:37], v[196:199], v[28:31], 0
	ds_read_b128 v[196:199], v78 offset:61888
	v_div_fixup_f32 v32, v32, v81, 1.0
	s_waitcnt lgkmcnt(9)
	v_mfma_f32_16x16x32_bf16 v[34:37], v[200:203], v[24:27], v[34:37]
	ds_read_b128 v[200:203], v78 offset:61952
	s_waitcnt lgkmcnt(7)
	v_mfma_f32_16x16x32_bf16 v[34:37], v[212:215], v[20:23], v[34:37]
	ds_read_b128 v[212:215], v78 offset:62016
	s_waitcnt lgkmcnt(7)
	v_mfma_f32_16x16x32_bf16 v[34:37], v[228:231], v[16:19], v[34:37]
	ds_read_b128 v[228:231], v77 offset:12800
	s_waitcnt lgkmcnt(7)
	v_mfma_f32_16x16x32_bf16 v[34:37], v[232:235], v[12:15], v[34:37]
	ds_read_b128 v[232:235], v77 offset:12928
	s_waitcnt lgkmcnt(7)
	v_mfma_f32_16x16x32_bf16 v[36:39], v[236:239], v[8:11], v[34:37]
	ds_read_b128 v[236:239], v77 offset:12992
	s_nop 7
	v_pk_mul_f32 v[34:35], v[38:39], v[32:33] op_sel_hi:[1,0]
	s_waitcnt lgkmcnt(7)
	v_mfma_f32_16x16x32_bf16 v[38:41], v[240:243], v[28:31], 0
	ds_read_b128 v[240:243], v77 offset:13056
	v_mul_f32_e64 v36, v36, v32
	v_mul_f32_e64 v37, v37, v32
	v_mfma_f32_16x16x32_bf16 v[38:41], v[204:207], v[24:27], v[38:41]
	ds_read_b128 v[204:207], v77 offset:13120
	s_waitcnt lgkmcnt(8)
	v_mfma_f32_16x16x32_bf16 v[38:41], v[244:247], v[20:23], v[38:41]
	ds_read_b128 v[244:247], v77 offset:19200
	s_waitcnt lgkmcnt(8)
	v_mfma_f32_16x16x32_bf16 v[38:41], v[196:199], v[16:19], v[38:41]
	ds_read_b128 v[196:199], v77 offset:19264
	s_waitcnt lgkmcnt(8)
	v_mfma_f32_16x16x32_bf16 v[38:41], v[200:203], v[12:15], v[38:41]
	ds_read_b128 v[200:203], v77 offset:19328
	s_waitcnt lgkmcnt(8)
	v_mfma_f32_16x16x32_bf16 v[40:43], v[212:215], v[8:11], v[38:41]
	s_nop 7
	v_pk_mul_f32 v[38:39], v[42:43], v[32:33] op_sel_hi:[1,0]
	ds_read_b128 v[212:215], v77 offset:19392
	s_waitcnt lgkmcnt(8)
	v_mfma_f32_16x16x32_bf16 v[42:45], v[228:231], v[28:31], 0
	v_mul_f32_e64 v40, v40, v32
	v_mul_f32_e64 v41, v41, v32
	v_mfma_f32_16x16x32_bf16 v[42:45], v[208:211], v[24:27], v[42:45]
	ds_read_b128 v[228:231], v77 offset:19456
	s_waitcnt lgkmcnt(8)
	v_mfma_f32_16x16x32_bf16 v[42:45], v[232:235], v[20:23], v[42:45]
	ds_read_b128 v[208:211], v77 offset:19520
	s_waitcnt lgkmcnt(8)
	v_mfma_f32_16x16x32_bf16 v[42:45], v[236:239], v[16:19], v[42:45]
	s_waitcnt lgkmcnt(7)
	v_mfma_f32_16x16x32_bf16 v[42:45], v[240:243], v[12:15], v[42:45]
	s_waitcnt lgkmcnt(6)
	v_mfma_f32_16x16x32_bf16 v[44:47], v[204:207], v[8:11], v[42:45]
	s_nop 7
	v_pk_mul_f32 v[42:43], v[32:33], v[46:47] op_sel_hi:[0,1]
	s_waitcnt lgkmcnt(5)
	v_mfma_f32_16x16x32_bf16 v[28:31], v[244:247], v[28:31], 0
	v_pk_mul_f32 v[44:45], v[32:33], v[44:45] op_sel_hi:[0,1]
	s_waitcnt lgkmcnt(4)
	v_mfma_f32_16x16x32_bf16 v[24:27], v[196:199], v[24:27], v[28:31]
	s_waitcnt lgkmcnt(3)
	v_mfma_f32_16x16x32_bf16 v[20:23], v[200:203], v[20:23], v[24:27]
	s_waitcnt lgkmcnt(2)
	v_mfma_f32_16x16x32_bf16 v[16:19], v[212:215], v[16:19], v[20:23]
	s_waitcnt lgkmcnt(1)
	v_mfma_f32_16x16x32_bf16 v[12:15], v[228:231], v[12:15], v[16:19]
	v_cvt_pk_bf16_f32 v53, v36, v37
	v_cvt_pk_bf16_f32 v52, v34, v35
	s_waitcnt lgkmcnt(0)
	v_mfma_f32_16x16x32_bf16 v[8:11], v[208:211], v[8:11], v[12:15]
	s_nop 2
	v_mul_f32_e32 v12, v37, v37
	v_mul_f32_e32 v13, v35, v35
	v_fmac_f32_e32 v12, v36, v36
	v_fmac_f32_e32 v13, v34, v34
	v_add_f32_e32 v12, v12, v13
	v_mul_f32_e32 v13, v41, v41
	v_mul_f32_e32 v14, v39, v39
	v_fmac_f32_e32 v13, v40, v40
	v_fmac_f32_e32 v14, v38, v38
	v_add_f32_e32 v12, v80, v12
	v_add_f32_e32 v13, v13, v14
	v_add_f32_e32 v12, v13, v12
	v_mul_f32_e32 v13, v45, v45
	v_mul_f32_e32 v14, v43, v43
	v_fmac_f32_e32 v13, v44, v44
	v_fmac_f32_e32 v14, v42, v42
	v_pk_mul_f32 v[10:11], v[32:33], v[10:11] op_sel_hi:[0,1]
	v_pk_mul_f32 v[8:9], v[32:33], v[8:9] op_sel_hi:[0,1]
	v_add_f32_e32 v13, v13, v14
	v_add_f32_e32 v12, v13, v12
	v_mul_f32_e32 v13, v9, v9
	v_mul_f32_e32 v14, v11, v11
	v_fmac_f32_e32 v13, v8, v8
	v_fmac_f32_e32 v14, v10, v10
	v_add_f32_e32 v13, v13, v14
	v_cvt_pk_bf16_f32 v55, v40, v41
	v_cvt_pk_bf16_f32 v54, v38, v39
	v_cvt_pk_bf16_f32 v57, v44, v45
	v_cvt_pk_bf16_f32 v56, v42, v43
	v_add_f32_e32 v80, v12, v13
	v_cvt_pk_bf16_f32 v59, v8, v9
	v_cvt_pk_bf16_f32 v58, v10, v11
	v_mov_b32_e32 v81, s101
	s_waitcnt lgkmcnt(0)
	ds_read_b128 v[92:95], v79
	ds_read_b128 v[196:199], v79 offset:64
	ds_read_b128 v[200:203], v79 offset:576
	ds_read_b128 v[204:207], v79 offset:640
	ds_read_b128 v[208:211], v79 offset:4608
	ds_read_b128 v[212:215], v79 offset:4672
	ds_read_b128 v[228:231], v79 offset:5184
	ds_read_b128 v[232:235], v79 offset:5248
	ds_read_b128 v[236:239], v79 offset:9216
	ds_read_b128 v[240:243], v79 offset:9280
	ds_read_b128 v[244:247], v79 offset:9792
	s_waitcnt lgkmcnt(10)
	v_mfma_f32_16x16x32_bf16 v[8:11], v[92:95], v[4:7], 0

; #define LAS __attribute__((address_space(3)))
; #define LAS __attribute__((address_space(3)))
; __device__ __forceinline__ f32x4 mfma16(bf16x8 a, bf16x8 b, f32x4 c) { return __builtin_amdgcn_mfma_f32_16x16x32_bf16(a, b, c, 0, 0, 0); }
; template <int NKT, int VSTR, bool SINK>
; __device__ __forceinline__ void attn_core(LAS const unsigned char* kb_, LAS const unsigned char* vb_, bf16x8 q0, bf16x8 q1, float sk, unsigned mskbits, int fr, f32x4 (&o)[4]) {
;     ...
;     for (int kt = 0; kt < NKT; ++kt) {
;         const int key = (kt >> 1) * 32 + ((kt & 1) << 2) + krow;
;         LAS const unsigned char* kp = kb_ + key * 144;
;         const bf16x8 a0 = *(LAS const bf16x8*)kp, a1 = *(LAS const bf16x8*)(kp + 64);
;         const float bias = ((mskbits >> (kt >> 2)) & 1u) ? -1e30f : 0.f;
;         f32x4 s = mfma16(a0, q0, (f32x4){bias, bias, bias, bias});
;         s = mfma16(a1, q1, s);
;         S[kt] = s;
;     }
;     float mx = S[0][0];
; #pragma unroll
;     for (int kt = 0; kt < NKT; ++kt) mx = fmaxf(fmaxf(mx, fmaxf(S[kt][0], S[kt][1])), fmaxf(S[kt][2], S[kt][3]));
;     mx = fmaxf(mx, __shfl_xor(mx, 16)); mx = fmaxf(mx, __shfl_xor(mx, 32));
	v_mul_f32_e32 v82, 0x3fb8aa3b, v81
	s_waitcnt lgkmcnt(9)
	v_mfma_f32_16x16x32_bf16 v[36:39], v[196:199], v[0:3], v[8:11]
	ds_read_b128 v[92:95], v79 offset:9856
	ds_read_b128 v[196:199], v79 offset:13824
	s_waitcnt lgkmcnt(10)
	v_mfma_f32_16x16x32_bf16 v[8:11], v[200:203], v[4:7], 0
	s_waitcnt lgkmcnt(9)
	v_mfma_f32_16x16x32_bf16 v[28:31], v[204:207], v[0:3], v[8:11]
	ds_read_b128 v[200:203], v79 offset:13888
	ds_read_b128 v[204:207], v79 offset:14400
	s_waitcnt lgkmcnt(10)
	v_mfma_f32_16x16x32_bf16 v[8:11], v[208:211], v[4:7], 0
	s_waitcnt lgkmcnt(9)
	v_mfma_f32_16x16x32_bf16 v[20:23], v[212:215], v[0:3], v[8:11]
	ds_read_b128 v[208:211], v79 offset:14464
	ds_read_b128 v[212:215], v79 offset:18432
	s_waitcnt lgkmcnt(10)
	v_mfma_f32_16x16x32_bf16 v[8:11], v[228:231], v[4:7], 0
	s_waitcnt lgkmcnt(9)
	v_mfma_f32_16x16x32_bf16 v[12:15], v[232:235], v[0:3], v[8:11]
	ds_read_b128 v[228:231], v79 offset:18496
	ds_read_b128 v[232:235], v79 offset:19008
	s_waitcnt lgkmcnt(10)
	v_mfma_f32_16x16x32_bf16 v[8:11], v[236:239], v[4:7], 0
	s_waitcnt lgkmcnt(9)
	v_mfma_f32_16x16x32_bf16 v[8:11], v[240:243], v[0:3], v[8:11]
	ds_read_b128 v[236:239], v79 offset:19072
	ds_read_b128 v[240:243], v79 offset:23040
	s_waitcnt lgkmcnt(10)
	v_mfma_f32_16x16x32_bf16 v[16:19], v[244:247], v[4:7], 0
	s_waitcnt lgkmcnt(9)
	v_mfma_f32_16x16x32_bf16 v[16:19], v[92:95], v[0:3], v[16:19]
	ds_read_b128 v[244:247], v79 offset:23104
	ds_read_b128 v[92:95], v79 offset:23616
	s_waitcnt lgkmcnt(10)
	v_mfma_f32_16x16x32_bf16 v[24:27], v[196:199], v[4:7], 0
	s_waitcnt lgkmcnt(9)
	v_mfma_f32_16x16x32_bf16 v[24:27], v[200:203], v[0:3], v[24:27]
	ds_read_b128 v[196:199], v79 offset:23680
	s_waitcnt lgkmcnt(9)
	v_mfma_f32_16x16x32_bf16 v[32:35], v[204:207], v[4:7], 0
	s_waitcnt lgkmcnt(8)
	v_mfma_f32_16x16x32_bf16 v[32:35], v[208:211], v[0:3], v[32:35]
	s_waitcnt lgkmcnt(7)
	v_mfma_f32_16x16x32_bf16 v[40:43], v[212:215], v[4:7], 0
	s_waitcnt lgkmcnt(6)
	v_mfma_f32_16x16x32_bf16 v[40:43], v[228:231], v[0:3], v[40:43]
	s_waitcnt lgkmcnt(5)
	v_mfma_f32_16x16x32_bf16 v[44:47], v[232:235], v[4:7], 0
	s_waitcnt lgkmcnt(4)
	v_mfma_f32_16x16x32_bf16 v[44:47], v[236:239], v[0:3], v[44:47]
	s_waitcnt lgkmcnt(3)
	v_mfma_f32_16x16x32_bf16 v[48:51], v[240:243], v[4:7], 0
	s_waitcnt lgkmcnt(2)
	v_mfma_f32_16x16x32_bf16 v[48:51], v[244:247], v[0:3], v[48:51]
	s_waitcnt lgkmcnt(1)
	v_mfma_f32_16x16x32_bf16 v[4:7], v[92:95], v[4:7], 0
	s_waitcnt lgkmcnt(0)
	v_mfma_f32_16x16x32_bf16 v[0:3], v[196:199], v[0:3], v[4:7]
	s_nop 5
	v_max_f32_e32 v4, v39, v39
	v_max_f32_e32 v5, v38, v38
	v_max_f32_e32 v4, v5, v4
	v_max_f32_e32 v5, v29, v29
	v_max_f32_e32 v6, v28, v28
	v_max_f32_e32 v5, v6, v5
	v_max_f32_e32 v6, v31, v31
	v_max_f32_e32 v7, v30, v30
	v_max3_f32 v4, v36, v37, v4
	v_max_f32_e32 v6, v7, v6
	v_max3_f32 v4, v4, v5, v6
	v_max_f32_e32 v5, v21, v21
	v_max_f32_e32 v6, v20, v20
	v_max_f32_e32 v5, v6, v5
	v_max_f32_e32 v6, v23, v23
	v_max_f32_e32 v7, v22, v22
	v_max_f32_e32 v6, v7, v6
	v_max3_f32 v4, v4, v5, v6
	v_max_f32_e32 v5, v13, v13
	v_max_f32_e32 v6, v12, v12
	v_max_f32_e32 v5, v6, v5
	v_max_f32_e32 v6, v15, v15
	v_max_f32_e32 v7, v14, v14
	v_max_f32_e32 v6, v7, v6
	v_max3_f32 v4, v4, v5, v6
	v_max_f32_e32 v5, v9, v9
	v_max_f32_e32 v6, v8, v8
	v_max_f32_e32 v5, v6, v5
	v_max_f32_e32 v6, v11, v11
	v_max_f32_e32 v7, v10, v10
	v_max_f32_e32 v6, v7, v6
	v_max3_f32 v4, v4, v5, v6
	v_max_f32_e32 v5, v17, v17
	v_max_f32_e32 v6, v16, v16
	v_max_f32_e32 v5, v6, v5
	v_max_f32_e32 v6, v19, v19
	v_max_f32_e32 v7, v18, v18
	v_max_f32_e32 v6, v7, v6
	v_max3_f32 v4, v4, v5, v6
	v_max_f32_e32 v5, v25, v25
	v_max_f32_e32 v6, v24, v24
	v_max_f32_e32 v5, v6, v5
	v_max_f32_e32 v6, v27, v27
	v_max_f32_e32 v7, v26, v26
	v_max_f32_e32 v6, v7, v6
	v_max3_f32 v4, v4, v5, v6
	v_max_f32_e32 v5, v33, v33
	v_max_f32_e32 v6, v32, v32
	v_max_f32_e32 v5, v6, v5
	v_max_f32_e32 v6, v35, v35
	v_max_f32_e32 v7, v34, v34
	v_max_f32_e32 v6, v7, v6
	v_max3_f32 v4, v4, v5, v6
	v_max_f32_e32 v5, v41, v41
	v_max_f32_e32 v6, v40, v40
	v_max_f32_e32 v5, v6, v5
	v_max_f32_e32 v6, v43, v43
	v_max_f32_e32 v7, v42, v42
	v_max_f32_e32 v6, v7, v6
	v_max3_f32 v4, v4, v5, v6
	v_max_f32_e32 v5, v45, v45
	v_max_f32_e32 v6, v44, v44
	v_max_f32_e32 v5, v6, v5
	v_max_f32_e32 v6, v47, v47
	v_max_f32_e32 v7, v46, v46
	v_max_f32_e32 v6, v7, v6
	v_max3_f32 v4, v4, v5, v6
	v_max_f32_e32 v5, v49, v49
	v_max_f32_e32 v6, v48, v48
	v_max_f32_e32 v5, v6, v5
	v_max_f32_e32 v6, v51, v51
	v_max_f32_e32 v7, v50, v50
	v_max_f32_e32 v6, v7, v6
	v_max3_f32 v4, v4, v5, v6
	v_max_f32_e32 v5, v1, v1
	v_max_f32_e32 v6, v0, v0
	v_max_f32_e32 v5, v6, v5
	v_max_f32_e32 v6, v3, v3
	v_max_f32_e32 v7, v2, v2
	v_max_f32_e32 v6, v7, v6
	v_max3_f32 v4, v4, v5, v6
	ds_bpermute_b32 v5, v135, v4
	s_waitcnt lgkmcnt(0)
	v_max_f32_e32 v5, v5, v5
	v_max_f32_e32 v4, v4, v5
	ds_bpermute_b32 v5, v76, v4
	s_waitcnt lgkmcnt(0)
; __device__ __forceinline__ unsigned pk2(float lo, float hi) { return pg8::cvt_pk_bf16(lo, hi); }
; template <int NKT, int VSTR, bool SINK>
; __device__ __forceinline__ void attn_core(LAS const unsigned char* kb_, LAS const unsigned char* vb_, bf16x8 q0, bf16x8 q1, float sk, unsigned mskbits, int fr, f32x4 (&o)[4]) {
;     ...
;     for (int kt = 0; kt < NKT; ++kt) mx = fmaxf(fmaxf(mx, fmaxf(S[kt][0], S[kt][1])), fmaxf(S[kt][2], S[kt][3]));
;     mx = fmaxf(mx, __shfl_xor(mx, 16)); mx = fmaxf(mx, __shfl_xor(mx, 32));
;     if (SINK) mx = fmaxf(mx, sk);
;     float sum = 0.f;
; #pragma unroll
;     for (int kt = 0; kt < NKT; ++kt)
; #pragma unroll
;         for (int r = 0; r < 4; ++r) { const float p = __builtin_amdgcn_exp2f(S[kt][r] - mx); S[kt][r] = p; sum += p; }
;     sum += __shfl_xor(sum, 16); sum += __shfl_xor(sum, 32);
;     if (SINK) sum += __builtin_amdgcn_exp2f(sk - mx);
;     const float inv = 1.0f / sum;
;     bf16x8 pf[NKT / 2];
; #pragma unroll
;     for (int kb = 0; kb < NKT / 2; ++kb) {
;         v4u w; w.x = pk2(S[2 * kb][0], S[2 * kb][1]); w.y = pk2(S[2 * kb][2], S[2 * kb][3]); w.z = pk2(S[2 * kb + 1][0], S[2 * kb + 1][1]); w.w = pk2(S[2 * kb + 1][2], S[2 * kb + 1][3]);
;         pf[kb] = __builtin_bit_cast(bf16x8, w);
;     }
	v_max3_f32 v4, v4, v5, v82
	v_sub_f32_e32 v5, v36, v4
	v_exp_f32_e32 v5, v5
	v_sub_f32_e32 v7, v37, v4
	v_exp_f32_e32 v7, v7
	v_sub_f32_e32 v36, v38, v4
	v_exp_f32_e32 v36, v36
	v_sub_f32_e32 v37, v39, v4
	v_exp_f32_e32 v37, v37
	v_sub_f32_e32 v28, v28, v4
	v_add_f32_e32 v6, 0, v5
	v_exp_f32_e32 v28, v28
	v_sub_f32_e32 v29, v29, v4
	v_add_f32_e32 v6, v7, v6
	v_exp_f32_e32 v29, v29
	v_sub_f32_e32 v30, v30, v4
	v_add_f32_e32 v6, v36, v6
	v_exp_f32_e32 v30, v30
	v_sub_f32_e32 v31, v31, v4
	v_add_f32_e32 v6, v37, v6
	v_exp_f32_e32 v31, v31
	v_sub_f32_e32 v20, v20, v4
	v_add_f32_e32 v6, v28, v6
	v_exp_f32_e32 v38, v20
	v_sub_f32_e32 v20, v21, v4
	v_add_f32_e32 v6, v29, v6
	v_exp_f32_e32 v39, v20
	v_sub_f32_e32 v20, v22, v4
	v_add_f32_e32 v6, v30, v6
	v_exp_f32_e32 v79, v20
	v_sub_f32_e32 v20, v23, v4
	v_add_f32_e32 v6, v31, v6
	v_exp_f32_e32 v82, v20
	v_sub_f32_e32 v12, v12, v4
	v_add_f32_e32 v6, v38, v6
	v_exp_f32_e32 v12, v12
	v_sub_f32_e32 v13, v13, v4
	v_add_f32_e32 v6, v39, v6
	v_exp_f32_e32 v13, v13
	v_sub_f32_e32 v14, v14, v4
	v_add_f32_e32 v6, v79, v6
	v_exp_f32_e32 v14, v14
	v_sub_f32_e32 v15, v15, v4
	v_add_f32_e32 v6, v82, v6
	v_exp_f32_e32 v15, v15
	v_sub_f32_e32 v8, v8, v4
	v_add_f32_e32 v6, v12, v6
	v_exp_f32_e32 v8, v8
	v_sub_f32_e32 v9, v9, v4
	v_add_f32_e32 v6, v13, v6
	v_exp_f32_e32 v9, v9
	v_sub_f32_e32 v10, v10, v4
	v_add_f32_e32 v6, v14, v6
	v_exp_f32_e32 v10, v10
	v_sub_f32_e32 v11, v11, v4
	v_add_f32_e32 v6, v15, v6
	v_exp_f32_e32 v11, v11
	v_sub_f32_e32 v16, v16, v4
	v_add_f32_e32 v6, v8, v6
	v_exp_f32_e32 v83, v16
	v_sub_f32_e32 v16, v17, v4
	v_add_f32_e32 v6, v9, v6
	v_exp_f32_e32 v84, v16
	v_sub_f32_e32 v16, v18, v4
	v_add_f32_e32 v6, v10, v6
	v_exp_f32_e32 v85, v16
	v_sub_f32_e32 v16, v19, v4
	v_add_f32_e32 v6, v11, v6
	v_exp_f32_e32 v86, v16
	v_sub_f32_e32 v16, v24, v4
	v_add_f32_e32 v6, v83, v6
	v_exp_f32_e32 v24, v16
	v_sub_f32_e32 v16, v25, v4
	v_add_f32_e32 v6, v84, v6
	v_exp_f32_e32 v25, v16
	v_sub_f32_e32 v16, v26, v4
	v_add_f32_e32 v6, v85, v6
	v_exp_f32_e32 v26, v16
	v_sub_f32_e32 v16, v27, v4
	v_add_f32_e32 v6, v86, v6
	v_exp_f32_e32 v27, v16
	v_sub_f32_e32 v16, v32, v4
	v_add_f32_e32 v6, v24, v6
	v_exp_f32_e32 v32, v16
	v_sub_f32_e32 v16, v33, v4
	v_add_f32_e32 v6, v25, v6
	v_exp_f32_e32 v33, v16
	v_sub_f32_e32 v16, v34, v4
	v_add_f32_e32 v6, v26, v6
	v_exp_f32_e32 v34, v16
	v_sub_f32_e32 v16, v35, v4
	v_add_f32_e32 v6, v27, v6
	v_exp_f32_e32 v35, v16
	v_sub_f32_e32 v16, v40, v4
	v_add_f32_e32 v6, v32, v6
	v_exp_f32_e32 v40, v16
	v_sub_f32_e32 v16, v41, v4
	v_add_f32_e32 v6, v33, v6
	v_exp_f32_e32 v41, v16
	v_sub_f32_e32 v16, v42, v4
	v_add_f32_e32 v6, v34, v6
	v_exp_f32_e32 v42, v16
	v_sub_f32_e32 v16, v43, v4
	v_add_f32_e32 v6, v35, v6
	v_exp_f32_e32 v43, v16
	v_sub_f32_e32 v16, v44, v4
	v_add_f32_e32 v6, v40, v6
	v_exp_f32_e32 v44, v16
	v_sub_f32_e32 v16, v45, v4
	v_add_f32_e32 v6, v41, v6
	v_exp_f32_e32 v45, v16
	v_sub_f32_e32 v16, v46, v4
	v_add_f32_e32 v6, v42, v6
	v_exp_f32_e32 v46, v16
	v_sub_f32_e32 v16, v47, v4
	v_add_f32_e32 v6, v43, v6
	v_exp_f32_e32 v47, v16
	v_sub_f32_e32 v16, v48, v4
	v_add_f32_e32 v6, v44, v6
	v_exp_f32_e32 v48, v16
	v_sub_f32_e32 v16, v49, v4
	v_add_f32_e32 v6, v45, v6
	v_exp_f32_e32 v49, v16
	v_sub_f32_e32 v16, v50, v4
	v_add_f32_e32 v6, v46, v6
	v_exp_f32_e32 v50, v16
	v_sub_f32_e32 v16, v51, v4
	v_add_f32_e32 v6, v47, v6
	v_exp_f32_e32 v51, v16
	v_sub_f32_e32 v0, v0, v4
	v_add_f32_e32 v6, v48, v6
	v_exp_f32_e32 v87, v0
	v_sub_f32_e32 v1, v1, v4
	v_add_f32_e32 v6, v49, v6
	v_exp_f32_e32 v88, v1
	v_sub_f32_e32 v1, v2, v4
	v_add_f32_e32 v6, v50, v6
	v_exp_f32_e32 v89, v1
	v_sub_f32_e32 v1, v3, v4
	v_add_f32_e32 v6, v51, v6
	v_exp_f32_e32 v3, v1
	v_add_f32_e32 v0, v87, v6
	v_add_f32_e32 v0, v88, v0
	v_add_f32_e32 v0, v89, v0
	v_add_f32_e32 v0, v3, v0
	ds_bpermute_b32 v1, v135, v0
	v_cvt_pk_bf16_f32 v20, v5, v7
	v_cvt_pk_bf16_f32 v21, v36, v37
	v_cvt_pk_bf16_f32 v22, v28, v29
	v_cvt_pk_bf16_f32 v23, v30, v31
	s_waitcnt lgkmcnt(0)
	v_add_f32_e32 v0, v0, v1
	ds_bpermute_b32 v1, v76, v0
	v_cvt_pk_bf16_f32 v16, v38, v39
	v_cvt_pk_bf16_f32 v17, v79, v82
	v_cvt_pk_bf16_f32 v18, v12, v13
	v_cvt_pk_bf16_f32 v19, v14, v15
	s_waitcnt lgkmcnt(0)
	v_add_f32_e32 v0, v0, v1
	v_fma_f32 v1, v81, s2, -v4
	v_exp_f32_e32 v1, v1
	v_cvt_pk_bf16_f32 v12, v8, v9
	v_cvt_pk_bf16_f32 v13, v10, v11
	v_cvt_pk_bf16_f32 v14, v83, v84
	v_cvt_pk_bf16_f32 v15, v85, v86
	v_cvt_pk_bf16_f32 v8, v24, v25
	s_nop 0
	v_add_f32_e32 v81, v1, v0
	v_div_scale_f32 v24, s[0:1], v81, v81, 1.0
	v_rcp_f32_e32 v25, v24
	v_cvt_pk_bf16_f32 v9, v26, v27
	v_cvt_pk_bf16_f32 v10, v32, v33
	v_cvt_pk_bf16_f32 v11, v34, v35
	v_cvt_pk_bf16_f32 v4, v40, v41
	v_cvt_pk_bf16_f32 v5, v42, v43
	s_nop 0
	v_fma_f32 v26, -v24, v25, 1.0
	v_fmac_f32_e32 v25, v26, v25
	v_div_scale_f32 v26, vcc, 1.0, v81, 1.0
	v_mul_f32_e32 v27, v26, v25
	v_fma_f32 v28, -v24, v27, v26
	v_fmac_f32_e32 v27, v28, v25
	v_fma_f32 v24, -v24, v27, v26
	v_cvt_pk_bf16_f32 v6, v44, v45
	v_cvt_pk_bf16_f32 v7, v46, v47
	v_cvt_pk_bf16_f32 v0, v48, v49
	v_cvt_pk_bf16_f32 v1, v50, v51
	v_cvt_pk_bf16_f32 v2, v87, v88
	v_cvt_pk_bf16_f32 v3, v89, v3
	v_div_fmas_f32 v24, v24, v25, v27
	s_waitcnt lgkmcnt(0)
; #define LAS __attribute__((address_space(3)))
; __device__ __forceinline__ float quad_sum(float s) { s += __shfl_xor(s, 16); s += __shfl_xor(s, 32); return s; }
; __device__ __forceinline__ float sq4(const f32x4 a) { return (a[0] * a[0] + a[1] * a[1]) + (a[2] * a[2] + a[3] * a[3]); }
; #define LAS __attribute__((address_space(3)))
; __device__ __forceinline__ unsigned pk2(float lo, float hi) { return pg8::cvt_pk_bf16(lo, hi); }
; __device__ __forceinline__ f32x4 mfma16(bf16x8 a, bf16x8 b, f32x4 c) { return __builtin_amdgcn_mfma_f32_16x16x32_bf16(a, b, c, 0, 0, 0); }
; template <int NKT, int VSTR, bool SINK>
; __device__ __forceinline__ void attn_core(LAS const unsigned char* kb_, LAS const unsigned char* vb_, bf16x8 q0, bf16x8 q1, float sk, unsigned mskbits, int fr, f32x4 (&o)[4]) {
;     ...
; #pragma unroll
;     for (int dt = 0; dt < 4; ++dt) {
;         f32x4 acc = (f32x4){0.f, 0.f, 0.f, 0.f};
; #pragma unroll
;         for (int kb = 0; kb < NKT / 2; ++kb) {
;             const bf16x8 vf = *(LAS const bf16x8*)(vb_ + dt * 16 * VSTR + kb * 64);
;             acc = mfma16(vf, pf[kb], acc);
;         }
;         o[dt] = acc * inv;
;     }
; template <bool DO_SWA, bool DO_MEM>
; __device__ __forceinline__ void attn_unit(const Args& a, unsigned char* ws, LAS unsigned char* lds, int l, int tid_in, int lane_in, int wave, int unit) {
;     ...
; #pragma unroll
;                 for (int dt = 0; dt < 4; ++dt) { ssq += pg8::sq4(o[dt]); osv[hh][dt] = (v2u){pk2(o[dt][0], o[dt][1]), pk2(o[dt][2], o[dt][3])}; }
;             }
;             ssq = pg8::quad_sum(ssq);
;             if (fq == 0) red_a[g * 64 + qs * 16 + fr] = ssq;
	ds_read_b128 v[92:95], v78 offset:55296
	ds_read_b128 v[196:199], v78 offset:55360
	ds_read_b128 v[200:203], v78 offset:61760
	ds_read_b128 v[204:207], v77 offset:12864
	ds_read_b128 v[208:211], v78 offset:55424
	ds_read_b128 v[212:215], v78 offset:55488
	ds_read_b128 v[228:231], v78 offset:55552
	ds_read_b128 v[232:235], v78 offset:55616
	ds_read_b128 v[236:239], v78 offset:61696
	ds_read_b128 v[240:243], v78 offset:61824
	ds_read_b128 v[244:247], v78 offset:61888
	s_waitcnt lgkmcnt(10)
	v_mfma_f32_16x16x32_bf16 v[26:29], v[92:95], v[20:23], 0
	ds_read_b128 v[92:95], v78 offset:61952
	v_div_fixup_f32 v24, v24, v81, 1.0
	s_waitcnt lgkmcnt(10)
	v_mfma_f32_16x16x32_bf16 v[26:29], v[196:199], v[16:19], v[26:29]
	ds_read_b128 v[196:199], v78 offset:62016
	v_cmp_gt_u32_e32 vcc, 16, v133
	s_waitcnt lgkmcnt(8)
	v_mfma_f32_16x16x32_bf16 v[26:29], v[208:211], v[12:15], v[26:29]
	ds_read_b128 v[208:211], v77 offset:12800
	s_waitcnt lgkmcnt(8)
	v_mfma_f32_16x16x32_bf16 v[26:29], v[212:215], v[8:11], v[26:29]
	ds_read_b128 v[212:215], v77 offset:12928
	s_waitcnt lgkmcnt(8)
	v_mfma_f32_16x16x32_bf16 v[26:29], v[228:231], v[4:7], v[26:29]
	ds_read_b128 v[228:231], v77 offset:12992
	s_waitcnt lgkmcnt(8)
	v_mfma_f32_16x16x32_bf16 v[28:31], v[232:235], v[0:3], v[26:29]
	ds_read_b128 v[232:235], v77 offset:13056
	s_nop 7
	v_pk_mul_f32 v[26:27], v[30:31], v[24:25] op_sel_hi:[1,0]
	s_waitcnt lgkmcnt(8)
	v_mfma_f32_16x16x32_bf16 v[30:33], v[236:239], v[20:23], 0
	ds_read_b128 v[236:239], v77 offset:13120
	v_mul_f32_e64 v28, v28, v24
	v_mul_f32_e64 v29, v29, v24
	v_mfma_f32_16x16x32_bf16 v[30:33], v[200:203], v[16:19], v[30:33]
	ds_read_b128 v[200:203], v77 offset:19200
	s_waitcnt lgkmcnt(9)
	v_mfma_f32_16x16x32_bf16 v[30:33], v[240:243], v[12:15], v[30:33]
	ds_read_b128 v[240:243], v77 offset:19264
	s_waitcnt lgkmcnt(9)
	v_mfma_f32_16x16x32_bf16 v[30:33], v[244:247], v[8:11], v[30:33]
	ds_read_b128 v[244:247], v77 offset:19328
	s_waitcnt lgkmcnt(9)
	v_mfma_f32_16x16x32_bf16 v[30:33], v[92:95], v[4:7], v[30:33]
	ds_read_b128 v[92:95], v77 offset:19392
	s_waitcnt lgkmcnt(9)
	v_mfma_f32_16x16x32_bf16 v[32:35], v[196:199], v[0:3], v[30:33]
	s_nop 7
	v_pk_mul_f32 v[30:31], v[34:35], v[24:25] op_sel_hi:[1,0]
	ds_read_b128 v[196:199], v77 offset:19456
	s_waitcnt lgkmcnt(9)
	v_mfma_f32_16x16x32_bf16 v[34:37], v[208:211], v[20:23], 0
	v_mul_f32_e64 v32, v32, v24
	v_mul_f32_e64 v33, v33, v24
	v_mfma_f32_16x16x32_bf16 v[34:37], v[204:207], v[16:19], v[34:37]
	ds_read_b128 v[208:211], v77 offset:19520
	s_waitcnt lgkmcnt(9)
	v_mfma_f32_16x16x32_bf16 v[34:37], v[212:215], v[12:15], v[34:37]
	s_waitcnt lgkmcnt(8)
	v_mfma_f32_16x16x32_bf16 v[34:37], v[228:231], v[8:11], v[34:37]
	s_waitcnt lgkmcnt(7)
	v_mfma_f32_16x16x32_bf16 v[34:37], v[232:235], v[4:7], v[34:37]
	s_waitcnt lgkmcnt(6)
	v_mfma_f32_16x16x32_bf16 v[34:37], v[236:239], v[0:3], v[34:37]
	s_nop 7
	v_pk_mul_f32 v[38:39], v[24:25], v[36:37] op_sel_hi:[0,1]
	v_pk_mul_f32 v[40:41], v[24:25], v[34:35] op_sel_hi:[0,1]
	s_waitcnt lgkmcnt(5)
	v_mfma_f32_16x16x32_bf16 v[20:23], v[200:203], v[20:23], 0
	s_waitcnt lgkmcnt(4)
	v_mfma_f32_16x16x32_bf16 v[16:19], v[240:243], v[16:19], v[20:23]
	s_waitcnt lgkmcnt(3)
	v_mfma_f32_16x16x32_bf16 v[12:15], v[244:247], v[12:15], v[16:19]
	s_waitcnt lgkmcnt(2)
	v_mfma_f32_16x16x32_bf16 v[8:11], v[92:95], v[8:11], v[12:15]
	s_waitcnt lgkmcnt(1)
	v_mfma_f32_16x16x32_bf16 v[4:7], v[196:199], v[4:7], v[8:11]
	s_waitcnt lgkmcnt(0)
	v_mfma_f32_16x16x32_bf16 v[0:3], v[208:211], v[0:3], v[4:7]
	s_nop 2
	v_mul_f32_e32 v4, v31, v31
	v_fmac_f32_e32 v4, v30, v30
	v_mul_f32_e32 v5, v41, v41
	s_nop 1
	v_pk_mul_f32 v[6:7], v[24:25], v[0:1] op_sel_hi:[0,1]
	v_mul_f32_e32 v0, v29, v29
	v_mul_f32_e32 v1, v27, v27
	v_pk_mul_f32 v[8:9], v[24:25], v[2:3] op_sel_hi:[0,1]
	v_fmac_f32_e32 v0, v28, v28
	v_fmac_f32_e32 v1, v26, v26
	v_mul_f32_e32 v3, v33, v33
	v_add_f32_e32 v0, v0, v1
	v_fmac_f32_e32 v3, v32, v32
	v_mul_f32_e32 v10, v39, v39
	v_add_f32_e32 v2, v80, v0
	v_add_f32_e32 v3, v3, v4
	v_fmac_f32_e32 v5, v40, v40
	v_fmac_f32_e32 v10, v38, v38
	v_mul_f32_e32 v11, v7, v7
	v_mul_f32_e32 v12, v9, v9
	v_add_f32_e32 v4, v3, v2
	v_add_f32_e32 v5, v5, v10
	v_fmac_f32_e32 v11, v6, v6
	v_fmac_f32_e32 v12, v8, v8
	v_add_f32_e32 v10, v5, v4
	v_add_f32_e32 v11, v11, v12
	v_add_f32_e32 v10, v10, v11
	v_cvt_pk_bf16_f32 v1, v28, v29
	v_cvt_pk_bf16_f32 v0, v26, v27
	v_cvt_pk_bf16_f32 v3, v32, v33
	v_cvt_pk_bf16_f32 v2, v30, v31
	v_cvt_pk_bf16_f32 v5, v40, v41
	v_cvt_pk_bf16_f32 v4, v38, v39
	v_cvt_pk_bf16_f32 v7, v6, v7
	v_cvt_pk_bf16_f32 v6, v8, v9
	ds_bpermute_b32 v8, v135, v10
	s_waitcnt lgkmcnt(0)
	v_add_f32_e32 v8, v10, v8
	ds_bpermute_b32 v9, v76, v8
	s_and_saveexec_b64 s[0:1], vcc
	s_cbranch_execz .LBB0_274
	v_readlane_b32 s2, v251, 30
	s_waitcnt lgkmcnt(0)
	v_add_f32_e32 v8, v8, v9
	v_lshl_add_u32 v10, v133, 2, s2
	ds_write_b32 v10, v8

; __device__ __forceinline__ unsigned pk2(float lo, float hi) { return pg8::cvt_pk_bf16(lo, hi); }
; template <bool DO_SWA, bool DO_MEM>
; __device__ __forceinline__ void attn_unit(const Args& a, unsigned char* ws, LAS unsigned char* lds, int l, int tid_in, int lane_in, int wave, int unit) {
;     ...
;             const bf16* ub = UB + (size_t)(row0 + t0) * UBW;
; #pragma unroll
;             for (int r = 0; r < 6; ++r) {
;                 if (r >= 2 || tg > 0 || !first) cu[r] = __builtin_nontemporal_load((const v4u*)(ub + (ptrdiff_t)(r - 2) * UBW + 896 + ch));
;                 else if (is_s) { const float* sp = a.in[5] + (size_t)(l * NBS + sb) * 512 + r * 256 + ch; const f32x4 s0 = *(const f32x4*)sp, s1 = *(const f32x4*)(sp + 4);
;                                  cu[r] = (v4u){pk2(s0[0], s0[1]), pk2(s0[2], s0[3]), pk2(s1[0], s1[1]), pk2(s1[2], s1[3])}; }
;                 else cu[r] = zero4;
;             }
; #pragma unroll
;             for (int i = 0; i < 4; ++i) ccb[i] = __builtin_nontemporal_load((const v4u*)(ub + (size_t)i * UBW + 640 + ch));
;         }
;         __builtin_amdgcn_sched_barrier(0);
;         if constexpr (DO_SWA) {
;             float w0[8], w1[8], w2[8];
; #pragma unroll
;             for (int j = 0; j < 4; ++j) { w0[j] = cwv[0][j]; w0[4 + j] = cwv[1][j]; w1[j] = cwv[2][j]; w1[4 + j] = cwv[3][j]; w2[j] = cwv[4][j]; w2[4 + j] = cwv[5][j]; }
; #pragma unroll
;             for (int i = 0; i < 4; ++i) {
;                 float ua[8], ub_[8], uc[8], cbv[8], cy[8];
;                 unpack8(cu[i], ua); unpack8(cu[i + 1], ub_); unpack8(cu[i + 2], uc); unpack8(ccb[i], cbv);
;                 float ss = 0.f;
; #pragma unroll
;                 for (int j = 0; j < 8; ++j) { const float y = ua[j] * w0[j] + ub_[j] * w1[j] + uc[j] * w2[j]; cy[j] = cbv[j] * y; ss += cy[j] * cy[j]; }
.LBB0_290:
	s_or_b64 exec, exec, s[4:5]
	v_lshl_add_u64 v[124:125], v[124:125], 0, v[184:185]
	s_movk_i32 s0, 0x1000
	v_add_co_u32_e32 v128, vcc, s0, v124
	s_movk_i32 s0, 0x2000
	s_nop 0
	v_addc_co_u32_e32 v129, vcc, 0, v125, vcc
	v_add_co_u32_e32 v132, vcc, s0, v124
	v_ashrrev_i32_e32 v153, 31, v152
	s_nop 0
	v_addc_co_u32_e32 v133, vcc, 0, v125, vcc
	global_load_dwordx4 v[202:205], v[124:125], off offset:1792 nt
	global_load_dwordx4 v[162:165], v[124:125], off offset:1280 nt
	global_load_dwordx4 v[140:143], v[128:129], off offset:512 nt
	global_load_dwordx4 v[206:209], v[128:129], off nt
	s_nop 0
	global_load_dwordx4 v[124:127], v[128:129], off offset:3328 nt
	global_load_dwordx4 v[136:139], v[128:129], off offset:2816 nt
	s_nop 0
	global_load_dwordx4 v[128:131], v[132:133], off offset:2048 nt
	s_nop 0
	global_load_dwordx4 v[132:135], v[132:133], off offset:1536 nt
	v_ashrrev_i32_e32 v149, 31, v148
	v_ashrrev_i32_e32 v161, 31, v160
	s_waitcnt vmcnt(0)
	v_lshlrev_b32_e32 v199, 16, v202
	v_lshlrev_b32_e32 v198, 16, v144
	v_mov_b32_e32 v200, v112
	v_mov_b32_e32 v201, v120
	v_pk_mul_f32 v[194:195], v[200:201], v[198:199]
	v_lshlrev_b32_e32 v198, 16, v208
	v_and_b32_e32 v220, 0xffff0000, v208
	v_lshlrev_b32_e32 v208, 16, v108
	v_and_b32_e32 v151, 64, v222
	v_fma_f32 v194, v116, v208, v194
	v_xor_b32_e32 v159, 1, v222
	v_add_u32_e32 v151, 64, v151
	v_lshlrev_b32_e32 v226, 16, v162
	v_lshlrev_b32_e32 v190, 16, v209
	v_and_b32_e32 v191, 0xffff0000, v209
	v_lshlrev_b32_e32 v209, 16, v140
	v_add_f32_e32 v194, v194, v195
	v_cmp_lt_i32_e32 vcc, v159, v151
	v_and_b32_e32 v246, 0xffff0000, v162
	v_lshlrev_b32_e32 v247, 16, v163
	v_and_b32_e32 v248, 0xffff0000, v163
	v_lshlrev_b32_e32 v249, 16, v164
	v_and_b32_e32 v223, 0xffff0000, v164
	v_lshlrev_b32_e32 v250, 16, v165
	v_and_b32_e32 v217, 0xffff0000, v165
	v_and_b32_e32 v183, 0xffff0000, v202
	v_and_b32_e32 v182, 0xffff0000, v144
	v_mov_b32_e32 v196, v113
	v_mov_b32_e32 v197, v121
	v_lshlrev_b32_e32 v163, 16, v205
	v_lshlrev_b32_e32 v162, 16, v147
	v_mov_b32_e32 v164, v98
	v_mov_b32_e32 v165, v106
	v_mul_f32_e32 v226, v194, v226
	v_pk_mul_f32 v[194:195], v[200:201], v[208:209]
	v_cndmask_b32_e32 v159, v222, v159, vcc
	v_pk_mul_f32 v[224:225], v[196:197], v[182:183]
	v_lshlrev_b32_e32 v179, 16, v203
	v_lshlrev_b32_e32 v178, 16, v145
	v_mov_b32_e32 v180, v114
	v_mov_b32_e32 v181, v122
	v_lshlrev_b32_e32 v171, 16, v204
	v_lshlrev_b32_e32 v170, 16, v146
	v_mov_b32_e32 v172, v96
	v_mov_b32_e32 v173, v104
	v_pk_mul_f32 v[240:241], v[164:165], v[162:163]
	v_lshlrev_b64 v[244:245], 11, v[160:161]
	v_lshlrev_b32_e32 v161, 16, v206
	v_and_b32_e32 v162, 0xffff0000, v206
	v_fma_f32 v194, v116, v199, v194
	v_and_b32_e32 v206, 0xffff0000, v108
	v_lshlrev_b32_e32 v231, 2, v159
	v_xor_b32_e32 v159, 2, v222
	v_pk_mul_f32 v[232:233], v[180:181], v[178:179]
	v_pk_mul_f32 v[236:237], v[172:173], v[170:171]
	v_lshlrev_b32_e32 v170, 16, v207
	v_and_b32_e32 v178, 0xffff0000, v207
	v_add_f32_e32 v194, v194, v195
	v_and_b32_e32 v207, 0xffff0000, v140
	v_fma_f32 v108, v117, v206, v224
	v_cmp_lt_i32_e32 vcc, v159, v151
	v_mul_f32_e32 v161, v194, v161
	v_add_f32_e32 v108, v108, v225
	v_pk_mul_f32 v[194:195], v[196:197], v[206:207]
	v_cndmask_b32_e32 v159, v222, v159, vcc
	v_mul_f32_e32 v208, v108, v246
	v_fma_f32 v108, v117, v183, v194
	v_lshlrev_b32_e32 v230, 2, v159
	v_xor_b32_e32 v159, 4, v222
	v_and_b32_e32 v167, 0xffff0000, v204
	v_add_f32_e32 v108, v108, v195
	v_lshlrev_b32_e32 v204, 16, v109
	v_cmp_lt_i32_e32 vcc, v159, v151
	v_and_b32_e32 v174, 0xffff0000, v145
	v_and_b32_e32 v145, 0xffff0000, v205
	v_mul_f32_e32 v162, v108, v162
	v_lshlrev_b32_e32 v205, 16, v141
	v_fma_f32 v108, v118, v204, v232
	v_cndmask_b32_e32 v159, v222, v159, vcc
	v_add_f32_e32 v108, v108, v233
	v_pk_mul_f32 v[194:195], v[180:181], v[204:205]
	v_lshlrev_b32_e32 v229, 2, v159
	v_xor_b32_e32 v159, 8, v222
	v_and_b32_e32 v175, 0xffff0000, v203
	v_mov_b32_e32 v176, v115
	v_mov_b32_e32 v177, v123
	v_mul_f32_e32 v233, v108, v247
	v_fma_f32 v108, v118, v179, v194
	v_cmp_lt_i32_e32 vcc, v159, v151
	v_xor_b32_e32 v166, 16, v222
	v_pk_mul_f32 v[234:235], v[176:177], v[174:175]
	v_add_f32_e32 v108, v108, v195
	v_and_b32_e32 v202, 0xffff0000, v109
	v_cndmask_b32_e32 v159, v222, v159, vcc
	v_cmp_lt_i32_e32 vcc, v166, v151
	v_mul_f32_e32 v170, v108, v170
	v_fma_f32 v108, v119, v202, v234
	v_cndmask_b32_e32 v166, v222, v166, vcc
	v_add_f32_e32 v108, v108, v235
	v_lshlrev_b32_e32 v140, 16, v110
	v_lshlrev_b32_e32 v212, 2, v166
	v_and_b32_e32 v166, 0xffff0000, v146
	v_mov_b32_e32 v168, v97
	v_mov_b32_e32 v169, v105
	v_mul_f32_e32 v204, v108, v248
	v_fma_f32 v108, v100, v140, v236
	v_pk_mul_f32 v[238:239], v[168:169], v[166:167]
	v_and_b32_e32 v203, 0xffff0000, v141
	v_add_f32_e32 v108, v108, v237
	v_and_b32_e32 v110, 0xffff0000, v110
	v_pk_mul_f32 v[224:225], v[176:177], v[202:203]
	v_mul_f32_e32 v202, v108, v249
	v_fma_f32 v108, v101, v110, v238
	v_mul_f32_e32 v246, v208, v208
	v_add_f32_e32 v108, v108, v239
	v_lshlrev_b32_e32 v194, 16, v111
	v_fmac_f32_e32 v246, v226, v226
	v_mul_f32_e32 v223, v108, v223
	v_fma_f32 v108, v102, v194, v240
	v_and_b32_e32 v144, 0xffff0000, v147
	v_mov_b32_e32 v146, v99
	v_mov_b32_e32 v147, v107
	v_fmac_f32_e32 v246, v233, v233
	v_add_f32_e32 v108, v108, v241
	v_pk_mul_f32 v[242:243], v[146:147], v[144:145]
	v_fmac_f32_e32 v246, v204, v204
	v_mul_f32_e32 v235, v108, v250
	v_and_b32_e32 v108, 0xffff0000, v111
	v_fmac_f32_e32 v246, v202, v202
	v_fma_f32 v109, v103, v108, v242
	v_fmac_f32_e32 v246, v223, v223
	v_add_f32_e32 v109, v109, v243
	v_fmac_f32_e32 v246, v235, v235
	v_mul_f32_e32 v217, v109, v217
	v_fmac_f32_e32 v246, v217, v217
	ds_bpermute_b32 v109, v231, v246
	v_fma_f32 v111, v119, v175, v224
	v_add_f32_e32 v111, v111, v225
	v_mul_f32_e32 v178, v111, v178
	v_lshlrev_b32_e32 v141, 16, v142
	s_waitcnt lgkmcnt(0)
; __device__ __forceinline__ unsigned pk2(float lo, float hi) { return pg8::cvt_pk_bf16(lo, hi); }
; template <bool DO_SWA, bool DO_MEM>
; __device__ __forceinline__ void attn_unit(const Args& a, unsigned char* ws, LAS unsigned char* lds, int l, int tid_in, int lane_in, int wave, int unit) {
;     ...
; #pragma unroll
;             for (int i = 0; i < 4; ++i) {
;                 float ua[8], ub_[8], uc[8], cbv[8], cy[8];
;                 unpack8(cu[i], ua); unpack8(cu[i + 1], ub_); unpack8(cu[i + 2], uc); unpack8(ccb[i], cbv);
;                 float ss = 0.f;
; #pragma unroll
;                 for (int j = 0; j < 8; ++j) { const float y = ua[j] * w0[j] + ub_[j] * w1[j] + uc[j] * w2[j]; cy[j] = cbv[j] * y; ss += cy[j] * cy[j]; }
;                 ss += __shfl_xor(ss, 1); ss += __shfl_xor(ss, 2); ss += __shfl_xor(ss, 4); ss += __shfl_xor(ss, 8); ss += __shfl_xor(ss, 16);
;                 const float rs = 1.0f / sqrtf(ss * (1.0f / 256.0f) + EPS);
;                 v4u o; o.x = pk2(cy[0] * rs, cy[1] * rs); o.y = pk2(cy[2] * rs, cy[3] * rs); o.z = pk2(cy[4] * rs, cy[5] * rs); o.w = pk2(cy[6] * rs, cy[7] * rs);
;                 *(v4u*)(MIX + (size_t)(row0 + t0 + i) * D + 512 + ch) = o;
	v_add_f32_e32 v109, v246, v109
	ds_bpermute_b32 v111, v230, v109
	v_pk_mul_f32 v[224:225], v[172:173], v[140:141]
	v_lshlrev_b32_e32 v159, 2, v159
	v_fma_f32 v140, v100, v171, v224
	v_add_f32_e32 v140, v140, v225
	s_waitcnt lgkmcnt(0)
	v_add_f32_e32 v109, v109, v111
	ds_bpermute_b32 v195, v229, v109
	v_and_b32_e32 v111, 0xffff0000, v142
	v_pk_mul_f32 v[224:225], v[168:169], v[110:111]
	s_mov_b32 s4, 0xf800000
	v_fma_f32 v142, v101, v167, v224
	s_waitcnt lgkmcnt(0)
	v_add_f32_e32 v109, v109, v195
	ds_bpermute_b32 v110, v159, v109
	v_lshlrev_b32_e32 v195, 16, v143
	v_add_f32_e32 v142, v142, v225
	v_pk_mul_f32 v[224:225], v[164:165], v[194:195]
	v_mul_f32_e32 v140, v140, v198
	s_waitcnt lgkmcnt(0)
	v_add_f32_e32 v109, v109, v110
	ds_bpermute_b32 v110, v212, v109
	v_mul_f32_e32 v198, v142, v220
	v_fma_f32 v142, v102, v163, v224
	v_add_f32_e32 v142, v142, v225
	v_mul_f32_e32 v190, v142, v190
	s_waitcnt lgkmcnt(0)
	v_add_f32_e32 v109, v109, v110
	v_fmamk_f32 v109, v109, 0x3b800000, v218
	v_mul_f32_e32 v110, 0x4f800000, v109
	v_cmp_gt_f32_e32 vcc, s4, v109
	v_mul_f32_e32 v206, v162, v162
	v_fmac_f32_e32 v206, v161, v161
	v_cndmask_b32_e32 v110, v109, v110, vcc
	v_sqrt_f32_e32 v194, v110
	v_and_b32_e32 v109, 0xffff0000, v143
	v_fmac_f32_e32 v206, v170, v170
	v_fmac_f32_e32 v206, v178, v178
	v_add_u32_e32 v142, -1, v194
	v_fma_f32 v143, -v142, v194, v110
	v_cmp_ge_f32_e64 s[0:1], 0, v143
	v_add_u32_e32 v143, 1, v194
	v_fmac_f32_e32 v206, v140, v140
	v_cndmask_b32_e64 v142, v194, v142, s[0:1]
	v_fma_f32 v194, -v143, v194, v110
	v_cmp_lt_f32_e64 s[0:1], 0, v194
	v_fmac_f32_e32 v206, v198, v198
	v_fmac_f32_e32 v206, v190, v190
	v_cndmask_b32_e64 v142, v142, v143, s[0:1]
	v_mul_f32_e32 v143, 0x37800000, v142
	v_cndmask_b32_e32 v142, v142, v143, vcc
	v_cmp_class_f32_e32 vcc, v110, v219
	s_movk_i32 s5, 0x190
	s_nop 0
	v_cndmask_b32_e32 v110, v142, v110, vcc
	v_pk_mul_f32 v[142:143], v[146:147], v[108:109]
	v_div_scale_f32 v194, s[0:1], v110, v110, 1.0
	v_fma_f32 v108, v103, v145, v142
	v_add_f32_e32 v108, v108, v143
	v_mul_f32_e32 v108, v108, v191
	v_fmac_f32_e32 v206, v108, v108
	ds_bpermute_b32 v191, v231, v206
	v_rcp_f32_e32 v220, v194
	v_lshl_add_u64 v[142:143], s[20:21], 0, v[244:245]
	v_lshl_add_u64 v[142:143], v[142:143], 0, v[184:185]
	s_waitcnt lgkmcnt(0)
	v_add_f32_e32 v191, v206, v191
	ds_bpermute_b32 v206, v230, v191
	v_fma_f32 v224, -v194, v220, 1.0
	v_fmac_f32_e32 v220, v224, v220
	v_div_scale_f32 v224, vcc, 1.0, v110, 1.0
	s_waitcnt lgkmcnt(0)
	v_add_f32_e32 v191, v191, v206
	ds_bpermute_b32 v206, v229, v191
	v_mul_f32_e32 v225, v224, v220
	v_fma_f32 v232, -v194, v225, v224
	v_fmac_f32_e32 v225, v232, v220
	v_fma_f32 v194, -v194, v225, v224
	s_waitcnt lgkmcnt(0)
	v_add_f32_e32 v191, v191, v206
	ds_bpermute_b32 v206, v159, v191
	v_div_fmas_f32 v194, v194, v220, v225
	v_div_fixup_f32 v110, v194, v110, 1.0
	v_mul_f32_e32 v194, v226, v110
	v_mul_f32_e32 v208, v208, v110
	s_waitcnt lgkmcnt(0)
	v_add_f32_e32 v191, v191, v206
	v_cvt_pk_bf16_f32 v232, v194, v208
	ds_bpermute_b32 v194, v212, v191
	v_mul_f32_e32 v204, v204, v110
	v_mul_f32_e32 v206, v233, v110
	v_cvt_pk_bf16_f32 v233, v206, v204
	v_mul_f32_e32 v204, v223, v110
	s_waitcnt lgkmcnt(0)
	v_add_f32_e32 v191, v191, v194
	v_fmamk_f32 v191, v191, 0x3b800000, v218
	v_mul_f32_e32 v194, 0x4f800000, v191
	v_cmp_gt_f32_e32 vcc, s4, v191
	v_mul_f32_e32 v202, v202, v110
	v_cvt_pk_bf16_f32 v234, v202, v204
	v_mul_f32_e32 v202, v235, v110
	v_cndmask_b32_e32 v191, v191, v194, vcc
	v_sqrt_f32_e32 v194, v191
	v_mul_f32_e32 v110, v217, v110
	v_cvt_pk_bf16_f32 v235, v202, v110
	global_store_dwordx4 v[142:143], v[232:235], off offset:1024
	v_add_u32_e32 v204, -1, v194
	v_fma_f32 v206, -v204, v194, v191
	v_cmp_ge_f32_e64 s[0:1], 0, v206
	v_add_u32_e32 v206, 1, v194
	v_and_b32_e32 v202, 0xffff0000, v135
	v_cndmask_b32_e64 v204, v194, v204, s[0:1]
	v_fma_f32 v194, -v206, v194, v191
	v_cmp_lt_f32_e64 s[0:1], 0, v194
	s_nop 1
	v_cndmask_b32_e64 v194, v204, v206, s[0:1]
	v_mul_f32_e32 v204, 0x37800000, v194
	v_cndmask_b32_e32 v194, v194, v204, vcc
	v_cmp_class_f32_e32 vcc, v191, v219
	s_nop 1
	v_cndmask_b32_e32 v191, v194, v191, vcc
	v_div_scale_f32 v194, s[0:1], v191, v191, 1.0
	v_rcp_f32_e32 v204, v194
	s_nop 0
	v_fma_f32 v110, -v194, v204, 1.0
	v_fmac_f32_e32 v204, v110, v204
	v_div_scale_f32 v110, vcc, 1.0, v191, 1.0
	v_mul_f32_e32 v142, v110, v204
	v_fma_f32 v143, -v194, v142, v110
	v_fmac_f32_e32 v142, v143, v204
	v_fma_f32 v110, -v194, v142, v110
	v_div_fmas_f32 v110, v110, v204, v142
	v_div_fixup_f32 v110, v110, v191, 1.0
	v_mul_f32_e32 v142, v161, v110
	v_mul_f32_e32 v143, v162, v110
	v_cvt_pk_bf16_f32 v232, v142, v143
	v_mul_f32_e32 v142, v170, v110
	v_mul_f32_e32 v140, v140, v110
	v_mul_f32_e32 v143, v178, v110
	v_cvt_pk_bf16_f32 v233, v142, v143
	v_mul_f32_e32 v142, v198, v110
	v_cvt_pk_bf16_f32 v234, v140, v142
	v_mul_f32_e32 v140, v190, v110
	v_lshlrev_b32_e32 v162, 16, v132
	v_and_b32_e32 v170, 0xffff0000, v132
	v_lshlrev_b32_e32 v178, 16, v133
	v_and_b32_e32 v190, 0xffff0000, v133
	v_lshlrev_b32_e32 v198, 16, v135
	v_lshlrev_b32_e32 v132, 16, v124
	v_lshlrev_b32_e32 v133, 16, v128
	v_lshlrev_b32_e32 v191, 16, v134
	v_and_b32_e32 v194, 0xffff0000, v134
	v_pk_mov_b32 v[134:135], v[198:199], v[132:133] op_sel:[1,0]
	v_mul_f32_e32 v108, v108, v110
	v_pk_mul_f32 v[134:135], v[200:201], v[134:135]
	v_cvt_pk_bf16_f32 v235, v140, v108
	v_lshlrev_b32_e32 v108, 16, v136
	v_fma_f32 v134, v116, v209, v134
	v_add_f32_e32 v134, v134, v135
	v_mul_f32_e32 v108, v134, v108
	v_mov_b32_e32 v134, v116
	v_mov_b32_e32 v135, v120
	v_pk_mul_f32 v[132:133], v[134:135], v[132:133]
	v_mov_b32_e32 v120, v117
; __device__ __forceinline__ unsigned pk2(float lo, float hi) { return pg8::cvt_pk_bf16(lo, hi); }
; template <bool DO_SWA, bool DO_MEM>
; __device__ __forceinline__ void attn_unit(const Args& a, unsigned char* ws, LAS unsigned char* lds, int l, int tid_in, int lane_in, int wave, int unit) {
;     ...
; #pragma unroll
;             for (int i = 0; i < 4; ++i) {
;                 float ua[8], ub_[8], uc[8], cbv[8], cy[8];
;                 unpack8(cu[i], ua); unpack8(cu[i + 1], ub_); unpack8(cu[i + 2], uc); unpack8(ccb[i], cbv);
;                 float ss = 0.f;
; #pragma unroll
;                 for (int j = 0; j < 8; ++j) { const float y = ua[j] * w0[j] + ub_[j] * w1[j] + uc[j] * w2[j]; cy[j] = cbv[j] * y; ss += cy[j] * cy[j]; }
;                 ss += __shfl_xor(ss, 1); ss += __shfl_xor(ss, 2); ss += __shfl_xor(ss, 4); ss += __shfl_xor(ss, 8); ss += __shfl_xor(ss, 16);
;                 const float rs = 1.0f / sqrtf(ss * (1.0f / 256.0f) + EPS);
;                 v4u o; o.x = pk2(cy[0] * rs, cy[1] * rs); o.y = pk2(cy[2] * rs, cy[3] * rs); o.z = pk2(cy[4] * rs, cy[5] * rs); o.w = pk2(cy[6] * rs, cy[7] * rs);
;                 *(v4u*)(MIX + (size_t)(row0 + t0 + i) * D + 512 + ch) = o;
;             }
	v_fma_f32 v112, v112, v209, v132
	v_add_f32_e32 v112, v112, v133
	v_and_b32_e32 v133, 0xffff0000, v128
	v_and_b32_e32 v132, 0xffff0000, v124
	v_pk_mov_b32 v[134:135], v[182:183], v[132:133] op_sel:[1,0]
	v_mul_f32_e32 v162, v112, v162
	v_pk_mul_f32 v[134:135], v[196:197], v[134:135]
	v_and_b32_e32 v110, 0xffff0000, v136
	v_fma_f32 v112, v117, v207, v134
	v_add_f32_e32 v112, v112, v135
	v_pk_mul_f32 v[116:117], v[120:121], v[132:133]
	v_mul_f32_e32 v110, v112, v110
	v_fma_f32 v112, v113, v207, v116
	v_add_f32_e32 v112, v112, v117
	v_mul_f32_e32 v128, v112, v170
	v_lshlrev_b32_e32 v112, 16, v125
	v_lshlrev_b32_e32 v113, 16, v129
	v_pk_mov_b32 v[116:117], v[178:179], v[112:113] op_sel:[1,0]
	v_lshlrev_b32_e32 v140, 16, v137
	v_pk_mul_f32 v[116:117], v[180:181], v[116:117]
	v_or_b32_e32 v142, 1, v160
	v_fma_f32 v116, v118, v205, v116
	v_add_f32_e32 v116, v116, v117
	v_mul_f32_e32 v133, v116, v140
	v_mov_b32_e32 v116, v118
	v_mov_b32_e32 v117, v122
	v_pk_mul_f32 v[112:113], v[116:117], v[112:113]
	v_ashrrev_i32_e32 v143, 31, v142
	v_fma_f32 v112, v114, v205, v112
	v_add_f32_e32 v112, v112, v113
	v_mul_f32_e32 v134, v112, v178
	v_and_b32_e32 v113, 0xffff0000, v129
	v_and_b32_e32 v112, 0xffff0000, v125
	v_lshlrev_b64 v[142:143], 11, v[142:143]
	v_pk_mov_b32 v[116:117], v[174:175], v[112:113] op_sel:[1,0]
	v_lshl_add_u64 v[142:143], s[20:21], 0, v[142:143]
	v_pk_mul_f32 v[116:117], v[176:177], v[116:117]
	v_lshl_add_u64 v[142:143], v[142:143], 0, v[184:185]
	v_fma_f32 v114, v119, v203, v116
	v_mov_b32_e32 v122, v119
	global_store_dwordx4 v[142:143], v[232:235], off offset:1024
	v_and_b32_e32 v142, 0xffff0000, v137
	v_add_f32_e32 v114, v114, v117
	v_pk_mul_f32 v[112:113], v[122:123], v[112:113]
	v_mul_f32_e32 v125, v114, v142
	v_fma_f32 v112, v115, v203, v112
	v_lshlrev_b32_e32 v114, 16, v126
	v_lshlrev_b32_e32 v115, 16, v130
	v_pk_mov_b32 v[116:117], v[170:171], v[114:115] op_sel:[1,0]
	v_lshlrev_b32_e32 v143, 16, v138
	v_pk_mul_f32 v[116:117], v[172:173], v[116:117]
	v_and_b32_e32 v138, 0xffff0000, v138
	v_fma_f32 v116, v100, v141, v116
	v_add_f32_e32 v116, v116, v117
	v_mul_f32_e32 v129, v116, v143
	v_and_b32_e32 v117, 0xffff0000, v130
	v_and_b32_e32 v116, 0xffff0000, v126
	v_pk_mov_b32 v[118:119], v[166:167], v[116:117] op_sel:[1,0]
	v_lshlrev_b32_e32 v161, 16, v139
	v_pk_mul_f32 v[118:119], v[168:169], v[118:119]
	v_mul_f32_e32 v124, v110, v110
	v_fma_f32 v118, v101, v111, v118
	v_add_f32_e32 v118, v118, v119
	v_mul_f32_e32 v126, v118, v138
	v_lshlrev_b32_e32 v118, 16, v127
	v_lshlrev_b32_e32 v119, 16, v131
	v_pk_mov_b32 v[120:121], v[162:163], v[118:119] op_sel:[1,0]
	v_fmac_f32_e32 v124, v108, v108
	v_pk_mul_f32 v[120:121], v[164:165], v[120:121]
	v_fmac_f32_e32 v124, v133, v133
	v_fma_f32 v120, v102, v195, v120
	v_add_f32_e32 v120, v120, v121
	v_mul_f32_e32 v130, v120, v161
	v_and_b32_e32 v121, 0xffff0000, v131
	v_and_b32_e32 v120, 0xffff0000, v127
	v_pk_mov_b32 v[122:123], v[144:145], v[120:121] op_sel:[1,0]
	v_fmac_f32_e32 v124, v125, v125
	v_pk_mul_f32 v[122:123], v[146:147], v[122:123]
	v_fmac_f32_e32 v124, v129, v129
	v_fma_f32 v122, v103, v109, v122
	v_and_b32_e32 v139, 0xffff0000, v139
	v_fmac_f32_e32 v124, v126, v126
	v_add_f32_e32 v122, v122, v123
	v_fmac_f32_e32 v124, v130, v130
	v_mul_f32_e32 v122, v122, v139
	v_fmac_f32_e32 v124, v122, v122
	ds_bpermute_b32 v123, v231, v124
	v_add_f32_e32 v112, v112, v113
	v_mul_f32_e32 v127, v112, v190
	v_mov_b32_e32 v112, v100
	v_mov_b32_e32 v113, v104
	s_waitcnt lgkmcnt(0)
	v_add_f32_e32 v100, v124, v123
	ds_bpermute_b32 v123, v230, v100
	v_pk_mul_f32 v[112:113], v[112:113], v[114:115]
	v_mov_b32_e32 v104, v101
	v_fma_f32 v96, v96, v141, v112
	v_add_f32_e32 v96, v96, v113
	s_waitcnt lgkmcnt(0)
	v_add_f32_e32 v112, v100, v123
	ds_bpermute_b32 v113, v229, v112
	v_mul_f32_e32 v114, v96, v191
	v_pk_mul_f32 v[100:101], v[104:105], v[116:117]
	v_mul_f32_e32 v132, v128, v128
	v_fma_f32 v97, v97, v111, v100
	s_waitcnt lgkmcnt(0)
	v_add_f32_e32 v96, v112, v113
	ds_bpermute_b32 v104, v159, v96
	v_add_f32_e32 v97, v97, v101
	v_mul_f32_e32 v105, v97, v194
	v_mov_b32_e32 v97, v106
	v_fmac_f32_e32 v132, v162, v162
	s_waitcnt lgkmcnt(0)
	v_add_f32_e32 v100, v96, v104
	ds_bpermute_b32 v101, v212, v100
	v_mov_b32_e32 v96, v102
	v_pk_mul_f32 v[96:97], v[96:97], v[118:119]
	v_fmac_f32_e32 v132, v134, v134
	v_fma_f32 v96, v98, v195, v96
	s_waitcnt lgkmcnt(0)
	v_add_f32_e32 v98, v100, v101
	v_fmamk_f32 v98, v98, 0x3b800000, v218
	v_mul_f32_e32 v100, 0x4f800000, v98
	v_cmp_gt_f32_e32 vcc, s4, v98
	v_add_f32_e32 v96, v96, v97
	v_mul_f32_e32 v102, v96, v198
	v_cndmask_b32_e32 v98, v98, v100, vcc
	v_sqrt_f32_e32 v100, v98
	v_mov_b32_e32 v106, v103
	v_fmac_f32_e32 v132, v127, v127
	v_fmac_f32_e32 v132, v114, v114
	v_add_u32_e32 v96, -1, v100
	v_fma_f32 v97, -v96, v100, v98
	v_cmp_ge_f32_e64 s[0:1], 0, v97
	v_add_u32_e32 v97, 1, v100
	v_fmac_f32_e32 v132, v105, v105
	v_cndmask_b32_e64 v96, v100, v96, s[0:1]
	v_fma_f32 v100, -v97, v100, v98
	v_cmp_lt_f32_e64 s[0:1], 0, v100
	v_fmac_f32_e32 v132, v102, v102
	v_or_b32_e32 v136, 2, v160
	v_cndmask_b32_e64 v96, v96, v97, s[0:1]
	v_mul_f32_e32 v97, 0x37800000, v96
	v_cndmask_b32_e32 v96, v96, v97, vcc
	v_cmp_class_f32_e32 vcc, v98, v219
	v_ashrrev_i32_e32 v137, 31, v136
	v_lshlrev_b64 v[136:137], 11, v[136:137]
	v_cndmask_b32_e32 v98, v96, v98, vcc
	v_pk_mul_f32 v[96:97], v[106:107], v[120:121]
	v_div_scale_f32 v104, s[0:1], v98, v98, 1.0
	v_fma_f32 v96, v99, v109, v96
	v_add_f32_e32 v96, v96, v97
	v_mul_f32_e32 v103, v96, v202
	v_fmac_f32_e32 v132, v103, v103
	v_rcp_f32_e32 v111, v104
	ds_bpermute_b32 v99, v231, v132
	v_lshl_add_u64 v[96:97], s[20:21], 0, v[136:137]
	v_lshl_add_u64 v[100:101], v[96:97], 0, v[184:185]
	v_fma_f32 v96, -v104, v111, 1.0
	v_fmac_f32_e32 v111, v96, v111
	s_waitcnt lgkmcnt(0)
; #define LAS __attribute__((address_space(3)))
; #define LAS __attribute__((address_space(3)))
; template <int NKT, int VSTR, bool SINK>
; __device__ __forceinline__ void attn_core(LAS const unsigned char* kb_, LAS const unsigned char* vb_, bf16x8 q0, bf16x8 q1, float sk, unsigned mskbits, int fr, f32x4 (&o)[4]) {
;     ...
;     const int krow = ((fr >> 2) << 3) + (fr & 3);
; #pragma unroll
;     for (int kt = 0; kt < NKT; ++kt) {
;         const int key = (kt >> 1) * 32 + ((kt & 1) << 2) + krow;
;         LAS const unsigned char* kp = kb_ + key * 144;
;         const bf16x8 a0 = *(LAS const bf16x8*)kp, a1 = *(LAS const bf16x8*)(kp + 64);
;         const float bias = ((mskbits >> (kt >> 2)) & 1u) ? -1e30f : 0.f;
;         f32x4 s = mfma16(a0, q0, (f32x4){bias, bias, bias, bias});
;         s = mfma16(a1, q1, s);
;         S[kt] = s;
; template <bool DO_SWA, bool DO_MEM>
; __device__ __forceinline__ void attn_unit(const Args& a, unsigned char* ws, LAS unsigned char* lds, int l, int tid_in, int lane_in, int wave, int unit) {
;     ...
;                 *(v4u*)(MIX + (size_t)(row0 + t0 + i) * D + 512 + ch) = o;
;             }
;         }
;         if constexpr (DO_SWA)
; #pragma unroll
;         for (int i = 0; i < 6; ++i) {
;             const int s = i >> 1, rem = tid + 512 * (i & 1);
;             { const int key = rem >> 4, c16 = rem & 15; *(LAS v4u*)(lds + A_KS + ((c16 >> 3) * 192 + s * 64 + key) * 144 + (c16 & 7) * 16) = kst[i]; }
;             { const int col = rem >> 3, kc = rem & 7; *(LAS v4u*)(lds + A_VT1 + col * 400 + (s * 64 + kc * 8) * 2) = vst[i]; }
;         }
;         const bf16* MKb = (const bf16*)(ws + WS_MK) + (size_t)(l * 40 + bb) * 65536;
;         const bf16* MVTb = (const bf16*)(ws + WS_MVT) + (size_t)(l * 40 + bb) * 65536;
;         v4u mkst[8], mvst[8];
;         __builtin_amdgcn_sched_barrier(0);
;         __syncthreads();
;         v2u osv[4][4];
;         if constexpr (DO_SWA) {
;             float ssq = 0.f;
; #pragma unroll
;             for (int hh = 0; hh < 4; ++hh) {
;                 const int h = g * 4 + hh;
;                 const float sk = a.in[12][l * 8 + h] * LOG2E;
;                 f32x4 o[4];
;                 attn_core<12, 400, true>(lds + A_KS + g * 192 * 144 + fq * 16, lds + A_VT1 + (g * 64 + fr) * 400 + fq * 16, qsw[hh][0], qsw[hh][1], sk, mskbits, fr, o);
	v_add_f32_e32 v96, v132, v99
	ds_bpermute_b32 v97, v230, v96
	v_div_scale_f32 v99, vcc, 1.0, v98, 1.0
	v_mul_f32_e32 v106, v99, v111
	v_fma_f32 v107, -v104, v106, v99
	s_waitcnt lgkmcnt(0)
	v_add_f32_e32 v96, v96, v97
	ds_bpermute_b32 v97, v229, v96
	v_fmac_f32_e32 v106, v107, v111
	v_fma_f32 v99, -v104, v106, v99
	v_div_fmas_f32 v99, v99, v111, v106
	v_div_fixup_f32 v99, v99, v98, 1.0
	s_waitcnt lgkmcnt(0)
	v_add_f32_e32 v97, v96, v97
	ds_bpermute_b32 v104, v159, v97
	v_mul_f32_e32 v96, v108, v99
	v_mul_f32_e32 v98, v110, v99
	v_cvt_pk_bf16_f32 v96, v96, v98
	v_mul_f32_e32 v106, v125, v99
	s_waitcnt lgkmcnt(0)
	v_add_f32_e32 v98, v97, v104
	ds_bpermute_b32 v104, v212, v98
	v_mul_f32_e32 v97, v133, v99
	v_cvt_pk_bf16_f32 v97, v97, v106
	v_mul_f32_e32 v106, v129, v99
	s_waitcnt lgkmcnt(0)
	v_add_f32_e32 v98, v98, v104
	v_fmamk_f32 v98, v98, 0x3b800000, v218
	v_mul_f32_e32 v104, 0x4f800000, v98
	v_cmp_gt_f32_e32 vcc, s4, v98
	s_movk_i32 s4, 0x90
	s_nop 0
	v_cndmask_b32_e32 v104, v98, v104, vcc
	v_sqrt_f32_e32 v107, v104
	v_mul_f32_e32 v98, v126, v99
	v_cvt_pk_bf16_f32 v98, v106, v98
	v_mul_f32_e32 v106, v130, v99
	v_add_u32_e32 v108, -1, v107
	v_fma_f32 v109, -v108, v107, v104
	v_cmp_ge_f32_e64 s[0:1], 0, v109
	v_add_u32_e32 v109, 1, v107
	v_mul_f32_e32 v99, v122, v99
	v_cndmask_b32_e64 v108, v107, v108, s[0:1]
	v_fma_f32 v107, -v109, v107, v104
	v_cmp_lt_f32_e64 s[0:1], 0, v107
	v_cvt_pk_bf16_f32 v99, v106, v99
	global_store_dwordx4 v[100:101], v[96:99], off offset:1024
	s_nop 0
	v_cndmask_b32_e64 v107, v108, v109, s[0:1]
	v_mul_f32_e32 v108, 0x37800000, v107
	v_cndmask_b32_e32 v107, v107, v108, vcc
	v_cmp_class_f32_e32 vcc, v104, v219
	s_nop 1
	v_cndmask_b32_e32 v104, v107, v104, vcc
	v_div_scale_f32 v107, s[0:1], v104, v104, 1.0
	v_rcp_f32_e32 v108, v107
	s_nop 0
	v_fma_f32 v96, -v107, v108, 1.0
	v_fmac_f32_e32 v108, v96, v108
	v_div_scale_f32 v96, vcc, 1.0, v104, 1.0
	v_mul_f32_e32 v97, v96, v108
	v_fma_f32 v98, -v107, v97, v96
	v_fmac_f32_e32 v97, v98, v108
	v_fma_f32 v96, -v107, v97, v96
	v_div_fmas_f32 v96, v96, v108, v97
	v_div_fixup_f32 v99, v96, v104, 1.0
	v_mul_f32_e32 v96, v162, v99
	v_mul_f32_e32 v97, v128, v99
	v_cvt_pk_bf16_f32 v96, v96, v97
	v_mul_f32_e32 v97, v134, v99
	v_mul_f32_e32 v98, v127, v99
	v_cvt_pk_bf16_f32 v97, v97, v98
	v_mul_f32_e32 v98, v114, v99
	v_mul_f32_e32 v100, v105, v99
	v_cvt_pk_bf16_f32 v98, v98, v100
	v_mul_f32_e32 v100, v102, v99
	v_mul_f32_e32 v99, v103, v99
	v_cvt_pk_bf16_f32 v99, v100, v99
	v_or_b32_e32 v100, 3, v160
	v_ashrrev_i32_e32 v101, 31, v100
	v_lshlrev_b64 v[100:101], 11, v[100:101]
	v_lshl_add_u64 v[100:101], s[20:21], 0, v[100:101]
	v_lshl_add_u64 v[100:101], v[100:101], 0, v[184:185]
	global_store_dwordx4 v[100:101], v[96:99], off offset:1024
	v_lshlrev_b32_e32 v104, 4, v213
	s_nop 0
	v_bfe_i32 v96, v213, 3, 1
	v_and_b32_e32 v98, 0xc0, v96
	v_and_b32_e32 v96, 0x70, v104
	v_add_u32_e32 v100, 0, v96
	v_add_u32_e32 v96, v98, v148
	v_mad_u64_u32 v[96:97], s[0:1], v96, s4, v[100:101]
	ds_write_b128 v96, v[28:31]
	v_mul_lo_u32 v28, v157, s5
	v_add3_u32 v28, 0, v28, v158
	ds_write_b128 v28, v[24:27] offset:55296
	v_add_u32_e32 v24, v98, v152
	v_mad_u64_u32 v[24:25], s[0:1], v24, s4, v[100:101]
	ds_write_b128 v24, v[60:63]
	v_mul_lo_u32 v24, v227, s5
	v_add_u32_e32 v27, 64, v98
	v_add3_u32 v26, 0, v24, v158
	v_add_u32_e32 v24, v27, v148
	v_mad_u64_u32 v[24:25], s[0:1], v24, s4, v[100:101]
	ds_write_b128 v26, v[56:59] offset:55296
	ds_write_b128 v24, v[68:71]
	ds_write_b128 v28, v[64:67] offset:55424
	v_add_u32_e32 v24, v27, v152
	v_mad_u64_u32 v[24:25], s[0:1], v24, s4, v[100:101]
	v_add_u32_e32 v27, 0x80, v98
	ds_write_b128 v24, v[72:75]
	ds_write_b128 v26, v[76:79] offset:55424
	v_add_u32_e32 v24, v27, v148
	v_mad_u64_u32 v[24:25], s[0:1], v24, s4, v[100:101]
	ds_write_b128 v24, v[80:83]
	ds_write_b128 v28, v[84:87] offset:55552
	v_add_u32_e32 v24, v27, v152
	v_mad_u64_u32 v[24:25], s[0:1], v24, s4, v[100:101]
	ds_write_b128 v24, v[88:91]
	ds_write_b128 v26, v[92:95] offset:55552
	v_readlane_b32 s0, v251, 22
	v_and_b32_e32 v101, -16, v210
	v_and_b32_e32 v25, 3, v210
	v_or_b32_e32 v102, s0, v228
	v_mul_lo_u32 v24, v102, s5
	v_add3_u32 v106, 0, v24, v101
	v_lshlrev_b32_e32 v24, 1, v228
	v_and_or_b32 v24, v24, 24, v25
	v_xor_b32_e32 v56, 32, v222
	v_mul_u32_u24_e32 v103, 0x90, v24
	v_readlane_b32 s0, v251, 24
	v_cmp_lt_i32_e32 vcc, v56, v151
	s_waitcnt lgkmcnt(0)
	v_add3_u32 v107, s0, v101, v103
	v_cndmask_b32_e32 v56, v222, v56, vcc
	s_barrier
	v_lshlrev_b32_e32 v176, 2, v56
	v_mov_b32_e32 v108, s98
	s_waitcnt lgkmcnt(0)
	ds_read_b128 v[120:123], v107
	ds_read_b128 v[124:127], v107 offset:64
	ds_read_b128 v[128:131], v107 offset:576
	ds_read_b128 v[132:135], v107 offset:640
	ds_read_b128 v[136:139], v107 offset:4608
	ds_read_b128 v[140:143], v107 offset:4672
	ds_read_b128 v[144:147], v107 offset:5184
	ds_read_b128 v[160:163], v107 offset:5248
	ds_read_b128 v[164:167], v107 offset:9216
	ds_read_b128 v[168:171], v107 offset:9280
	ds_read_b128 v[172:175], v107 offset:9792
	ds_read_b128 v[180:183], v107 offset:9856
	ds_read_b128 v[196:199], v107 offset:13824
	ds_read_b128 v[200:203], v107 offset:13888
	v_mov_b32_e32 v24, 0xf149f2ca
	v_cndmask_b32_e64 v28, v24, 0, s[2:3]
	v_mov_b32_e32 v29, v28
	v_mov_b32_e32 v30, v28
	v_mov_b32_e32 v31, v28
	v_cndmask_b32_e64 v24, 0, v24, s[36:37]
	v_mov_b32_e32 v25, v24
	s_waitcnt lgkmcnt(13)
	v_mfma_f32_16x16x32_bf16 v[56:59], v[120:123], v[48:51], v[28:31]
	v_mov_b32_e32 v26, v24
	v_mov_b32_e32 v27, v24
	s_mov_b32 s2, 0x3fb8aa3b
	s_waitcnt lgkmcnt(12)
	v_mfma_f32_16x16x32_bf16 v[96:99], v[124:127], v[52:55], v[56:59]
	ds_read_b128 v[204:207], v107 offset:14400
	ds_read_b128 v[224:227], v107 offset:14464
	v_add_u32_e32 v105, 0xd800, v106
	v_cmp_gt_u32_e64 s[36:37], 16, v210
	s_waitcnt lgkmcnt(13)
	v_mfma_f32_16x16x32_bf16 v[56:59], v[128:131], v[48:51], v[28:31]

; #define LAS __attribute__((address_space(3)))
; #define LAS __attribute__((address_space(3)))
; __device__ __forceinline__ f32x4 mfma16(bf16x8 a, bf16x8 b, f32x4 c) { return __builtin_amdgcn_mfma_f32_16x16x32_bf16(a, b, c, 0, 0, 0); }
; template <int NKT, int VSTR, bool SINK>
; __device__ __forceinline__ void attn_core(LAS const unsigned char* kb_, LAS const unsigned char* vb_, bf16x8 q0, bf16x8 q1, float sk, unsigned mskbits, int fr, f32x4 (&o)[4]) {
;     ...
;     for (int kt = 0; kt < NKT; ++kt) {
;         const int key = (kt >> 1) * 32 + ((kt & 1) << 2) + krow;
;         LAS const unsigned char* kp = kb_ + key * 144;
;         const bf16x8 a0 = *(LAS const bf16x8*)kp, a1 = *(LAS const bf16x8*)(kp + 64);
;         const float bias = ((mskbits >> (kt >> 2)) & 1u) ? -1e30f : 0.f;
;         f32x4 s = mfma16(a0, q0, (f32x4){bias, bias, bias, bias});
;         s = mfma16(a1, q1, s);
;         S[kt] = s;
;     }
;     float mx = S[0][0];
; #pragma unroll
;     for (int kt = 0; kt < NKT; ++kt) mx = fmaxf(fmaxf(mx, fmaxf(S[kt][0], S[kt][1])), fmaxf(S[kt][2], S[kt][3]));
;     mx = fmaxf(mx, __shfl_xor(mx, 16)); mx = fmaxf(mx, __shfl_xor(mx, 32));
; template <bool DO_SWA, bool DO_MEM>
; __device__ __forceinline__ void attn_unit(const Args& a, unsigned char* ws, LAS unsigned char* lds, int l, int tid_in, int lane_in, int wave, int unit) {
;     ...
;                 const float sk = a.in[12][l * 8 + h] * LOG2E;
	v_mul_f32_e32 v109, 0x3fb8aa3b, v108
	s_waitcnt lgkmcnt(12)
	v_mfma_f32_16x16x32_bf16 v[92:95], v[132:135], v[52:55], v[56:59]
	ds_read_b128 v[232:235], v107 offset:18432
	ds_read_b128 v[236:239], v107 offset:18496
	s_waitcnt lgkmcnt(13)
	v_mfma_f32_16x16x32_bf16 v[56:59], v[136:139], v[48:51], v[28:31]
	s_waitcnt lgkmcnt(12)
	v_mfma_f32_16x16x32_bf16 v[88:91], v[140:143], v[52:55], v[56:59]
	ds_read_b128 v[240:243], v107 offset:19008
	ds_read_b128 v[244:247], v107 offset:19072
	s_waitcnt lgkmcnt(13)
	v_mfma_f32_16x16x32_bf16 v[56:59], v[144:147], v[48:51], v[28:31]
	s_waitcnt lgkmcnt(12)
	v_mfma_f32_16x16x32_bf16 v[84:87], v[160:163], v[52:55], v[56:59]
	ds_read_b128 v[120:123], v107 offset:23040
	ds_read_b128 v[124:127], v107 offset:23104
	s_waitcnt lgkmcnt(13)
	v_mfma_f32_16x16x32_bf16 v[56:59], v[164:167], v[48:51], v[24:27]
	s_waitcnt lgkmcnt(12)
	v_mfma_f32_16x16x32_bf16 v[80:83], v[168:171], v[52:55], v[56:59]
	ds_read_b128 v[128:131], v107 offset:23616
	ds_read_b128 v[132:135], v107 offset:23680
	s_waitcnt lgkmcnt(13)
	v_mfma_f32_16x16x32_bf16 v[56:59], v[172:175], v[48:51], v[24:27]
	s_waitcnt lgkmcnt(12)
	v_mfma_f32_16x16x32_bf16 v[76:79], v[180:183], v[52:55], v[56:59]
	s_waitcnt lgkmcnt(11)
	v_mfma_f32_16x16x32_bf16 v[56:59], v[196:199], v[48:51], v[24:27]
	s_waitcnt lgkmcnt(10)
	v_mfma_f32_16x16x32_bf16 v[72:75], v[200:203], v[52:55], v[56:59]
	s_waitcnt lgkmcnt(9)
	v_mfma_f32_16x16x32_bf16 v[56:59], v[204:207], v[48:51], v[24:27]
	s_waitcnt lgkmcnt(8)
	v_mfma_f32_16x16x32_bf16 v[68:71], v[224:227], v[52:55], v[56:59]
	s_waitcnt lgkmcnt(7)
	v_mfma_f32_16x16x32_bf16 v[56:59], v[232:235], v[48:51], 0
	s_waitcnt lgkmcnt(6)
	v_mfma_f32_16x16x32_bf16 v[64:67], v[236:239], v[52:55], v[56:59]
	s_waitcnt lgkmcnt(5)
	v_mfma_f32_16x16x32_bf16 v[56:59], v[240:243], v[48:51], 0
	s_waitcnt lgkmcnt(4)
	v_mfma_f32_16x16x32_bf16 v[60:63], v[244:247], v[52:55], v[56:59]
	s_waitcnt lgkmcnt(3)
	v_mfma_f32_16x16x32_bf16 v[56:59], v[120:123], v[48:51], 0
	s_waitcnt lgkmcnt(2)
	v_mfma_f32_16x16x32_bf16 v[56:59], v[124:127], v[52:55], v[56:59]
	s_waitcnt lgkmcnt(1)
	v_mfma_f32_16x16x32_bf16 v[48:51], v[128:131], v[48:51], 0
	s_waitcnt lgkmcnt(0)
	v_mfma_f32_16x16x32_bf16 v[48:51], v[132:135], v[52:55], v[48:51]
	v_max_f32_e32 v52, v99, v99
	v_max_f32_e32 v53, v98, v98
	v_max_f32_e32 v52, v53, v52
	v_max_f32_e32 v53, v93, v93
	v_max_f32_e32 v54, v92, v92
	v_max_f32_e32 v53, v54, v53
	v_max_f32_e32 v54, v95, v95
	v_max_f32_e32 v55, v94, v94
	v_max3_f32 v52, v96, v97, v52
	v_max_f32_e32 v54, v55, v54
	v_max3_f32 v52, v52, v53, v54
	v_max_f32_e32 v53, v89, v89
	v_max_f32_e32 v54, v88, v88
	v_max_f32_e32 v53, v54, v53
	v_max_f32_e32 v54, v91, v91
	v_max_f32_e32 v55, v90, v90
	v_max_f32_e32 v54, v55, v54
	v_max3_f32 v52, v52, v53, v54
	v_max_f32_e32 v53, v85, v85
	v_max_f32_e32 v54, v84, v84
	v_max_f32_e32 v53, v54, v53
	v_max_f32_e32 v54, v87, v87
	v_max_f32_e32 v55, v86, v86
	v_max_f32_e32 v54, v55, v54
	v_max3_f32 v52, v52, v53, v54
	v_max_f32_e32 v53, v81, v81
	v_max_f32_e32 v54, v80, v80
	v_max_f32_e32 v53, v54, v53
	v_max_f32_e32 v54, v83, v83
	v_max_f32_e32 v55, v82, v82
	v_max_f32_e32 v54, v55, v54
	v_max3_f32 v52, v52, v53, v54
	v_max_f32_e32 v53, v77, v77
	v_max_f32_e32 v54, v76, v76
	v_max_f32_e32 v53, v54, v53
	v_max_f32_e32 v54, v79, v79
	v_max_f32_e32 v55, v78, v78
	v_max_f32_e32 v54, v55, v54
	v_max3_f32 v52, v52, v53, v54
	v_max_f32_e32 v53, v73, v73
	v_max_f32_e32 v54, v72, v72
	v_max_f32_e32 v53, v54, v53
	v_max_f32_e32 v54, v75, v75
	v_max_f32_e32 v55, v74, v74
	v_max_f32_e32 v54, v55, v54
	v_max3_f32 v52, v52, v53, v54
	v_max_f32_e32 v53, v69, v69
	v_max_f32_e32 v54, v68, v68
	v_max_f32_e32 v53, v54, v53
	v_max_f32_e32 v54, v71, v71
	v_max_f32_e32 v55, v70, v70
	v_max_f32_e32 v54, v55, v54
	v_max3_f32 v52, v52, v53, v54
	v_max_f32_e32 v53, v65, v65
	v_max_f32_e32 v54, v64, v64
	v_max_f32_e32 v53, v54, v53
	v_max_f32_e32 v54, v67, v67
	v_max_f32_e32 v55, v66, v66
	v_max_f32_e32 v54, v55, v54
	v_max3_f32 v52, v52, v53, v54
	v_max_f32_e32 v53, v61, v61
	v_max_f32_e32 v54, v60, v60
	v_max_f32_e32 v53, v54, v53
	v_max_f32_e32 v54, v63, v63
	v_max_f32_e32 v55, v62, v62
	v_max_f32_e32 v54, v55, v54
	v_max3_f32 v52, v52, v53, v54
	v_max_f32_e32 v53, v57, v57
	v_max_f32_e32 v54, v56, v56
	v_max_f32_e32 v53, v54, v53
	v_max_f32_e32 v54, v59, v59
	v_max_f32_e32 v55, v58, v58
	v_max_f32_e32 v54, v55, v54
	v_max3_f32 v52, v52, v53, v54
	v_max_f32_e32 v53, v49, v49
	v_max_f32_e32 v54, v48, v48
	v_max_f32_e32 v53, v54, v53
	v_max_f32_e32 v54, v51, v51
	v_max_f32_e32 v55, v50, v50
	v_max_f32_e32 v54, v55, v54
	v_max3_f32 v52, v52, v53, v54
	ds_bpermute_b32 v53, v212, v52
	s_waitcnt lgkmcnt(0)
	v_max_f32_e32 v53, v53, v53
	v_max_f32_e32 v52, v52, v53
	ds_bpermute_b32 v53, v176, v52
	s_waitcnt lgkmcnt(0)
; __device__ __forceinline__ unsigned pk2(float lo, float hi) { return pg8::cvt_pk_bf16(lo, hi); }
; template <int NKT, int VSTR, bool SINK>
; __device__ __forceinline__ void attn_core(LAS const unsigned char* kb_, LAS const unsigned char* vb_, bf16x8 q0, bf16x8 q1, float sk, unsigned mskbits, int fr, f32x4 (&o)[4]) {
;     ...
;     if (SINK) mx = fmaxf(mx, sk);
;     float sum = 0.f;
; #pragma unroll
;     for (int kt = 0; kt < NKT; ++kt)
; #pragma unroll
;         for (int r = 0; r < 4; ++r) { const float p = __builtin_amdgcn_exp2f(S[kt][r] - mx); S[kt][r] = p; sum += p; }
;     sum += __shfl_xor(sum, 16); sum += __shfl_xor(sum, 32);
;     if (SINK) sum += __builtin_amdgcn_exp2f(sk - mx);
;     const float inv = 1.0f / sum;
;     bf16x8 pf[NKT / 2];
; #pragma unroll
;     for (int kb = 0; kb < NKT / 2; ++kb) {
;         v4u w; w.x = pk2(S[2 * kb][0], S[2 * kb][1]); w.y = pk2(S[2 * kb][2], S[2 * kb][3]); w.z = pk2(S[2 * kb + 1][0], S[2 * kb + 1][1]); w.w = pk2(S[2 * kb + 1][2], S[2 * kb + 1][3]);
;         pf[kb] = __builtin_bit_cast(bf16x8, w);
;     }
	v_max3_f32 v52, v52, v53, v109
	v_sub_f32_e32 v53, v96, v52
	v_exp_f32_e32 v53, v53
	v_sub_f32_e32 v55, v97, v52
	v_exp_f32_e32 v55, v55
	v_sub_f32_e32 v96, v98, v52
	v_exp_f32_e32 v96, v96
	v_sub_f32_e32 v97, v99, v52
	v_exp_f32_e32 v97, v97
	v_sub_f32_e32 v92, v92, v52
	v_add_f32_e32 v54, 0, v53
	v_exp_f32_e32 v92, v92
	v_sub_f32_e32 v93, v93, v52
	v_add_f32_e32 v54, v55, v54
	v_exp_f32_e32 v93, v93
	v_sub_f32_e32 v94, v94, v52
	v_add_f32_e32 v54, v96, v54
	v_exp_f32_e32 v94, v94
	v_sub_f32_e32 v95, v95, v52
	v_add_f32_e32 v54, v97, v54
	v_exp_f32_e32 v95, v95
	v_sub_f32_e32 v88, v88, v52
	v_add_f32_e32 v54, v92, v54
	v_exp_f32_e32 v88, v88
	v_sub_f32_e32 v89, v89, v52
	v_add_f32_e32 v54, v93, v54
	v_exp_f32_e32 v89, v89
	v_sub_f32_e32 v90, v90, v52
	v_add_f32_e32 v54, v94, v54
	v_exp_f32_e32 v90, v90
	v_sub_f32_e32 v91, v91, v52
	v_add_f32_e32 v54, v95, v54
	v_exp_f32_e32 v91, v91
	v_sub_f32_e32 v84, v84, v52
	v_add_f32_e32 v54, v88, v54
	v_exp_f32_e32 v84, v84
	v_sub_f32_e32 v85, v85, v52
	v_add_f32_e32 v54, v89, v54
	v_exp_f32_e32 v85, v85
	v_sub_f32_e32 v86, v86, v52
	v_add_f32_e32 v54, v90, v54
	v_exp_f32_e32 v86, v86
	v_sub_f32_e32 v87, v87, v52
	v_add_f32_e32 v54, v91, v54
	v_exp_f32_e32 v87, v87
	v_sub_f32_e32 v80, v80, v52
	v_add_f32_e32 v54, v84, v54
	v_exp_f32_e32 v80, v80
	v_sub_f32_e32 v81, v81, v52
	v_add_f32_e32 v54, v85, v54
	v_exp_f32_e32 v81, v81
	v_sub_f32_e32 v82, v82, v52
	v_add_f32_e32 v54, v86, v54
	v_exp_f32_e32 v82, v82
	v_sub_f32_e32 v83, v83, v52
	v_add_f32_e32 v54, v87, v54
	v_exp_f32_e32 v83, v83
	v_sub_f32_e32 v76, v76, v52
	v_add_f32_e32 v54, v80, v54
	v_exp_f32_e32 v76, v76
	v_sub_f32_e32 v77, v77, v52
	v_add_f32_e32 v54, v81, v54
	v_exp_f32_e32 v77, v77
	v_sub_f32_e32 v78, v78, v52
	v_add_f32_e32 v54, v82, v54
	v_exp_f32_e32 v78, v78
	v_sub_f32_e32 v79, v79, v52
	v_add_f32_e32 v54, v83, v54
	v_exp_f32_e32 v79, v79
	v_sub_f32_e32 v72, v72, v52
	v_add_f32_e32 v54, v76, v54
	v_exp_f32_e32 v72, v72
	v_sub_f32_e32 v73, v73, v52
	v_add_f32_e32 v54, v77, v54
	v_exp_f32_e32 v73, v73
	v_sub_f32_e32 v74, v74, v52
	v_add_f32_e32 v54, v78, v54
	v_exp_f32_e32 v74, v74
	v_sub_f32_e32 v75, v75, v52
	v_add_f32_e32 v54, v79, v54
	v_exp_f32_e32 v75, v75
	v_sub_f32_e32 v68, v68, v52
	v_add_f32_e32 v54, v72, v54
	v_exp_f32_e32 v98, v68
	v_sub_f32_e32 v68, v69, v52
	v_add_f32_e32 v54, v73, v54
	v_exp_f32_e32 v99, v68
	v_sub_f32_e32 v68, v70, v52
	v_add_f32_e32 v54, v74, v54
	v_exp_f32_e32 v109, v68
	v_sub_f32_e32 v68, v71, v52
	v_add_f32_e32 v54, v75, v54
	v_exp_f32_e32 v110, v68
	v_sub_f32_e32 v64, v64, v52
	v_add_f32_e32 v54, v98, v54
	v_exp_f32_e32 v111, v64
	v_sub_f32_e32 v64, v65, v52
	v_add_f32_e32 v54, v99, v54
	v_exp_f32_e32 v112, v64
	v_sub_f32_e32 v64, v66, v52
	v_add_f32_e32 v54, v109, v54
	v_exp_f32_e32 v113, v64
	v_sub_f32_e32 v64, v67, v52
	v_add_f32_e32 v54, v110, v54
	v_exp_f32_e32 v114, v64
	v_sub_f32_e32 v60, v60, v52
	v_add_f32_e32 v54, v111, v54
	v_exp_f32_e32 v115, v60
	v_sub_f32_e32 v60, v61, v52
	v_add_f32_e32 v54, v112, v54
	v_exp_f32_e32 v116, v60
	v_sub_f32_e32 v60, v62, v52
	v_add_f32_e32 v54, v113, v54
	v_exp_f32_e32 v117, v60
	v_sub_f32_e32 v60, v63, v52
	v_add_f32_e32 v54, v114, v54
	v_exp_f32_e32 v118, v60
	v_sub_f32_e32 v56, v56, v52
	v_add_f32_e32 v54, v115, v54
	v_exp_f32_e32 v119, v56
	v_sub_f32_e32 v56, v57, v52
	v_add_f32_e32 v54, v116, v54
	v_exp_f32_e32 v120, v56
	v_sub_f32_e32 v56, v58, v52
	v_add_f32_e32 v54, v117, v54
	v_exp_f32_e32 v121, v56
	v_sub_f32_e32 v56, v59, v52
	v_add_f32_e32 v54, v118, v54
	v_exp_f32_e32 v122, v56
	v_sub_f32_e32 v48, v48, v52
	v_add_f32_e32 v54, v119, v54
	v_exp_f32_e32 v123, v48
	v_sub_f32_e32 v49, v49, v52
	v_add_f32_e32 v54, v120, v54
	v_exp_f32_e32 v124, v49
	v_sub_f32_e32 v49, v50, v52
	v_add_f32_e32 v54, v121, v54
	v_exp_f32_e32 v125, v49
	v_sub_f32_e32 v49, v51, v52
	v_add_f32_e32 v54, v122, v54
	v_exp_f32_e32 v51, v49
	v_add_f32_e32 v48, v123, v54
	v_add_f32_e32 v48, v124, v48
	v_add_f32_e32 v48, v125, v48
	v_add_f32_e32 v48, v51, v48
	ds_bpermute_b32 v49, v212, v48
	v_cvt_pk_bf16_f32 v68, v53, v55
	v_cvt_pk_bf16_f32 v69, v96, v97
	v_cvt_pk_bf16_f32 v70, v92, v93
	v_cvt_pk_bf16_f32 v71, v94, v95
	s_waitcnt lgkmcnt(0)
	v_add_f32_e32 v48, v48, v49
	ds_bpermute_b32 v49, v176, v48
	v_cvt_pk_bf16_f32 v64, v88, v89
	v_cvt_pk_bf16_f32 v65, v90, v91
	v_cvt_pk_bf16_f32 v66, v84, v85
	v_cvt_pk_bf16_f32 v67, v86, v87
	s_waitcnt lgkmcnt(0)
	v_add_f32_e32 v48, v48, v49
	v_fma_f32 v49, v108, s2, -v52
	v_exp_f32_e32 v49, v49
	v_cvt_pk_bf16_f32 v60, v80, v81
	v_cvt_pk_bf16_f32 v61, v82, v83
	v_cvt_pk_bf16_f32 v62, v76, v77
	v_cvt_pk_bf16_f32 v63, v78, v79
	v_cvt_pk_bf16_f32 v56, v72, v73
	s_nop 0
	v_add_f32_e32 v108, v49, v48
	v_div_scale_f32 v72, s[0:1], v108, v108, 1.0
	v_rcp_f32_e32 v73, v72
	v_cvt_pk_bf16_f32 v57, v74, v75
	v_cvt_pk_bf16_f32 v58, v98, v99
	v_cvt_pk_bf16_f32 v59, v109, v110
	v_cvt_pk_bf16_f32 v52, v111, v112
	v_cvt_pk_bf16_f32 v53, v113, v114
	s_nop 0
	v_fma_f32 v74, -v72, v73, 1.0
	v_fmac_f32_e32 v73, v74, v73
	v_div_scale_f32 v74, vcc, 1.0, v108, 1.0
	v_mul_f32_e32 v75, v74, v73
	v_fma_f32 v76, -v72, v75, v74
	v_fmac_f32_e32 v75, v76, v73
	v_fma_f32 v72, -v72, v75, v74
	v_cvt_pk_bf16_f32 v54, v115, v116
	v_cvt_pk_bf16_f32 v55, v117, v118
	v_cvt_pk_bf16_f32 v48, v119, v120
	v_cvt_pk_bf16_f32 v49, v121, v122
	v_cvt_pk_bf16_f32 v50, v123, v124
	v_cvt_pk_bf16_f32 v51, v125, v51
	v_div_fmas_f32 v72, v72, v73, v75
	s_waitcnt lgkmcnt(0)
; #define LAS __attribute__((address_space(3)))
; __device__ __forceinline__ float sq4(const f32x4 a) { return (a[0] * a[0] + a[1] * a[1]) + (a[2] * a[2] + a[3] * a[3]); }
; #define LAS __attribute__((address_space(3)))
; __device__ __forceinline__ unsigned pk2(float lo, float hi) { return pg8::cvt_pk_bf16(lo, hi); }
; __device__ __forceinline__ f32x4 mfma16(bf16x8 a, bf16x8 b, f32x4 c) { return __builtin_amdgcn_mfma_f32_16x16x32_bf16(a, b, c, 0, 0, 0); }
; template <int NKT, int VSTR, bool SINK>
; __device__ __forceinline__ void attn_core(LAS const unsigned char* kb_, LAS const unsigned char* vb_, bf16x8 q0, bf16x8 q1, float sk, unsigned mskbits, int fr, f32x4 (&o)[4]) {
;     ...
; #pragma unroll
;     for (int dt = 0; dt < 4; ++dt) {
;         f32x4 acc = (f32x4){0.f, 0.f, 0.f, 0.f};
; #pragma unroll
;         for (int kb = 0; kb < NKT / 2; ++kb) {
;             const bf16x8 vf = *(LAS const bf16x8*)(vb_ + dt * 16 * VSTR + kb * 64);
;             acc = mfma16(vf, pf[kb], acc);
;         }
;         o[dt] = acc * inv;
;     }
; template <bool DO_SWA, bool DO_MEM>
; __device__ __forceinline__ void attn_unit(const Args& a, unsigned char* ws, LAS unsigned char* lds, int l, int tid_in, int lane_in, int wave, int unit) {
;     ...
;             for (int hh = 0; hh < 4; ++hh) {
;                 const int h = g * 4 + hh;
;                 const float sk = a.in[12][l * 8 + h] * LOG2E;
;                 f32x4 o[4];
;                 attn_core<12, 400, true>(lds + A_KS + g * 192 * 144 + fq * 16, lds + A_VT1 + (g * 64 + fr) * 400 + fq * 16, qsw[hh][0], qsw[hh][1], sk, mskbits, fr, o);
; #pragma unroll
;                 for (int dt = 0; dt < 4; ++dt) { ssq += pg8::sq4(o[dt]); osv[hh][dt] = (v2u){pk2(o[dt][0], o[dt][1]), pk2(o[dt][2], o[dt][3])}; }
	ds_read_b128 v[128:131], v106 offset:55296
	ds_read_b128 v[132:135], v106 offset:55360
	ds_read_b128 v[136:139], v106 offset:61760
	ds_read_b128 v[140:143], v105 offset:12864
	ds_read_b128 v[144:147], v106 offset:55424
	ds_read_b128 v[160:163], v106 offset:55488
	ds_read_b128 v[164:167], v106 offset:55552
	ds_read_b128 v[168:171], v106 offset:55616
	ds_read_b128 v[172:175], v106 offset:61696
	ds_read_b128 v[180:183], v106 offset:61824
	ds_read_b128 v[196:199], v106 offset:61888
	ds_read_b128 v[200:203], v106 offset:61952
	ds_read_b128 v[204:207], v106 offset:62016
	ds_read_b128 v[224:227], v105 offset:12800
	s_waitcnt lgkmcnt(13)
	v_mfma_f32_16x16x32_bf16 v[74:77], v[128:131], v[68:71], 0
	ds_read_b128 v[228:231], v105 offset:12928
	v_div_fixup_f32 v72, v72, v108, 1.0
	s_waitcnt lgkmcnt(13)
	v_mfma_f32_16x16x32_bf16 v[74:77], v[132:135], v[64:67], v[74:77]
	ds_read_b128 v[232:235], v105 offset:12992
	s_waitcnt lgkmcnt(11)
	v_mfma_f32_16x16x32_bf16 v[74:77], v[144:147], v[60:63], v[74:77]
	ds_read_b128 v[236:239], v105 offset:13056
	ds_read_b128 v[240:243], v105 offset:13120
	s_waitcnt lgkmcnt(12)
	v_mfma_f32_16x16x32_bf16 v[74:77], v[160:163], v[56:59], v[74:77]
	ds_read_b128 v[244:247], v105 offset:19200
	s_waitcnt lgkmcnt(12)
	v_mfma_f32_16x16x32_bf16 v[74:77], v[164:167], v[52:55], v[74:77]
	ds_read_b128 v[128:131], v105 offset:19264
	s_waitcnt lgkmcnt(12)
	v_mfma_f32_16x16x32_bf16 v[76:79], v[168:171], v[48:51], v[74:77]
	s_nop 7
	v_pk_mul_f32 v[74:75], v[78:79], v[72:73] op_sel_hi:[1,0]
	ds_read_b128 v[132:135], v105 offset:19328
	s_waitcnt lgkmcnt(12)
	v_mfma_f32_16x16x32_bf16 v[78:81], v[172:175], v[68:71], 0
	v_mul_f32_e64 v76, v76, v72
	v_mul_f32_e64 v77, v77, v72
	v_mfma_f32_16x16x32_bf16 v[78:81], v[136:139], v[64:67], v[78:81]
	ds_read_b128 v[144:147], v105 offset:19392
	s_waitcnt lgkmcnt(12)
	v_mfma_f32_16x16x32_bf16 v[78:81], v[180:183], v[60:63], v[78:81]
	ds_read_b128 v[160:163], v105 offset:19456
	s_waitcnt lgkmcnt(12)
	v_mfma_f32_16x16x32_bf16 v[78:81], v[196:199], v[56:59], v[78:81]
	ds_read_b128 v[164:167], v105 offset:19520
	s_waitcnt lgkmcnt(12)
	v_mfma_f32_16x16x32_bf16 v[78:81], v[200:203], v[52:55], v[78:81]
	s_waitcnt lgkmcnt(11)
	v_mfma_f32_16x16x32_bf16 v[80:83], v[204:207], v[48:51], v[78:81]
	s_nop 7
	v_pk_mul_f32 v[78:79], v[82:83], v[72:73] op_sel_hi:[1,0]
	s_waitcnt lgkmcnt(10)
	v_mfma_f32_16x16x32_bf16 v[82:85], v[224:227], v[68:71], 0
	v_mul_f32_e64 v80, v80, v72
	v_mul_f32_e64 v81, v81, v72
	v_mfma_f32_16x16x32_bf16 v[82:85], v[140:143], v[64:67], v[82:85]
	s_waitcnt lgkmcnt(9)
	v_mfma_f32_16x16x32_bf16 v[82:85], v[228:231], v[60:63], v[82:85]
	s_waitcnt lgkmcnt(8)
	v_mfma_f32_16x16x32_bf16 v[82:85], v[232:235], v[56:59], v[82:85]
	s_waitcnt lgkmcnt(7)
	v_mfma_f32_16x16x32_bf16 v[82:85], v[236:239], v[52:55], v[82:85]
	s_waitcnt lgkmcnt(6)
	v_mfma_f32_16x16x32_bf16 v[84:87], v[240:243], v[48:51], v[82:85]
	s_nop 7
	v_pk_mul_f32 v[82:83], v[72:73], v[86:87] op_sel_hi:[0,1]
	s_waitcnt lgkmcnt(5)
	v_mfma_f32_16x16x32_bf16 v[68:71], v[244:247], v[68:71], 0
	v_pk_mul_f32 v[84:85], v[72:73], v[84:85] op_sel_hi:[0,1]
	s_waitcnt lgkmcnt(4)
	v_mfma_f32_16x16x32_bf16 v[64:67], v[128:131], v[64:67], v[68:71]
	s_waitcnt lgkmcnt(3)
	v_mfma_f32_16x16x32_bf16 v[60:63], v[132:135], v[60:63], v[64:67]
	s_waitcnt lgkmcnt(2)
	v_mfma_f32_16x16x32_bf16 v[56:59], v[144:147], v[56:59], v[60:63]
	s_waitcnt lgkmcnt(1)
	v_mfma_f32_16x16x32_bf16 v[52:55], v[160:163], v[52:55], v[56:59]
	v_cvt_pk_bf16_f32 v93, v76, v77
	v_cvt_pk_bf16_f32 v92, v74, v75
	s_waitcnt lgkmcnt(0)
	v_mfma_f32_16x16x32_bf16 v[48:51], v[164:167], v[48:51], v[52:55]
	s_nop 2
	v_mul_f32_e32 v52, v77, v77
	v_mul_f32_e32 v53, v75, v75
	v_fmac_f32_e32 v52, v76, v76
	v_fmac_f32_e32 v53, v74, v74
	v_add_f32_e32 v52, v52, v53
	v_mul_f32_e32 v53, v81, v81
	v_mul_f32_e32 v54, v79, v79
	v_fmac_f32_e32 v53, v80, v80
	v_fmac_f32_e32 v54, v78, v78
	v_add_f32_e32 v53, v53, v54
	v_add_f32_e32 v52, v52, v53
	v_mul_f32_e32 v53, v85, v85
	v_mul_f32_e32 v54, v83, v83
	v_fmac_f32_e32 v53, v84, v84
	v_fmac_f32_e32 v54, v82, v82
	v_pk_mul_f32 v[50:51], v[72:73], v[50:51] op_sel_hi:[0,1]
	v_pk_mul_f32 v[48:49], v[72:73], v[48:49] op_sel_hi:[0,1]
	v_add_f32_e32 v53, v53, v54
	v_add_f32_e32 v52, v53, v52
	v_mul_f32_e32 v53, v49, v49
	v_mul_f32_e32 v54, v51, v51
	v_fmac_f32_e32 v53, v48, v48
	v_fmac_f32_e32 v54, v50, v50
	v_add_f32_e32 v53, v53, v54
	v_cvt_pk_bf16_f32 v95, v80, v81
	v_cvt_pk_bf16_f32 v94, v78, v79
	v_cvt_pk_bf16_f32 v97, v84, v85
	v_cvt_pk_bf16_f32 v96, v82, v83
	v_add_f32_e32 v108, v52, v53
	v_cvt_pk_bf16_f32 v99, v48, v49
	v_cvt_pk_bf16_f32 v98, v50, v51
	v_mov_b32_e32 v109, s99
	s_waitcnt lgkmcnt(0)
	ds_read_b128 v[120:123], v107
	ds_read_b128 v[124:127], v107 offset:64
	ds_read_b128 v[128:131], v107 offset:576
	ds_read_b128 v[132:135], v107 offset:640
	ds_read_b128 v[136:139], v107 offset:4608
	ds_read_b128 v[140:143], v107 offset:4672
	ds_read_b128 v[144:147], v107 offset:5184
	ds_read_b128 v[160:163], v107 offset:5248
	ds_read_b128 v[164:167], v107 offset:9216
	ds_read_b128 v[168:171], v107 offset:9280
	ds_read_b128 v[172:175], v107 offset:9792
	ds_read_b128 v[180:183], v107 offset:9856
	ds_read_b128 v[196:199], v107 offset:13824
	ds_read_b128 v[200:203], v107 offset:13888
	s_waitcnt lgkmcnt(13)
	v_mfma_f32_16x16x32_bf16 v[48:51], v[120:123], v[44:47], v[28:31]

; #define LAS __attribute__((address_space(3)))
; #define LAS __attribute__((address_space(3)))
; __device__ __forceinline__ f32x4 mfma16(bf16x8 a, bf16x8 b, f32x4 c) { return __builtin_amdgcn_mfma_f32_16x16x32_bf16(a, b, c, 0, 0, 0); }
; template <int NKT, int VSTR, bool SINK>
; __device__ __forceinline__ void attn_core(LAS const unsigned char* kb_, LAS const unsigned char* vb_, bf16x8 q0, bf16x8 q1, float sk, unsigned mskbits, int fr, f32x4 (&o)[4]) {
;     ...
;     for (int kt = 0; kt < NKT; ++kt) {
;         const int key = (kt >> 1) * 32 + ((kt & 1) << 2) + krow;
;         LAS const unsigned char* kp = kb_ + key * 144;
;         const bf16x8 a0 = *(LAS const bf16x8*)kp, a1 = *(LAS const bf16x8*)(kp + 64);
;         const float bias = ((mskbits >> (kt >> 2)) & 1u) ? -1e30f : 0.f;
;         f32x4 s = mfma16(a0, q0, (f32x4){bias, bias, bias, bias});
;         s = mfma16(a1, q1, s);
;         S[kt] = s;
;     }
;     float mx = S[0][0];
; #pragma unroll
;     for (int kt = 0; kt < NKT; ++kt) mx = fmaxf(fmaxf(mx, fmaxf(S[kt][0], S[kt][1])), fmaxf(S[kt][2], S[kt][3]));
;     mx = fmaxf(mx, __shfl_xor(mx, 16)); mx = fmaxf(mx, __shfl_xor(mx, 32));
; template <bool DO_SWA, bool DO_MEM>
; __device__ __forceinline__ void attn_unit(const Args& a, unsigned char* ws, LAS unsigned char* lds, int l, int tid_in, int lane_in, int wave, int unit) {
;     ...
;                 const float sk = a.in[12][l * 8 + h] * LOG2E;
	v_mul_f32_e32 v118, 0x3fb8aa3b, v109
	s_waitcnt lgkmcnt(12)
	v_mfma_f32_16x16x32_bf16 v[88:91], v[124:127], v[40:43], v[48:51]
	ds_read_b128 v[204:207], v107 offset:14400
	ds_read_b128 v[224:227], v107 offset:14464
	s_waitcnt lgkmcnt(13)
	v_mfma_f32_16x16x32_bf16 v[48:51], v[128:131], v[44:47], v[28:31]
	s_waitcnt lgkmcnt(12)
	v_mfma_f32_16x16x32_bf16 v[84:87], v[132:135], v[40:43], v[48:51]
	ds_read_b128 v[228:231], v107 offset:18432
	ds_read_b128 v[232:235], v107 offset:18496
	s_waitcnt lgkmcnt(13)
	v_mfma_f32_16x16x32_bf16 v[48:51], v[136:139], v[44:47], v[28:31]
	s_waitcnt lgkmcnt(12)
	v_mfma_f32_16x16x32_bf16 v[80:83], v[140:143], v[40:43], v[48:51]
	ds_read_b128 v[236:239], v107 offset:19008
	ds_read_b128 v[240:243], v107 offset:19072
	s_waitcnt lgkmcnt(13)
	v_mfma_f32_16x16x32_bf16 v[48:51], v[144:147], v[44:47], v[28:31]
	s_waitcnt lgkmcnt(12)
	v_mfma_f32_16x16x32_bf16 v[76:79], v[160:163], v[40:43], v[48:51]
	ds_read_b128 v[244:247], v107 offset:23040
	ds_read_b128 v[120:123], v107 offset:23104
	s_waitcnt lgkmcnt(13)
	v_mfma_f32_16x16x32_bf16 v[48:51], v[164:167], v[44:47], v[24:27]
	s_waitcnt lgkmcnt(12)
	v_mfma_f32_16x16x32_bf16 v[72:75], v[168:171], v[40:43], v[48:51]
	ds_read_b128 v[124:127], v107 offset:23616
	ds_read_b128 v[128:131], v107 offset:23680
	s_waitcnt lgkmcnt(13)
	v_mfma_f32_16x16x32_bf16 v[48:51], v[172:175], v[44:47], v[24:27]
	s_waitcnt lgkmcnt(12)
	v_mfma_f32_16x16x32_bf16 v[68:71], v[180:183], v[40:43], v[48:51]
	s_waitcnt lgkmcnt(11)
	v_mfma_f32_16x16x32_bf16 v[48:51], v[196:199], v[44:47], v[24:27]
	s_waitcnt lgkmcnt(10)
	v_mfma_f32_16x16x32_bf16 v[64:67], v[200:203], v[40:43], v[48:51]
	s_waitcnt lgkmcnt(9)
	v_mfma_f32_16x16x32_bf16 v[48:51], v[204:207], v[44:47], v[24:27]
	s_waitcnt lgkmcnt(8)
	v_mfma_f32_16x16x32_bf16 v[60:63], v[224:227], v[40:43], v[48:51]
	s_waitcnt lgkmcnt(7)
	v_mfma_f32_16x16x32_bf16 v[48:51], v[228:231], v[44:47], 0
	s_waitcnt lgkmcnt(6)
	v_mfma_f32_16x16x32_bf16 v[56:59], v[232:235], v[40:43], v[48:51]
	s_waitcnt lgkmcnt(5)
	v_mfma_f32_16x16x32_bf16 v[48:51], v[236:239], v[44:47], 0
	s_waitcnt lgkmcnt(4)
	v_mfma_f32_16x16x32_bf16 v[52:55], v[240:243], v[40:43], v[48:51]
	s_waitcnt lgkmcnt(3)
	v_mfma_f32_16x16x32_bf16 v[48:51], v[244:247], v[44:47], 0
	s_waitcnt lgkmcnt(2)
	v_mfma_f32_16x16x32_bf16 v[48:51], v[120:123], v[40:43], v[48:51]
	s_waitcnt lgkmcnt(1)
	v_mfma_f32_16x16x32_bf16 v[44:47], v[124:127], v[44:47], 0
	s_waitcnt lgkmcnt(0)
	v_mfma_f32_16x16x32_bf16 v[40:43], v[128:131], v[40:43], v[44:47]
	s_nop 5
	v_max_f32_e32 v44, v91, v91
	v_max_f32_e32 v45, v90, v90
	v_max_f32_e32 v44, v45, v44
	v_max_f32_e32 v45, v85, v85
	v_max_f32_e32 v46, v84, v84
	v_max_f32_e32 v45, v46, v45
	v_max_f32_e32 v46, v87, v87
	v_max_f32_e32 v47, v86, v86
	v_max3_f32 v44, v88, v89, v44
	v_max_f32_e32 v46, v47, v46
	v_max3_f32 v44, v44, v45, v46
	v_max_f32_e32 v45, v81, v81
	v_max_f32_e32 v46, v80, v80
	v_max_f32_e32 v45, v46, v45
	v_max_f32_e32 v46, v83, v83
	v_max_f32_e32 v47, v82, v82
	v_max_f32_e32 v46, v47, v46
	v_max3_f32 v44, v44, v45, v46
	v_max_f32_e32 v45, v77, v77
	v_max_f32_e32 v46, v76, v76
	v_max_f32_e32 v45, v46, v45
	v_max_f32_e32 v46, v79, v79
	v_max_f32_e32 v47, v78, v78
	v_max_f32_e32 v46, v47, v46
	v_max3_f32 v44, v44, v45, v46
	v_max_f32_e32 v45, v73, v73
	v_max_f32_e32 v46, v72, v72
	v_max_f32_e32 v45, v46, v45
	v_max_f32_e32 v46, v75, v75
	v_max_f32_e32 v47, v74, v74
	v_max_f32_e32 v46, v47, v46
	v_max3_f32 v44, v44, v45, v46
	v_max_f32_e32 v45, v69, v69
	v_max_f32_e32 v46, v68, v68
	v_max_f32_e32 v45, v46, v45
	v_max_f32_e32 v46, v71, v71
	v_max_f32_e32 v47, v70, v70
	v_max_f32_e32 v46, v47, v46
	v_max3_f32 v44, v44, v45, v46
	v_max_f32_e32 v45, v65, v65
	v_max_f32_e32 v46, v64, v64
	v_max_f32_e32 v45, v46, v45
	v_max_f32_e32 v46, v67, v67
	v_max_f32_e32 v47, v66, v66
	v_max_f32_e32 v46, v47, v46
	v_max3_f32 v44, v44, v45, v46
	v_max_f32_e32 v45, v61, v61
	v_max_f32_e32 v46, v60, v60
	v_max_f32_e32 v45, v46, v45
	v_max_f32_e32 v46, v63, v63
	v_max_f32_e32 v47, v62, v62
	v_max_f32_e32 v46, v47, v46
	v_max3_f32 v44, v44, v45, v46
	v_max_f32_e32 v45, v57, v57
	v_max_f32_e32 v46, v56, v56
	v_max_f32_e32 v45, v46, v45
	v_max_f32_e32 v46, v59, v59
	v_max_f32_e32 v47, v58, v58
	v_max_f32_e32 v46, v47, v46
	v_max3_f32 v44, v44, v45, v46
	v_max_f32_e32 v45, v53, v53
	v_max_f32_e32 v46, v52, v52
	v_max_f32_e32 v45, v46, v45
	v_max_f32_e32 v46, v55, v55
	v_max_f32_e32 v47, v54, v54
	v_max_f32_e32 v46, v47, v46
	v_max3_f32 v44, v44, v45, v46
	v_max_f32_e32 v45, v49, v49
	v_max_f32_e32 v46, v48, v48
	v_max_f32_e32 v45, v46, v45
	v_max_f32_e32 v46, v51, v51
	v_max_f32_e32 v47, v50, v50
	v_max_f32_e32 v46, v47, v46
	v_max3_f32 v44, v44, v45, v46
	v_max_f32_e32 v45, v41, v41
	v_max_f32_e32 v46, v40, v40
	v_max_f32_e32 v45, v46, v45
	v_max_f32_e32 v46, v43, v43
	v_max_f32_e32 v47, v42, v42
	v_max_f32_e32 v46, v47, v46
	v_max3_f32 v44, v44, v45, v46
	ds_bpermute_b32 v45, v212, v44
	s_waitcnt lgkmcnt(0)
	v_max_f32_e32 v45, v45, v45
	v_max_f32_e32 v44, v44, v45
	ds_bpermute_b32 v45, v176, v44
	s_waitcnt lgkmcnt(0)
; __device__ __forceinline__ unsigned pk2(float lo, float hi) { return pg8::cvt_pk_bf16(lo, hi); }
; template <int NKT, int VSTR, bool SINK>
; __device__ __forceinline__ void attn_core(LAS const unsigned char* kb_, LAS const unsigned char* vb_, bf16x8 q0, bf16x8 q1, float sk, unsigned mskbits, int fr, f32x4 (&o)[4]) {
;     ...
;     if (SINK) mx = fmaxf(mx, sk);
;     float sum = 0.f;
; #pragma unroll
;     for (int kt = 0; kt < NKT; ++kt)
; #pragma unroll
;         for (int r = 0; r < 4; ++r) { const float p = __builtin_amdgcn_exp2f(S[kt][r] - mx); S[kt][r] = p; sum += p; }
;     sum += __shfl_xor(sum, 16); sum += __shfl_xor(sum, 32);
;     if (SINK) sum += __builtin_amdgcn_exp2f(sk - mx);
;     const float inv = 1.0f / sum;
;     bf16x8 pf[NKT / 2];
; #pragma unroll
;     for (int kb = 0; kb < NKT / 2; ++kb) {
;         v4u w; w.x = pk2(S[2 * kb][0], S[2 * kb][1]); w.y = pk2(S[2 * kb][2], S[2 * kb][3]); w.z = pk2(S[2 * kb + 1][0], S[2 * kb + 1][1]); w.w = pk2(S[2 * kb + 1][2], S[2 * kb + 1][3]);
;         pf[kb] = __builtin_bit_cast(bf16x8, w);
;     }
	v_max3_f32 v44, v44, v45, v118
	v_sub_f32_e32 v45, v88, v44
	v_exp_f32_e32 v45, v45
	v_sub_f32_e32 v47, v89, v44
	v_exp_f32_e32 v47, v47
	v_sub_f32_e32 v88, v90, v44
	v_exp_f32_e32 v88, v88
	v_sub_f32_e32 v89, v91, v44
	v_exp_f32_e32 v89, v89
	v_sub_f32_e32 v84, v84, v44
	v_add_f32_e32 v46, 0, v45
	v_exp_f32_e32 v84, v84
	v_sub_f32_e32 v85, v85, v44
	v_add_f32_e32 v46, v47, v46
	v_exp_f32_e32 v85, v85
	v_sub_f32_e32 v86, v86, v44
	v_add_f32_e32 v46, v88, v46
	v_exp_f32_e32 v86, v86
	v_sub_f32_e32 v87, v87, v44
	v_add_f32_e32 v46, v89, v46
	v_exp_f32_e32 v87, v87
	v_sub_f32_e32 v80, v80, v44
	v_add_f32_e32 v46, v84, v46
	v_exp_f32_e32 v80, v80
	v_sub_f32_e32 v81, v81, v44
	v_add_f32_e32 v46, v85, v46
	v_exp_f32_e32 v81, v81
	v_sub_f32_e32 v82, v82, v44
	v_add_f32_e32 v46, v86, v46
	v_exp_f32_e32 v82, v82
	v_sub_f32_e32 v83, v83, v44
	v_add_f32_e32 v46, v87, v46
	v_exp_f32_e32 v83, v83
	v_sub_f32_e32 v76, v76, v44
	v_add_f32_e32 v46, v80, v46
	v_exp_f32_e32 v76, v76
	v_sub_f32_e32 v77, v77, v44
	v_add_f32_e32 v46, v81, v46
	v_exp_f32_e32 v77, v77
	v_sub_f32_e32 v78, v78, v44
	v_add_f32_e32 v46, v82, v46
	v_exp_f32_e32 v78, v78
	v_sub_f32_e32 v79, v79, v44
	v_add_f32_e32 v46, v83, v46
	v_exp_f32_e32 v79, v79
	v_sub_f32_e32 v72, v72, v44
	v_add_f32_e32 v46, v76, v46
	v_exp_f32_e32 v72, v72
	v_sub_f32_e32 v73, v73, v44
	v_add_f32_e32 v46, v77, v46
	v_exp_f32_e32 v73, v73
	v_sub_f32_e32 v74, v74, v44
	v_add_f32_e32 v46, v78, v46
	v_exp_f32_e32 v74, v74
	v_sub_f32_e32 v75, v75, v44
	v_add_f32_e32 v46, v79, v46
	v_exp_f32_e32 v75, v75
	v_sub_f32_e32 v68, v68, v44
	v_add_f32_e32 v46, v72, v46
	v_exp_f32_e32 v68, v68
	v_sub_f32_e32 v69, v69, v44
	v_add_f32_e32 v46, v73, v46
	v_exp_f32_e32 v69, v69
	v_sub_f32_e32 v70, v70, v44
	v_add_f32_e32 v46, v74, v46
	v_exp_f32_e32 v70, v70
	v_sub_f32_e32 v71, v71, v44
	v_add_f32_e32 v46, v75, v46
	v_exp_f32_e32 v71, v71
	v_sub_f32_e32 v64, v64, v44
	v_add_f32_e32 v46, v68, v46
	v_exp_f32_e32 v64, v64
	v_sub_f32_e32 v65, v65, v44
	v_add_f32_e32 v46, v69, v46
	v_exp_f32_e32 v65, v65
	v_sub_f32_e32 v66, v66, v44
	v_add_f32_e32 v46, v70, v46
	v_exp_f32_e32 v66, v66
	v_sub_f32_e32 v67, v67, v44
	v_add_f32_e32 v46, v71, v46
	v_exp_f32_e32 v67, v67
	v_sub_f32_e32 v60, v60, v44
	v_add_f32_e32 v46, v64, v46
	v_exp_f32_e32 v90, v60
	v_sub_f32_e32 v60, v61, v44
	v_add_f32_e32 v46, v65, v46
	v_exp_f32_e32 v91, v60
	v_sub_f32_e32 v60, v62, v44
	v_add_f32_e32 v46, v66, v46
	v_exp_f32_e32 v110, v60
	v_sub_f32_e32 v60, v63, v44
	v_add_f32_e32 v46, v67, v46
	v_exp_f32_e32 v111, v60
	v_sub_f32_e32 v56, v56, v44
	v_add_f32_e32 v46, v90, v46
	v_exp_f32_e32 v112, v56
	v_sub_f32_e32 v56, v57, v44
	v_add_f32_e32 v46, v91, v46
	v_exp_f32_e32 v113, v56
	v_sub_f32_e32 v56, v58, v44
	v_add_f32_e32 v46, v110, v46
	v_exp_f32_e32 v114, v56
	v_sub_f32_e32 v56, v59, v44
	v_add_f32_e32 v46, v111, v46
	v_exp_f32_e32 v115, v56
	v_sub_f32_e32 v52, v52, v44
	v_add_f32_e32 v46, v112, v46
	v_exp_f32_e32 v116, v52
	v_sub_f32_e32 v52, v53, v44
	v_add_f32_e32 v46, v113, v46
	v_exp_f32_e32 v117, v52
	v_sub_f32_e32 v52, v54, v44
	v_add_f32_e32 v46, v114, v46
	v_exp_f32_e32 v118, v52
	v_sub_f32_e32 v52, v55, v44
	v_add_f32_e32 v46, v115, v46
	v_exp_f32_e32 v119, v52
	v_sub_f32_e32 v48, v48, v44
	v_add_f32_e32 v46, v116, v46
	v_exp_f32_e32 v120, v48
	v_sub_f32_e32 v48, v49, v44
	v_add_f32_e32 v46, v117, v46
	v_exp_f32_e32 v121, v48
	v_sub_f32_e32 v48, v50, v44
	v_add_f32_e32 v46, v118, v46
	v_exp_f32_e32 v122, v48
	v_sub_f32_e32 v48, v51, v44
	v_add_f32_e32 v46, v119, v46
	v_exp_f32_e32 v123, v48
	v_sub_f32_e32 v40, v40, v44
	v_add_f32_e32 v46, v120, v46
	v_exp_f32_e32 v124, v40
	v_sub_f32_e32 v41, v41, v44
	v_add_f32_e32 v46, v121, v46
	v_exp_f32_e32 v125, v41
	v_sub_f32_e32 v41, v42, v44
	v_add_f32_e32 v46, v122, v46
	v_exp_f32_e32 v126, v41
	v_sub_f32_e32 v41, v43, v44
	v_add_f32_e32 v46, v123, v46
	v_exp_f32_e32 v43, v41
	v_add_f32_e32 v40, v124, v46
	v_add_f32_e32 v40, v125, v40
	v_add_f32_e32 v40, v126, v40
	v_add_f32_e32 v40, v43, v40
	ds_bpermute_b32 v41, v212, v40
	v_cvt_pk_bf16_f32 v60, v45, v47
	v_cvt_pk_bf16_f32 v61, v88, v89
	v_cvt_pk_bf16_f32 v62, v84, v85
	v_cvt_pk_bf16_f32 v63, v86, v87
	s_waitcnt lgkmcnt(0)
	v_add_f32_e32 v40, v40, v41
	ds_bpermute_b32 v41, v176, v40
	v_cvt_pk_bf16_f32 v56, v80, v81
	v_cvt_pk_bf16_f32 v57, v82, v83
	v_cvt_pk_bf16_f32 v58, v76, v77
	v_cvt_pk_bf16_f32 v59, v78, v79
	s_waitcnt lgkmcnt(0)
	v_add_f32_e32 v40, v40, v41
	v_fma_f32 v41, v109, s2, -v44
	v_exp_f32_e32 v41, v41
	v_cvt_pk_bf16_f32 v52, v72, v73
	v_cvt_pk_bf16_f32 v53, v74, v75
	v_cvt_pk_bf16_f32 v54, v68, v69
	v_cvt_pk_bf16_f32 v55, v70, v71
	v_cvt_pk_bf16_f32 v48, v64, v65
	s_nop 0
	v_add_f32_e32 v109, v41, v40
	v_div_scale_f32 v64, s[0:1], v109, v109, 1.0
	v_rcp_f32_e32 v65, v64
	v_cvt_pk_bf16_f32 v49, v66, v67
	v_cvt_pk_bf16_f32 v50, v90, v91
	v_cvt_pk_bf16_f32 v51, v110, v111
	v_cvt_pk_bf16_f32 v44, v112, v113
	v_cvt_pk_bf16_f32 v45, v114, v115
	s_nop 0
	v_fma_f32 v66, -v64, v65, 1.0
	v_fmac_f32_e32 v65, v66, v65
	v_div_scale_f32 v66, vcc, 1.0, v109, 1.0
	v_mul_f32_e32 v67, v66, v65
	v_fma_f32 v68, -v64, v67, v66
	v_fmac_f32_e32 v67, v68, v65
	v_fma_f32 v64, -v64, v67, v66
	v_cvt_pk_bf16_f32 v46, v116, v117
	v_cvt_pk_bf16_f32 v47, v118, v119
	v_cvt_pk_bf16_f32 v40, v120, v121
	v_cvt_pk_bf16_f32 v41, v122, v123
	v_cvt_pk_bf16_f32 v42, v124, v125
	v_cvt_pk_bf16_f32 v43, v126, v43
	v_div_fmas_f32 v64, v64, v65, v67
	s_waitcnt lgkmcnt(0)
; #define LAS __attribute__((address_space(3)))
; __device__ __forceinline__ float sq4(const f32x4 a) { return (a[0] * a[0] + a[1] * a[1]) + (a[2] * a[2] + a[3] * a[3]); }
; #define LAS __attribute__((address_space(3)))
; __device__ __forceinline__ unsigned pk2(float lo, float hi) { return pg8::cvt_pk_bf16(lo, hi); }
; __device__ __forceinline__ f32x4 mfma16(bf16x8 a, bf16x8 b, f32x4 c) { return __builtin_amdgcn_mfma_f32_16x16x32_bf16(a, b, c, 0, 0, 0); }
; template <int NKT, int VSTR, bool SINK>
; __device__ __forceinline__ void attn_core(LAS const unsigned char* kb_, LAS const unsigned char* vb_, bf16x8 q0, bf16x8 q1, float sk, unsigned mskbits, int fr, f32x4 (&o)[4]) {
;     ...
; #pragma unroll
;     for (int dt = 0; dt < 4; ++dt) {
;         f32x4 acc = (f32x4){0.f, 0.f, 0.f, 0.f};
; #pragma unroll
;         for (int kb = 0; kb < NKT / 2; ++kb) {
;             const bf16x8 vf = *(LAS const bf16x8*)(vb_ + dt * 16 * VSTR + kb * 64);
;             acc = mfma16(vf, pf[kb], acc);
;         }
;         o[dt] = acc * inv;
;     }
; template <bool DO_SWA, bool DO_MEM>
; __device__ __forceinline__ void attn_unit(const Args& a, unsigned char* ws, LAS unsigned char* lds, int l, int tid_in, int lane_in, int wave, int unit) {
;     ...
;             for (int hh = 0; hh < 4; ++hh) {
;                 const int h = g * 4 + hh;
;                 const float sk = a.in[12][l * 8 + h] * LOG2E;
;                 f32x4 o[4];
;                 attn_core<12, 400, true>(lds + A_KS + g * 192 * 144 + fq * 16, lds + A_VT1 + (g * 64 + fr) * 400 + fq * 16, qsw[hh][0], qsw[hh][1], sk, mskbits, fr, o);
; #pragma unroll
;                 for (int dt = 0; dt < 4; ++dt) { ssq += pg8::sq4(o[dt]); osv[hh][dt] = (v2u){pk2(o[dt][0], o[dt][1]), pk2(o[dt][2], o[dt][3])}; }
	ds_read_b128 v[128:131], v106 offset:55296
	ds_read_b128 v[132:135], v106 offset:55360
	ds_read_b128 v[136:139], v106 offset:61760
	ds_read_b128 v[140:143], v105 offset:12864
	ds_read_b128 v[144:147], v106 offset:55424
	ds_read_b128 v[160:163], v106 offset:55488
	ds_read_b128 v[164:167], v106 offset:55552
	ds_read_b128 v[168:171], v106 offset:55616
	ds_read_b128 v[172:175], v106 offset:61696
	ds_read_b128 v[180:183], v106 offset:61824
	ds_read_b128 v[196:199], v106 offset:61888
	ds_read_b128 v[200:203], v106 offset:61952
	ds_read_b128 v[204:207], v106 offset:62016
	ds_read_b128 v[224:227], v105 offset:12800
	s_waitcnt lgkmcnt(13)
	v_mfma_f32_16x16x32_bf16 v[66:69], v[128:131], v[60:63], 0
	ds_read_b128 v[228:231], v105 offset:12928
	v_div_fixup_f32 v64, v64, v109, 1.0
	s_waitcnt lgkmcnt(13)
	v_mfma_f32_16x16x32_bf16 v[66:69], v[132:135], v[56:59], v[66:69]
	ds_read_b128 v[232:235], v105 offset:12992
	s_waitcnt lgkmcnt(11)
	v_mfma_f32_16x16x32_bf16 v[66:69], v[144:147], v[52:55], v[66:69]
	ds_read_b128 v[236:239], v105 offset:13056
	ds_read_b128 v[240:243], v105 offset:13120
	s_waitcnt lgkmcnt(12)
	v_mfma_f32_16x16x32_bf16 v[66:69], v[160:163], v[48:51], v[66:69]
	ds_read_b128 v[244:247], v105 offset:19200
	s_waitcnt lgkmcnt(12)
	v_mfma_f32_16x16x32_bf16 v[66:69], v[164:167], v[44:47], v[66:69]
	ds_read_b128 v[128:131], v105 offset:19264
	s_waitcnt lgkmcnt(12)
	v_mfma_f32_16x16x32_bf16 v[68:71], v[168:171], v[40:43], v[66:69]
	s_nop 7
	v_pk_mul_f32 v[66:67], v[70:71], v[64:65] op_sel_hi:[1,0]
	ds_read_b128 v[132:135], v105 offset:19328
	s_waitcnt lgkmcnt(12)
	v_mfma_f32_16x16x32_bf16 v[70:73], v[172:175], v[60:63], 0
	v_mul_f32_e64 v68, v68, v64
	v_mul_f32_e64 v69, v69, v64
	v_mfma_f32_16x16x32_bf16 v[70:73], v[136:139], v[56:59], v[70:73]
	ds_read_b128 v[144:147], v105 offset:19392
	s_waitcnt lgkmcnt(12)
	v_mfma_f32_16x16x32_bf16 v[70:73], v[180:183], v[52:55], v[70:73]
	ds_read_b128 v[160:163], v105 offset:19456
	s_waitcnt lgkmcnt(12)
	v_mfma_f32_16x16x32_bf16 v[70:73], v[196:199], v[48:51], v[70:73]
	ds_read_b128 v[164:167], v105 offset:19520
	s_waitcnt lgkmcnt(12)
	v_mfma_f32_16x16x32_bf16 v[70:73], v[200:203], v[44:47], v[70:73]
	s_waitcnt lgkmcnt(11)
	v_mfma_f32_16x16x32_bf16 v[72:75], v[204:207], v[40:43], v[70:73]
	s_nop 7
	v_pk_mul_f32 v[70:71], v[74:75], v[64:65] op_sel_hi:[1,0]
	s_waitcnt lgkmcnt(10)
	v_mfma_f32_16x16x32_bf16 v[74:77], v[224:227], v[60:63], 0
	v_mul_f32_e64 v72, v72, v64
	v_mul_f32_e64 v73, v73, v64
	v_mfma_f32_16x16x32_bf16 v[74:77], v[140:143], v[56:59], v[74:77]
	s_waitcnt lgkmcnt(9)
	v_mfma_f32_16x16x32_bf16 v[74:77], v[228:231], v[52:55], v[74:77]
	s_waitcnt lgkmcnt(8)
	v_mfma_f32_16x16x32_bf16 v[74:77], v[232:235], v[48:51], v[74:77]
	s_waitcnt lgkmcnt(7)
	v_mfma_f32_16x16x32_bf16 v[74:77], v[236:239], v[44:47], v[74:77]
	s_waitcnt lgkmcnt(6)
	v_mfma_f32_16x16x32_bf16 v[76:79], v[240:243], v[40:43], v[74:77]
	s_nop 7
	v_pk_mul_f32 v[74:75], v[64:65], v[78:79] op_sel_hi:[0,1]
	s_waitcnt lgkmcnt(5)
	v_mfma_f32_16x16x32_bf16 v[60:63], v[244:247], v[60:63], 0
	v_pk_mul_f32 v[76:77], v[64:65], v[76:77] op_sel_hi:[0,1]
	s_waitcnt lgkmcnt(4)
	v_mfma_f32_16x16x32_bf16 v[56:59], v[128:131], v[56:59], v[60:63]
	s_waitcnt lgkmcnt(3)
	v_mfma_f32_16x16x32_bf16 v[52:55], v[132:135], v[52:55], v[56:59]
	s_waitcnt lgkmcnt(2)
	v_mfma_f32_16x16x32_bf16 v[48:51], v[144:147], v[48:51], v[52:55]
	s_waitcnt lgkmcnt(1)
	v_mfma_f32_16x16x32_bf16 v[44:47], v[160:163], v[44:47], v[48:51]
	v_cvt_pk_bf16_f32 v85, v68, v69
	v_cvt_pk_bf16_f32 v84, v66, v67
	s_waitcnt lgkmcnt(0)
	v_mfma_f32_16x16x32_bf16 v[40:43], v[164:167], v[40:43], v[44:47]
	s_nop 2
	v_mul_f32_e32 v44, v69, v69
	v_mul_f32_e32 v45, v67, v67
	v_fmac_f32_e32 v44, v68, v68
	v_fmac_f32_e32 v45, v66, v66
	v_add_f32_e32 v44, v44, v45
	v_mul_f32_e32 v45, v73, v73
	v_mul_f32_e32 v46, v71, v71
	v_fmac_f32_e32 v45, v72, v72
	v_fmac_f32_e32 v46, v70, v70
	v_add_f32_e32 v44, v108, v44
	v_add_f32_e32 v45, v45, v46
	v_add_f32_e32 v44, v45, v44
	v_mul_f32_e32 v45, v77, v77
	v_mul_f32_e32 v46, v75, v75
	v_fmac_f32_e32 v45, v76, v76
	v_fmac_f32_e32 v46, v74, v74
	v_pk_mul_f32 v[42:43], v[64:65], v[42:43] op_sel_hi:[0,1]
	v_pk_mul_f32 v[40:41], v[64:65], v[40:41] op_sel_hi:[0,1]
	v_add_f32_e32 v45, v45, v46
	v_add_f32_e32 v44, v45, v44
	v_mul_f32_e32 v45, v41, v41
	v_mul_f32_e32 v46, v43, v43
	v_fmac_f32_e32 v45, v40, v40
	v_fmac_f32_e32 v46, v42, v42
	v_add_f32_e32 v45, v45, v46
	v_cvt_pk_bf16_f32 v87, v72, v73
	v_cvt_pk_bf16_f32 v86, v70, v71
	v_cvt_pk_bf16_f32 v89, v76, v77
	v_cvt_pk_bf16_f32 v88, v74, v75
	v_add_f32_e32 v108, v44, v45
	v_cvt_pk_bf16_f32 v91, v40, v41
	v_cvt_pk_bf16_f32 v90, v42, v43
	v_mov_b32_e32 v109, s100
	s_waitcnt lgkmcnt(0)
	ds_read_b128 v[120:123], v107
	ds_read_b128 v[124:127], v107 offset:64
	ds_read_b128 v[128:131], v107 offset:576
	ds_read_b128 v[132:135], v107 offset:640
	ds_read_b128 v[136:139], v107 offset:4608
	ds_read_b128 v[140:143], v107 offset:4672
	ds_read_b128 v[144:147], v107 offset:5184
	ds_read_b128 v[160:163], v107 offset:5248
	ds_read_b128 v[164:167], v107 offset:9216
	ds_read_b128 v[168:171], v107 offset:9280
	ds_read_b128 v[172:175], v107 offset:9792
	ds_read_b128 v[180:183], v107 offset:9856
	ds_read_b128 v[196:199], v107 offset:13824
	ds_read_b128 v[200:203], v107 offset:13888
	s_waitcnt lgkmcnt(13)
	v_mfma_f32_16x16x32_bf16 v[40:43], v[120:123], v[36:39], v[28:31]

; #define LAS __attribute__((address_space(3)))
; #define LAS __attribute__((address_space(3)))
; __device__ __forceinline__ f32x4 mfma16(bf16x8 a, bf16x8 b, f32x4 c) { return __builtin_amdgcn_mfma_f32_16x16x32_bf16(a, b, c, 0, 0, 0); }
; template <int NKT, int VSTR, bool SINK>
; __device__ __forceinline__ void attn_core(LAS const unsigned char* kb_, LAS const unsigned char* vb_, bf16x8 q0, bf16x8 q1, float sk, unsigned mskbits, int fr, f32x4 (&o)[4]) {
;     ...
;     for (int kt = 0; kt < NKT; ++kt) {
;         const int key = (kt >> 1) * 32 + ((kt & 1) << 2) + krow;
;         LAS const unsigned char* kp = kb_ + key * 144;
;         const bf16x8 a0 = *(LAS const bf16x8*)kp, a1 = *(LAS const bf16x8*)(kp + 64);
;         const float bias = ((mskbits >> (kt >> 2)) & 1u) ? -1e30f : 0.f;
;         f32x4 s = mfma16(a0, q0, (f32x4){bias, bias, bias, bias});
;         s = mfma16(a1, q1, s);
;         S[kt] = s;
;     }
;     float mx = S[0][0];
; #pragma unroll
;     for (int kt = 0; kt < NKT; ++kt) mx = fmaxf(fmaxf(mx, fmaxf(S[kt][0], S[kt][1])), fmaxf(S[kt][2], S[kt][3]));
;     mx = fmaxf(mx, __shfl_xor(mx, 16)); mx = fmaxf(mx, __shfl_xor(mx, 32));
; template <bool DO_SWA, bool DO_MEM>
; __device__ __forceinline__ void attn_unit(const Args& a, unsigned char* ws, LAS unsigned char* lds, int l, int tid_in, int lane_in, int wave, int unit) {
;     ...
;                 const float sk = a.in[12][l * 8 + h] * LOG2E;
	v_mul_f32_e32 v118, 0x3fb8aa3b, v109
	s_waitcnt lgkmcnt(12)
	v_mfma_f32_16x16x32_bf16 v[80:83], v[124:127], v[32:35], v[40:43]
	ds_read_b128 v[204:207], v107 offset:14400
	ds_read_b128 v[224:227], v107 offset:14464
	s_waitcnt lgkmcnt(13)
	v_mfma_f32_16x16x32_bf16 v[40:43], v[128:131], v[36:39], v[28:31]
	s_waitcnt lgkmcnt(12)
	v_mfma_f32_16x16x32_bf16 v[76:79], v[132:135], v[32:35], v[40:43]
	ds_read_b128 v[228:231], v107 offset:18432
	ds_read_b128 v[232:235], v107 offset:18496
	s_waitcnt lgkmcnt(13)
	v_mfma_f32_16x16x32_bf16 v[40:43], v[136:139], v[36:39], v[28:31]
	s_waitcnt lgkmcnt(12)
	v_mfma_f32_16x16x32_bf16 v[72:75], v[140:143], v[32:35], v[40:43]
	ds_read_b128 v[236:239], v107 offset:19008
	ds_read_b128 v[240:243], v107 offset:19072
	s_waitcnt lgkmcnt(13)
	v_mfma_f32_16x16x32_bf16 v[40:43], v[144:147], v[36:39], v[28:31]
	s_waitcnt lgkmcnt(12)
	v_mfma_f32_16x16x32_bf16 v[68:71], v[160:163], v[32:35], v[40:43]
	ds_read_b128 v[244:247], v107 offset:23040
	ds_read_b128 v[120:123], v107 offset:23104
	s_waitcnt lgkmcnt(13)
	v_mfma_f32_16x16x32_bf16 v[40:43], v[164:167], v[36:39], v[24:27]
	s_waitcnt lgkmcnt(12)
	v_mfma_f32_16x16x32_bf16 v[64:67], v[168:171], v[32:35], v[40:43]
	ds_read_b128 v[124:127], v107 offset:23616
	ds_read_b128 v[128:131], v107 offset:23680
	s_waitcnt lgkmcnt(13)
	v_mfma_f32_16x16x32_bf16 v[40:43], v[172:175], v[36:39], v[24:27]
	s_waitcnt lgkmcnt(12)
	v_mfma_f32_16x16x32_bf16 v[60:63], v[180:183], v[32:35], v[40:43]
	s_waitcnt lgkmcnt(11)
	v_mfma_f32_16x16x32_bf16 v[40:43], v[196:199], v[36:39], v[24:27]
	s_waitcnt lgkmcnt(10)
	v_mfma_f32_16x16x32_bf16 v[56:59], v[200:203], v[32:35], v[40:43]
	s_waitcnt lgkmcnt(9)
	v_mfma_f32_16x16x32_bf16 v[40:43], v[204:207], v[36:39], v[24:27]
	s_waitcnt lgkmcnt(8)
	v_mfma_f32_16x16x32_bf16 v[52:55], v[224:227], v[32:35], v[40:43]
	s_waitcnt lgkmcnt(7)
	v_mfma_f32_16x16x32_bf16 v[40:43], v[228:231], v[36:39], 0
	s_waitcnt lgkmcnt(6)
	v_mfma_f32_16x16x32_bf16 v[48:51], v[232:235], v[32:35], v[40:43]
	s_waitcnt lgkmcnt(5)
	v_mfma_f32_16x16x32_bf16 v[40:43], v[236:239], v[36:39], 0
	s_waitcnt lgkmcnt(4)
	v_mfma_f32_16x16x32_bf16 v[44:47], v[240:243], v[32:35], v[40:43]
	s_waitcnt lgkmcnt(3)
	v_mfma_f32_16x16x32_bf16 v[40:43], v[244:247], v[36:39], 0
	s_waitcnt lgkmcnt(2)
	v_mfma_f32_16x16x32_bf16 v[40:43], v[120:123], v[32:35], v[40:43]
	s_waitcnt lgkmcnt(1)
	v_mfma_f32_16x16x32_bf16 v[36:39], v[124:127], v[36:39], 0
	s_waitcnt lgkmcnt(0)
	v_mfma_f32_16x16x32_bf16 v[32:35], v[128:131], v[32:35], v[36:39]
	s_nop 5
	v_max_f32_e32 v36, v83, v83
	v_max_f32_e32 v37, v82, v82
	v_max_f32_e32 v36, v37, v36
	v_max_f32_e32 v37, v77, v77
	v_max_f32_e32 v38, v76, v76
	v_max_f32_e32 v37, v38, v37
	v_max_f32_e32 v38, v79, v79
	v_max_f32_e32 v39, v78, v78
	v_max3_f32 v36, v80, v81, v36
	v_max_f32_e32 v38, v39, v38
	v_max3_f32 v36, v36, v37, v38
	v_max_f32_e32 v37, v73, v73
	v_max_f32_e32 v38, v72, v72
	v_max_f32_e32 v37, v38, v37
	v_max_f32_e32 v38, v75, v75
	v_max_f32_e32 v39, v74, v74
	v_max_f32_e32 v38, v39, v38
	v_max3_f32 v36, v36, v37, v38
	v_max_f32_e32 v37, v69, v69
	v_max_f32_e32 v38, v68, v68
	v_max_f32_e32 v37, v38, v37
	v_max_f32_e32 v38, v71, v71
	v_max_f32_e32 v39, v70, v70
	v_max_f32_e32 v38, v39, v38
	v_max3_f32 v36, v36, v37, v38
	v_max_f32_e32 v37, v65, v65
	v_max_f32_e32 v38, v64, v64
	v_max_f32_e32 v37, v38, v37
	v_max_f32_e32 v38, v67, v67
	v_max_f32_e32 v39, v66, v66
	v_max_f32_e32 v38, v39, v38
	v_max3_f32 v36, v36, v37, v38
	v_max_f32_e32 v37, v61, v61
	v_max_f32_e32 v38, v60, v60
	v_max_f32_e32 v37, v38, v37
	v_max_f32_e32 v38, v63, v63
	v_max_f32_e32 v39, v62, v62
	v_max_f32_e32 v38, v39, v38
	v_max3_f32 v36, v36, v37, v38
	v_max_f32_e32 v37, v57, v57
	v_max_f32_e32 v38, v56, v56
	v_max_f32_e32 v37, v38, v37
	v_max_f32_e32 v38, v59, v59
	v_max_f32_e32 v39, v58, v58
	v_max_f32_e32 v38, v39, v38
	v_max3_f32 v36, v36, v37, v38
	v_max_f32_e32 v37, v53, v53
	v_max_f32_e32 v38, v52, v52
	v_max_f32_e32 v37, v38, v37
	v_max_f32_e32 v38, v55, v55
	v_max_f32_e32 v39, v54, v54
	v_max_f32_e32 v38, v39, v38
	v_max3_f32 v36, v36, v37, v38
	v_max_f32_e32 v37, v49, v49
	v_max_f32_e32 v38, v48, v48
	v_max_f32_e32 v37, v38, v37
	v_max_f32_e32 v38, v51, v51
	v_max_f32_e32 v39, v50, v50
	v_max_f32_e32 v38, v39, v38
	v_max3_f32 v36, v36, v37, v38
	v_max_f32_e32 v37, v45, v45
	v_max_f32_e32 v38, v44, v44
	v_max_f32_e32 v37, v38, v37
	v_max_f32_e32 v38, v47, v47
	v_max_f32_e32 v39, v46, v46
	v_max_f32_e32 v38, v39, v38
	v_max3_f32 v36, v36, v37, v38
	v_max_f32_e32 v37, v41, v41
	v_max_f32_e32 v38, v40, v40
	v_max_f32_e32 v37, v38, v37
	v_max_f32_e32 v38, v43, v43
	v_max_f32_e32 v39, v42, v42
	v_max_f32_e32 v38, v39, v38
	v_max3_f32 v36, v36, v37, v38
	v_max_f32_e32 v37, v33, v33
	v_max_f32_e32 v38, v32, v32
	v_max_f32_e32 v37, v38, v37
	v_max_f32_e32 v38, v35, v35
	v_max_f32_e32 v39, v34, v34
	v_max_f32_e32 v38, v39, v38
	v_max3_f32 v36, v36, v37, v38
	ds_bpermute_b32 v37, v212, v36
	s_waitcnt lgkmcnt(0)
	v_max_f32_e32 v37, v37, v37
	v_max_f32_e32 v36, v36, v37
	ds_bpermute_b32 v37, v176, v36
	s_waitcnt lgkmcnt(0)
; __device__ __forceinline__ unsigned pk2(float lo, float hi) { return pg8::cvt_pk_bf16(lo, hi); }
; template <int NKT, int VSTR, bool SINK>
; __device__ __forceinline__ void attn_core(LAS const unsigned char* kb_, LAS const unsigned char* vb_, bf16x8 q0, bf16x8 q1, float sk, unsigned mskbits, int fr, f32x4 (&o)[4]) {
;     ...
;     if (SINK) mx = fmaxf(mx, sk);
;     float sum = 0.f;
; #pragma unroll
;     for (int kt = 0; kt < NKT; ++kt)
; #pragma unroll
;         for (int r = 0; r < 4; ++r) { const float p = __builtin_amdgcn_exp2f(S[kt][r] - mx); S[kt][r] = p; sum += p; }
;     sum += __shfl_xor(sum, 16); sum += __shfl_xor(sum, 32);
;     if (SINK) sum += __builtin_amdgcn_exp2f(sk - mx);
;     const float inv = 1.0f / sum;
;     bf16x8 pf[NKT / 2];
; #pragma unroll
;     for (int kb = 0; kb < NKT / 2; ++kb) {
;         v4u w; w.x = pk2(S[2 * kb][0], S[2 * kb][1]); w.y = pk2(S[2 * kb][2], S[2 * kb][3]); w.z = pk2(S[2 * kb + 1][0], S[2 * kb + 1][1]); w.w = pk2(S[2 * kb + 1][2], S[2 * kb + 1][3]);
;         pf[kb] = __builtin_bit_cast(bf16x8, w);
;     }
	v_max3_f32 v36, v36, v37, v118
	v_sub_f32_e32 v37, v80, v36
	v_exp_f32_e32 v37, v37
	v_sub_f32_e32 v39, v81, v36
	v_exp_f32_e32 v39, v39
	v_sub_f32_e32 v80, v82, v36
	v_exp_f32_e32 v80, v80
	v_sub_f32_e32 v81, v83, v36
	v_exp_f32_e32 v81, v81
	v_sub_f32_e32 v76, v76, v36
	v_add_f32_e32 v38, 0, v37
	v_exp_f32_e32 v76, v76
	v_sub_f32_e32 v77, v77, v36
	v_add_f32_e32 v38, v39, v38
	v_exp_f32_e32 v77, v77
	v_sub_f32_e32 v78, v78, v36
	v_add_f32_e32 v38, v80, v38
	v_exp_f32_e32 v78, v78
	v_sub_f32_e32 v79, v79, v36
	v_add_f32_e32 v38, v81, v38
	v_exp_f32_e32 v79, v79
	v_sub_f32_e32 v72, v72, v36
	v_add_f32_e32 v38, v76, v38
	v_exp_f32_e32 v72, v72
	v_sub_f32_e32 v73, v73, v36
	v_add_f32_e32 v38, v77, v38
	v_exp_f32_e32 v73, v73
	v_sub_f32_e32 v74, v74, v36
	v_add_f32_e32 v38, v78, v38
	v_exp_f32_e32 v74, v74
	v_sub_f32_e32 v75, v75, v36
	v_add_f32_e32 v38, v79, v38
	v_exp_f32_e32 v75, v75
	v_sub_f32_e32 v68, v68, v36
	v_add_f32_e32 v38, v72, v38
	v_exp_f32_e32 v68, v68
	v_sub_f32_e32 v69, v69, v36
	v_add_f32_e32 v38, v73, v38
	v_exp_f32_e32 v69, v69
	v_sub_f32_e32 v70, v70, v36
	v_add_f32_e32 v38, v74, v38
	v_exp_f32_e32 v70, v70
	v_sub_f32_e32 v71, v71, v36
	v_add_f32_e32 v38, v75, v38
	v_exp_f32_e32 v71, v71
	v_sub_f32_e32 v64, v64, v36
	v_add_f32_e32 v38, v68, v38
	v_exp_f32_e32 v64, v64
	v_sub_f32_e32 v65, v65, v36
	v_add_f32_e32 v38, v69, v38
	v_exp_f32_e32 v65, v65
	v_sub_f32_e32 v66, v66, v36
	v_add_f32_e32 v38, v70, v38
	v_exp_f32_e32 v66, v66
	v_sub_f32_e32 v67, v67, v36
	v_add_f32_e32 v38, v71, v38
	v_exp_f32_e32 v67, v67
	v_sub_f32_e32 v60, v60, v36
	v_add_f32_e32 v38, v64, v38
	v_exp_f32_e32 v60, v60
	v_sub_f32_e32 v61, v61, v36
	v_add_f32_e32 v38, v65, v38
	v_exp_f32_e32 v61, v61
	v_sub_f32_e32 v62, v62, v36
	v_add_f32_e32 v38, v66, v38
	v_exp_f32_e32 v62, v62
	v_sub_f32_e32 v63, v63, v36
	v_add_f32_e32 v38, v67, v38
	v_exp_f32_e32 v63, v63
	v_sub_f32_e32 v56, v56, v36
	v_add_f32_e32 v38, v60, v38
	v_exp_f32_e32 v56, v56
	v_sub_f32_e32 v57, v57, v36
	v_add_f32_e32 v38, v61, v38
	v_exp_f32_e32 v57, v57
	v_sub_f32_e32 v58, v58, v36
	v_add_f32_e32 v38, v62, v38
	v_exp_f32_e32 v58, v58
	v_sub_f32_e32 v59, v59, v36
	v_add_f32_e32 v38, v63, v38
	v_exp_f32_e32 v59, v59
	v_sub_f32_e32 v52, v52, v36
	v_add_f32_e32 v38, v56, v38
	v_exp_f32_e32 v82, v52
	v_sub_f32_e32 v52, v53, v36
	v_add_f32_e32 v38, v57, v38
	v_exp_f32_e32 v83, v52
	v_sub_f32_e32 v52, v54, v36
	v_add_f32_e32 v38, v58, v38
	v_exp_f32_e32 v110, v52
	v_sub_f32_e32 v52, v55, v36
	v_add_f32_e32 v38, v59, v38
	v_exp_f32_e32 v111, v52
	v_sub_f32_e32 v48, v48, v36
	v_add_f32_e32 v38, v82, v38
	v_exp_f32_e32 v112, v48
	v_sub_f32_e32 v48, v49, v36
	v_add_f32_e32 v38, v83, v38
	v_exp_f32_e32 v113, v48
	v_sub_f32_e32 v48, v50, v36
	v_add_f32_e32 v38, v110, v38
	v_exp_f32_e32 v114, v48
	v_sub_f32_e32 v48, v51, v36
	v_add_f32_e32 v38, v111, v38
	v_exp_f32_e32 v115, v48
	v_sub_f32_e32 v44, v44, v36
	v_add_f32_e32 v38, v112, v38
	v_exp_f32_e32 v116, v44
	v_sub_f32_e32 v44, v45, v36
	v_add_f32_e32 v38, v113, v38
	v_exp_f32_e32 v117, v44
	v_sub_f32_e32 v44, v46, v36
	v_add_f32_e32 v38, v114, v38
	v_exp_f32_e32 v118, v44
	v_sub_f32_e32 v44, v47, v36
	v_add_f32_e32 v38, v115, v38
	v_exp_f32_e32 v119, v44
	v_sub_f32_e32 v40, v40, v36
	v_add_f32_e32 v38, v116, v38
	v_exp_f32_e32 v120, v40
	v_sub_f32_e32 v40, v41, v36
	v_add_f32_e32 v38, v117, v38
	v_exp_f32_e32 v121, v40
	v_sub_f32_e32 v40, v42, v36
	v_add_f32_e32 v38, v118, v38
	v_exp_f32_e32 v122, v40
	v_sub_f32_e32 v40, v43, v36
	v_add_f32_e32 v38, v119, v38
	v_exp_f32_e32 v123, v40
	v_sub_f32_e32 v32, v32, v36
	v_add_f32_e32 v38, v120, v38
	v_exp_f32_e32 v124, v32
	v_sub_f32_e32 v33, v33, v36
	v_add_f32_e32 v38, v121, v38
	v_exp_f32_e32 v125, v33
	v_sub_f32_e32 v33, v34, v36
	v_add_f32_e32 v38, v122, v38
	v_exp_f32_e32 v126, v33
	v_sub_f32_e32 v33, v35, v36
	v_add_f32_e32 v38, v123, v38
	v_exp_f32_e32 v35, v33
	v_add_f32_e32 v32, v124, v38
	v_add_f32_e32 v32, v125, v32
	v_add_f32_e32 v32, v126, v32
	v_add_f32_e32 v32, v35, v32
	ds_bpermute_b32 v33, v212, v32
	v_cvt_pk_bf16_f32 v52, v37, v39
	v_cvt_pk_bf16_f32 v53, v80, v81
	v_cvt_pk_bf16_f32 v54, v76, v77
	v_cvt_pk_bf16_f32 v55, v78, v79
	s_waitcnt lgkmcnt(0)
	v_add_f32_e32 v32, v32, v33
	ds_bpermute_b32 v33, v176, v32
	v_cvt_pk_bf16_f32 v48, v72, v73
	v_cvt_pk_bf16_f32 v49, v74, v75
	v_cvt_pk_bf16_f32 v50, v68, v69
	v_cvt_pk_bf16_f32 v51, v70, v71
	s_waitcnt lgkmcnt(0)
	v_add_f32_e32 v32, v32, v33
	v_fma_f32 v33, v109, s2, -v36
	v_exp_f32_e32 v33, v33
	v_cvt_pk_bf16_f32 v44, v64, v65
	v_cvt_pk_bf16_f32 v45, v66, v67
	v_cvt_pk_bf16_f32 v46, v60, v61
	v_cvt_pk_bf16_f32 v47, v62, v63
	v_cvt_pk_bf16_f32 v40, v56, v57
	s_nop 0
	v_add_f32_e32 v109, v33, v32
	v_div_scale_f32 v56, s[0:1], v109, v109, 1.0
	v_rcp_f32_e32 v57, v56
	v_cvt_pk_bf16_f32 v41, v58, v59
	v_cvt_pk_bf16_f32 v42, v82, v83
	v_cvt_pk_bf16_f32 v43, v110, v111
	v_cvt_pk_bf16_f32 v36, v112, v113
	v_cvt_pk_bf16_f32 v37, v114, v115
	s_nop 0
	v_fma_f32 v58, -v56, v57, 1.0
	v_fmac_f32_e32 v57, v58, v57
	v_div_scale_f32 v58, vcc, 1.0, v109, 1.0
	v_mul_f32_e32 v59, v58, v57
	v_fma_f32 v60, -v56, v59, v58
	v_fmac_f32_e32 v59, v60, v57
	v_fma_f32 v56, -v56, v59, v58
	v_cvt_pk_bf16_f32 v38, v116, v117
	v_cvt_pk_bf16_f32 v39, v118, v119
	v_cvt_pk_bf16_f32 v32, v120, v121
	v_cvt_pk_bf16_f32 v33, v122, v123
	v_cvt_pk_bf16_f32 v34, v124, v125
	v_cvt_pk_bf16_f32 v35, v126, v35
	v_div_fmas_f32 v56, v56, v57, v59
	s_waitcnt lgkmcnt(0)
; #define LAS __attribute__((address_space(3)))
; __device__ __forceinline__ float sq4(const f32x4 a) { return (a[0] * a[0] + a[1] * a[1]) + (a[2] * a[2] + a[3] * a[3]); }
; #define LAS __attribute__((address_space(3)))
; __device__ __forceinline__ unsigned pk2(float lo, float hi) { return pg8::cvt_pk_bf16(lo, hi); }
; __device__ __forceinline__ f32x4 mfma16(bf16x8 a, bf16x8 b, f32x4 c) { return __builtin_amdgcn_mfma_f32_16x16x32_bf16(a, b, c, 0, 0, 0); }
; template <int NKT, int VSTR, bool SINK>
; __device__ __forceinline__ void attn_core(LAS const unsigned char* kb_, LAS const unsigned char* vb_, bf16x8 q0, bf16x8 q1, float sk, unsigned mskbits, int fr, f32x4 (&o)[4]) {
;     ...
; #pragma unroll
;     for (int dt = 0; dt < 4; ++dt) {
;         f32x4 acc = (f32x4){0.f, 0.f, 0.f, 0.f};
; #pragma unroll
;         for (int kb = 0; kb < NKT / 2; ++kb) {
;             const bf16x8 vf = *(LAS const bf16x8*)(vb_ + dt * 16 * VSTR + kb * 64);
;             acc = mfma16(vf, pf[kb], acc);
;         }
;         o[dt] = acc * inv;
;     }
; template <bool DO_SWA, bool DO_MEM>
; __device__ __forceinline__ void attn_unit(const Args& a, unsigned char* ws, LAS unsigned char* lds, int l, int tid_in, int lane_in, int wave, int unit) {
;     ...
;             for (int hh = 0; hh < 4; ++hh) {
;                 const int h = g * 4 + hh;
;                 const float sk = a.in[12][l * 8 + h] * LOG2E;
;                 f32x4 o[4];
;                 attn_core<12, 400, true>(lds + A_KS + g * 192 * 144 + fq * 16, lds + A_VT1 + (g * 64 + fr) * 400 + fq * 16, qsw[hh][0], qsw[hh][1], sk, mskbits, fr, o);
; #pragma unroll
;                 for (int dt = 0; dt < 4; ++dt) { ssq += pg8::sq4(o[dt]); osv[hh][dt] = (v2u){pk2(o[dt][0], o[dt][1]), pk2(o[dt][2], o[dt][3])}; }
	ds_read_b128 v[76:79], v106 offset:55296
	ds_read_b128 v[128:131], v106 offset:55360
	ds_read_b128 v[132:135], v106 offset:61760
	ds_read_b128 v[136:139], v105 offset:12864
	ds_read_b128 v[140:143], v106 offset:55424
	ds_read_b128 v[144:147], v106 offset:55488
	ds_read_b128 v[160:163], v106 offset:55552
	ds_read_b128 v[164:167], v106 offset:55616
	ds_read_b128 v[168:171], v106 offset:61696
	ds_read_b128 v[172:175], v106 offset:61824
	ds_read_b128 v[180:183], v106 offset:61888
	ds_read_b128 v[196:199], v106 offset:61952
	ds_read_b128 v[200:203], v106 offset:62016
	ds_read_b128 v[204:207], v105 offset:12800
	s_waitcnt lgkmcnt(13)
	v_mfma_f32_16x16x32_bf16 v[58:61], v[76:79], v[52:55], 0
	ds_read_b128 v[224:227], v105 offset:12928
	v_div_fixup_f32 v56, v56, v109, 1.0
	s_waitcnt lgkmcnt(13)
	v_mfma_f32_16x16x32_bf16 v[58:61], v[128:131], v[48:51], v[58:61]
	ds_read_b128 v[228:231], v105 offset:12992
	s_waitcnt lgkmcnt(11)
	v_mfma_f32_16x16x32_bf16 v[58:61], v[140:143], v[44:47], v[58:61]
	ds_read_b128 v[232:235], v105 offset:13056
	ds_read_b128 v[236:239], v105 offset:13120
	s_waitcnt lgkmcnt(12)
	v_mfma_f32_16x16x32_bf16 v[58:61], v[144:147], v[40:43], v[58:61]
	ds_read_b128 v[240:243], v105 offset:19200
	s_waitcnt lgkmcnt(12)
	v_mfma_f32_16x16x32_bf16 v[58:61], v[160:163], v[36:39], v[58:61]
	ds_read_b128 v[244:247], v105 offset:19264
	s_waitcnt lgkmcnt(12)
	v_mfma_f32_16x16x32_bf16 v[60:63], v[164:167], v[32:35], v[58:61]
	s_nop 7
	v_pk_mul_f32 v[58:59], v[62:63], v[56:57] op_sel_hi:[1,0]
	ds_read_b128 v[76:79], v105 offset:19328
	s_waitcnt lgkmcnt(12)
	v_mfma_f32_16x16x32_bf16 v[62:65], v[168:171], v[52:55], 0
	v_mul_f32_e64 v60, v60, v56
	v_mul_f32_e64 v61, v61, v56
	v_mfma_f32_16x16x32_bf16 v[62:65], v[132:135], v[48:51], v[62:65]
	ds_read_b128 v[128:131], v105 offset:19392
	s_waitcnt lgkmcnt(12)
	v_mfma_f32_16x16x32_bf16 v[62:65], v[172:175], v[44:47], v[62:65]
	ds_read_b128 v[140:143], v105 offset:19456
	s_waitcnt lgkmcnt(12)
	v_mfma_f32_16x16x32_bf16 v[62:65], v[180:183], v[40:43], v[62:65]
	ds_read_b128 v[144:147], v105 offset:19520
	s_waitcnt lgkmcnt(12)
	v_mfma_f32_16x16x32_bf16 v[62:65], v[196:199], v[36:39], v[62:65]
	s_waitcnt lgkmcnt(11)
	v_mfma_f32_16x16x32_bf16 v[64:67], v[200:203], v[32:35], v[62:65]
	s_nop 7
	v_pk_mul_f32 v[62:63], v[66:67], v[56:57] op_sel_hi:[1,0]
	s_waitcnt lgkmcnt(10)
	v_mfma_f32_16x16x32_bf16 v[66:69], v[204:207], v[52:55], 0
	v_mul_f32_e64 v64, v64, v56
	v_mul_f32_e64 v65, v65, v56
	v_mfma_f32_16x16x32_bf16 v[66:69], v[136:139], v[48:51], v[66:69]
	s_waitcnt lgkmcnt(9)
	v_mfma_f32_16x16x32_bf16 v[66:69], v[224:227], v[44:47], v[66:69]
	s_waitcnt lgkmcnt(8)
	v_mfma_f32_16x16x32_bf16 v[66:69], v[228:231], v[40:43], v[66:69]
	s_waitcnt lgkmcnt(7)
	v_mfma_f32_16x16x32_bf16 v[66:69], v[232:235], v[36:39], v[66:69]
	s_waitcnt lgkmcnt(6)
	v_mfma_f32_16x16x32_bf16 v[68:71], v[236:239], v[32:35], v[66:69]
	s_nop 7
	v_pk_mul_f32 v[66:67], v[56:57], v[70:71] op_sel_hi:[0,1]
	s_waitcnt lgkmcnt(5)
	v_mfma_f32_16x16x32_bf16 v[52:55], v[240:243], v[52:55], 0
	v_pk_mul_f32 v[68:69], v[56:57], v[68:69] op_sel_hi:[0,1]
	s_waitcnt lgkmcnt(4)
	v_mfma_f32_16x16x32_bf16 v[48:51], v[244:247], v[48:51], v[52:55]
	s_waitcnt lgkmcnt(3)
	v_mfma_f32_16x16x32_bf16 v[44:47], v[76:79], v[44:47], v[48:51]
	s_waitcnt lgkmcnt(2)
	v_mfma_f32_16x16x32_bf16 v[40:43], v[128:131], v[40:43], v[44:47]
	s_waitcnt lgkmcnt(1)
	v_mfma_f32_16x16x32_bf16 v[36:39], v[140:143], v[36:39], v[40:43]
	v_cvt_pk_bf16_f32 v81, v60, v61
	v_cvt_pk_bf16_f32 v80, v58, v59
	s_waitcnt lgkmcnt(0)
	v_mfma_f32_16x16x32_bf16 v[32:35], v[144:147], v[32:35], v[36:39]
	s_nop 2
	v_mul_f32_e32 v36, v61, v61
	v_mul_f32_e32 v37, v59, v59
	v_fmac_f32_e32 v36, v60, v60
	v_fmac_f32_e32 v37, v58, v58
	v_add_f32_e32 v36, v36, v37
	v_mul_f32_e32 v37, v65, v65
	v_mul_f32_e32 v38, v63, v63
	v_fmac_f32_e32 v37, v64, v64
	v_fmac_f32_e32 v38, v62, v62
	v_add_f32_e32 v36, v108, v36
	v_add_f32_e32 v37, v37, v38
	v_add_f32_e32 v36, v37, v36
	v_mul_f32_e32 v37, v69, v69
	v_mul_f32_e32 v38, v67, v67
	v_fmac_f32_e32 v37, v68, v68
	v_fmac_f32_e32 v38, v66, v66
	v_pk_mul_f32 v[34:35], v[56:57], v[34:35] op_sel_hi:[0,1]
	v_pk_mul_f32 v[32:33], v[56:57], v[32:33] op_sel_hi:[0,1]
	v_add_f32_e32 v37, v37, v38
	v_add_f32_e32 v36, v37, v36
	v_mul_f32_e32 v37, v33, v33
	v_mul_f32_e32 v38, v35, v35
	v_fmac_f32_e32 v37, v32, v32
	v_fmac_f32_e32 v38, v34, v34
	v_add_f32_e32 v37, v37, v38
	v_cvt_pk_bf16_f32 v83, v64, v65
	v_cvt_pk_bf16_f32 v82, v62, v63
	v_cvt_pk_bf16_f32 v109, v68, v69
	v_cvt_pk_bf16_f32 v108, v66, v67
	v_add_f32_e32 v68, v36, v37
	v_cvt_pk_bf16_f32 v111, v32, v33
	v_cvt_pk_bf16_f32 v110, v34, v35
	v_mov_b32_e32 v69, s101
	s_waitcnt lgkmcnt(0)
	ds_read_b128 v[112:115], v107
	ds_read_b128 v[116:119], v107 offset:64
	ds_read_b128 v[120:123], v107 offset:576
	ds_read_b128 v[124:127], v107 offset:640
	ds_read_b128 v[128:131], v107 offset:4608
	ds_read_b128 v[132:135], v107 offset:4672
	ds_read_b128 v[136:139], v107 offset:5184
	ds_read_b128 v[140:143], v107 offset:5248
	ds_read_b128 v[144:147], v107 offset:9216
	ds_read_b128 v[160:163], v107 offset:9280
	ds_read_b128 v[164:167], v107 offset:9792
	ds_read_b128 v[168:171], v107 offset:9856
	ds_read_b128 v[172:175], v107 offset:13824
	ds_read_b128 v[180:183], v107 offset:13888
	s_waitcnt lgkmcnt(13)
	v_mfma_f32_16x16x32_bf16 v[32:35], v[112:115], v[20:23], v[28:31]

; #define LAS __attribute__((address_space(3)))
; #define LAS __attribute__((address_space(3)))
; __device__ __forceinline__ f32x4 mfma16(bf16x8 a, bf16x8 b, f32x4 c) { return __builtin_amdgcn_mfma_f32_16x16x32_bf16(a, b, c, 0, 0, 0); }
; template <int NKT, int VSTR, bool SINK>
; __device__ __forceinline__ void attn_core(LAS const unsigned char* kb_, LAS const unsigned char* vb_, bf16x8 q0, bf16x8 q1, float sk, unsigned mskbits, int fr, f32x4 (&o)[4]) {
;     ...
;     for (int kt = 0; kt < NKT; ++kt) {
;         const int key = (kt >> 1) * 32 + ((kt & 1) << 2) + krow;
;         LAS const unsigned char* kp = kb_ + key * 144;
;         const bf16x8 a0 = *(LAS const bf16x8*)kp, a1 = *(LAS const bf16x8*)(kp + 64);
;         const float bias = ((mskbits >> (kt >> 2)) & 1u) ? -1e30f : 0.f;
;         f32x4 s = mfma16(a0, q0, (f32x4){bias, bias, bias, bias});
;         s = mfma16(a1, q1, s);
;         S[kt] = s;
;     }
;     float mx = S[0][0];
; #pragma unroll
;     for (int kt = 0; kt < NKT; ++kt) mx = fmaxf(fmaxf(mx, fmaxf(S[kt][0], S[kt][1])), fmaxf(S[kt][2], S[kt][3]));
;     mx = fmaxf(mx, __shfl_xor(mx, 16)); mx = fmaxf(mx, __shfl_xor(mx, 32));
; template <bool DO_SWA, bool DO_MEM>
; __device__ __forceinline__ void attn_unit(const Args& a, unsigned char* ws, LAS unsigned char* lds, int l, int tid_in, int lane_in, int wave, int unit) {
;     ...
;                 const float sk = a.in[12][l * 8 + h] * LOG2E;
	v_mul_f32_e32 v70, 0x3fb8aa3b, v69
	s_waitcnt lgkmcnt(12)
	v_mfma_f32_16x16x32_bf16 v[52:55], v[116:119], v[16:19], v[32:35]
	ds_read_b128 v[196:199], v107 offset:14400
	ds_read_b128 v[200:203], v107 offset:14464
	s_waitcnt lgkmcnt(13)
	v_mfma_f32_16x16x32_bf16 v[32:35], v[120:123], v[20:23], v[28:31]
	s_waitcnt lgkmcnt(12)
	v_mfma_f32_16x16x32_bf16 v[48:51], v[124:127], v[16:19], v[32:35]
	ds_read_b128 v[204:207], v107 offset:18432
	ds_read_b128 v[224:227], v107 offset:18496
	s_waitcnt lgkmcnt(13)
	v_mfma_f32_16x16x32_bf16 v[32:35], v[128:131], v[20:23], v[28:31]
	s_waitcnt lgkmcnt(12)
	v_mfma_f32_16x16x32_bf16 v[40:43], v[132:135], v[16:19], v[32:35]
	ds_read_b128 v[228:231], v107 offset:19008
	ds_read_b128 v[232:235], v107 offset:19072
	s_waitcnt lgkmcnt(13)
	v_mfma_f32_16x16x32_bf16 v[28:31], v[136:139], v[20:23], v[28:31]
	s_waitcnt lgkmcnt(12)
	v_mfma_f32_16x16x32_bf16 v[32:35], v[140:143], v[16:19], v[28:31]
	ds_read_b128 v[236:239], v107 offset:23040
	ds_read_b128 v[240:243], v107 offset:23104
	s_waitcnt lgkmcnt(13)
	v_mfma_f32_16x16x32_bf16 v[28:31], v[144:147], v[20:23], v[24:27]
	s_waitcnt lgkmcnt(12)
	v_mfma_f32_16x16x32_bf16 v[28:31], v[160:163], v[16:19], v[28:31]
	ds_read_b128 v[244:247], v107 offset:23616
	ds_read_b128 v[112:115], v107 offset:23680
	s_waitcnt lgkmcnt(13)
	v_mfma_f32_16x16x32_bf16 v[36:39], v[164:167], v[20:23], v[24:27]
	s_waitcnt lgkmcnt(12)
	v_mfma_f32_16x16x32_bf16 v[36:39], v[168:171], v[16:19], v[36:39]
	s_waitcnt lgkmcnt(11)
	v_mfma_f32_16x16x32_bf16 v[44:47], v[172:175], v[20:23], v[24:27]
	s_waitcnt lgkmcnt(10)
	v_mfma_f32_16x16x32_bf16 v[44:47], v[180:183], v[16:19], v[44:47]
	s_waitcnt lgkmcnt(9)
	v_mfma_f32_16x16x32_bf16 v[24:27], v[196:199], v[20:23], v[24:27]
	s_waitcnt lgkmcnt(8)
	v_mfma_f32_16x16x32_bf16 v[24:27], v[200:203], v[16:19], v[24:27]
	s_waitcnt lgkmcnt(7)
	v_mfma_f32_16x16x32_bf16 v[56:59], v[204:207], v[20:23], 0
	s_waitcnt lgkmcnt(6)
	v_mfma_f32_16x16x32_bf16 v[56:59], v[224:227], v[16:19], v[56:59]
	s_waitcnt lgkmcnt(5)
	v_mfma_f32_16x16x32_bf16 v[60:63], v[228:231], v[20:23], 0
	s_waitcnt lgkmcnt(4)
	v_mfma_f32_16x16x32_bf16 v[60:63], v[232:235], v[16:19], v[60:63]
	s_waitcnt lgkmcnt(3)
	v_mfma_f32_16x16x32_bf16 v[64:67], v[236:239], v[20:23], 0
	s_waitcnt lgkmcnt(2)
	v_mfma_f32_16x16x32_bf16 v[64:67], v[240:243], v[16:19], v[64:67]
	s_waitcnt lgkmcnt(1)
	v_mfma_f32_16x16x32_bf16 v[20:23], v[244:247], v[20:23], 0
	s_waitcnt lgkmcnt(0)
	v_mfma_f32_16x16x32_bf16 v[16:19], v[112:115], v[16:19], v[20:23]
	s_nop 5
	v_max_f32_e32 v20, v55, v55
	v_max_f32_e32 v21, v54, v54
	v_max_f32_e32 v20, v21, v20
	v_max_f32_e32 v21, v49, v49
	v_max_f32_e32 v22, v48, v48
	v_max_f32_e32 v21, v22, v21
	v_max_f32_e32 v22, v51, v51
	v_max_f32_e32 v23, v50, v50
	v_max3_f32 v20, v52, v53, v20
	v_max_f32_e32 v22, v23, v22
	v_max3_f32 v20, v20, v21, v22
	v_max_f32_e32 v21, v41, v41
	v_max_f32_e32 v22, v40, v40
	v_max_f32_e32 v21, v22, v21
	v_max_f32_e32 v22, v43, v43
	v_max_f32_e32 v23, v42, v42
	v_max_f32_e32 v22, v23, v22
	v_max3_f32 v20, v20, v21, v22
	v_max_f32_e32 v21, v33, v33
	v_max_f32_e32 v22, v32, v32
	v_max_f32_e32 v21, v22, v21
	v_max_f32_e32 v22, v35, v35
	v_max_f32_e32 v23, v34, v34
	v_max_f32_e32 v22, v23, v22
	v_max3_f32 v20, v20, v21, v22
	v_max_f32_e32 v21, v29, v29
	v_max_f32_e32 v22, v28, v28
	v_max_f32_e32 v21, v22, v21
	v_max_f32_e32 v22, v31, v31
	v_max_f32_e32 v23, v30, v30
	v_max_f32_e32 v22, v23, v22
	v_max3_f32 v20, v20, v21, v22
	v_max_f32_e32 v21, v37, v37
	v_max_f32_e32 v22, v36, v36
	v_max_f32_e32 v21, v22, v21
	v_max_f32_e32 v22, v39, v39
	v_max_f32_e32 v23, v38, v38
	v_max_f32_e32 v22, v23, v22
	v_max3_f32 v20, v20, v21, v22
	v_max_f32_e32 v21, v45, v45
	v_max_f32_e32 v22, v44, v44
	v_max_f32_e32 v21, v22, v21
	v_max_f32_e32 v22, v47, v47
	v_max_f32_e32 v23, v46, v46
	v_max_f32_e32 v22, v23, v22
	v_max3_f32 v20, v20, v21, v22
	v_max_f32_e32 v21, v25, v25
	v_max_f32_e32 v22, v24, v24
	v_max_f32_e32 v21, v22, v21
	v_max_f32_e32 v22, v27, v27
	v_max_f32_e32 v23, v26, v26
	v_max_f32_e32 v22, v23, v22
	v_max3_f32 v20, v20, v21, v22
	v_max_f32_e32 v21, v57, v57
	v_max_f32_e32 v22, v56, v56
	v_max_f32_e32 v21, v22, v21
	v_max_f32_e32 v22, v59, v59
	v_max_f32_e32 v23, v58, v58
	v_max_f32_e32 v22, v23, v22
	v_max3_f32 v20, v20, v21, v22
	v_max_f32_e32 v21, v61, v61
	v_max_f32_e32 v22, v60, v60
	v_max_f32_e32 v21, v22, v21
	v_max_f32_e32 v22, v63, v63
	v_max_f32_e32 v23, v62, v62
	v_max_f32_e32 v22, v23, v22
	v_max3_f32 v20, v20, v21, v22
	v_max_f32_e32 v21, v65, v65
	v_max_f32_e32 v22, v64, v64
	v_max_f32_e32 v21, v22, v21
	v_max_f32_e32 v22, v67, v67
	v_max_f32_e32 v23, v66, v66
	v_max_f32_e32 v22, v23, v22
	v_max3_f32 v20, v20, v21, v22
	v_max_f32_e32 v21, v17, v17
	v_max_f32_e32 v22, v16, v16
	v_max_f32_e32 v21, v22, v21
	v_max_f32_e32 v22, v19, v19
	v_max_f32_e32 v23, v18, v18
	v_max_f32_e32 v22, v23, v22
	v_max3_f32 v20, v20, v21, v22
	ds_bpermute_b32 v21, v212, v20
	s_waitcnt lgkmcnt(0)
	v_max_f32_e32 v21, v21, v21
	v_max_f32_e32 v20, v20, v21
	ds_bpermute_b32 v21, v176, v20
	s_waitcnt lgkmcnt(0)
; __device__ __forceinline__ unsigned pk2(float lo, float hi) { return pg8::cvt_pk_bf16(lo, hi); }
; template <int NKT, int VSTR, bool SINK>
; __device__ __forceinline__ void attn_core(LAS const unsigned char* kb_, LAS const unsigned char* vb_, bf16x8 q0, bf16x8 q1, float sk, unsigned mskbits, int fr, f32x4 (&o)[4]) {
;     ...
;     if (SINK) mx = fmaxf(mx, sk);
;     float sum = 0.f;
; #pragma unroll
;     for (int kt = 0; kt < NKT; ++kt)
; #pragma unroll
;         for (int r = 0; r < 4; ++r) { const float p = __builtin_amdgcn_exp2f(S[kt][r] - mx); S[kt][r] = p; sum += p; }
;     sum += __shfl_xor(sum, 16); sum += __shfl_xor(sum, 32);
;     if (SINK) sum += __builtin_amdgcn_exp2f(sk - mx);
;     const float inv = 1.0f / sum;
;     bf16x8 pf[NKT / 2];
; #pragma unroll
;     for (int kb = 0; kb < NKT / 2; ++kb) {
;         v4u w; w.x = pk2(S[2 * kb][0], S[2 * kb][1]); w.y = pk2(S[2 * kb][2], S[2 * kb][3]); w.z = pk2(S[2 * kb + 1][0], S[2 * kb + 1][1]); w.w = pk2(S[2 * kb + 1][2], S[2 * kb + 1][3]);
;         pf[kb] = __builtin_bit_cast(bf16x8, w);
;     }
	v_max3_f32 v20, v20, v21, v70
	v_sub_f32_e32 v21, v52, v20
	v_exp_f32_e32 v21, v21
	v_sub_f32_e32 v23, v53, v20
	v_exp_f32_e32 v23, v23
	v_sub_f32_e32 v52, v54, v20
	v_exp_f32_e32 v52, v52
	v_sub_f32_e32 v53, v55, v20
	v_exp_f32_e32 v53, v53
	v_sub_f32_e32 v48, v48, v20
	v_add_f32_e32 v22, 0, v21
	v_exp_f32_e32 v48, v48
	v_sub_f32_e32 v49, v49, v20
	v_add_f32_e32 v22, v23, v22
	v_exp_f32_e32 v49, v49
	v_sub_f32_e32 v50, v50, v20
	v_add_f32_e32 v22, v52, v22
	v_exp_f32_e32 v50, v50
	v_sub_f32_e32 v51, v51, v20
	v_add_f32_e32 v22, v53, v22
	v_exp_f32_e32 v51, v51
	v_sub_f32_e32 v40, v40, v20
	v_add_f32_e32 v22, v48, v22
	v_exp_f32_e32 v40, v40
	v_sub_f32_e32 v41, v41, v20
	v_add_f32_e32 v22, v49, v22
	v_exp_f32_e32 v41, v41
	v_sub_f32_e32 v42, v42, v20
	v_add_f32_e32 v22, v50, v22
	v_exp_f32_e32 v42, v42
	v_sub_f32_e32 v43, v43, v20
	v_add_f32_e32 v22, v51, v22
	v_exp_f32_e32 v43, v43
	v_sub_f32_e32 v32, v32, v20
	v_add_f32_e32 v22, v40, v22
	v_exp_f32_e32 v54, v32
	v_sub_f32_e32 v32, v33, v20
	v_add_f32_e32 v22, v41, v22
	v_exp_f32_e32 v55, v32
	v_sub_f32_e32 v32, v34, v20
	v_add_f32_e32 v22, v42, v22
	v_exp_f32_e32 v70, v32
	v_sub_f32_e32 v32, v35, v20
	v_add_f32_e32 v22, v43, v22
	v_exp_f32_e32 v35, v32
	v_sub_f32_e32 v28, v28, v20
	v_add_f32_e32 v22, v54, v22
	v_exp_f32_e32 v28, v28
	v_sub_f32_e32 v29, v29, v20
	v_add_f32_e32 v22, v55, v22
	v_exp_f32_e32 v29, v29
	v_sub_f32_e32 v30, v30, v20
	v_add_f32_e32 v22, v70, v22
	v_exp_f32_e32 v30, v30
	v_sub_f32_e32 v31, v31, v20
	v_add_f32_e32 v22, v35, v22
	v_exp_f32_e32 v31, v31
	v_sub_f32_e32 v32, v36, v20
	v_add_f32_e32 v22, v28, v22
	v_exp_f32_e32 v71, v32
	v_sub_f32_e32 v32, v37, v20
	v_add_f32_e32 v22, v29, v22
	v_exp_f32_e32 v72, v32
	v_sub_f32_e32 v32, v38, v20
	v_add_f32_e32 v22, v30, v22
	v_exp_f32_e32 v73, v32
	v_sub_f32_e32 v32, v39, v20
	v_add_f32_e32 v22, v31, v22
	v_exp_f32_e32 v74, v32
	v_sub_f32_e32 v32, v44, v20
	v_add_f32_e32 v22, v71, v22
	v_exp_f32_e32 v44, v32
	v_sub_f32_e32 v32, v45, v20
	v_add_f32_e32 v22, v72, v22
	v_exp_f32_e32 v45, v32
	v_sub_f32_e32 v32, v46, v20
	v_add_f32_e32 v22, v73, v22
	v_exp_f32_e32 v46, v32
	v_sub_f32_e32 v32, v47, v20
	v_add_f32_e32 v22, v74, v22
	v_exp_f32_e32 v47, v32
	v_sub_f32_e32 v24, v24, v20
	v_add_f32_e32 v22, v44, v22
	v_exp_f32_e32 v75, v24
	v_sub_f32_e32 v24, v25, v20
	v_add_f32_e32 v22, v45, v22
	v_exp_f32_e32 v76, v24
	v_sub_f32_e32 v24, v26, v20
	v_add_f32_e32 v22, v46, v22
	v_exp_f32_e32 v77, v24
	v_sub_f32_e32 v24, v27, v20
	v_add_f32_e32 v22, v47, v22
	v_exp_f32_e32 v27, v24
	v_sub_f32_e32 v24, v56, v20
	v_add_f32_e32 v22, v75, v22
	v_exp_f32_e32 v56, v24
	v_sub_f32_e32 v24, v57, v20
	v_add_f32_e32 v22, v76, v22
	v_exp_f32_e32 v57, v24
	v_sub_f32_e32 v24, v58, v20
	v_add_f32_e32 v22, v77, v22
	v_exp_f32_e32 v58, v24
	v_sub_f32_e32 v24, v59, v20
	v_add_f32_e32 v22, v27, v22
	v_exp_f32_e32 v59, v24
	v_sub_f32_e32 v24, v60, v20
	v_add_f32_e32 v22, v56, v22
	v_exp_f32_e32 v60, v24
	v_sub_f32_e32 v24, v61, v20
	v_add_f32_e32 v22, v57, v22
	v_exp_f32_e32 v61, v24
	v_sub_f32_e32 v24, v62, v20
	v_add_f32_e32 v22, v58, v22
	v_exp_f32_e32 v62, v24
	v_sub_f32_e32 v24, v63, v20
	v_add_f32_e32 v22, v59, v22
	v_exp_f32_e32 v63, v24
	v_sub_f32_e32 v24, v64, v20
	v_add_f32_e32 v22, v60, v22
	v_exp_f32_e32 v64, v24
	v_sub_f32_e32 v24, v65, v20
	v_add_f32_e32 v22, v61, v22
	v_exp_f32_e32 v65, v24
	v_sub_f32_e32 v24, v66, v20
	v_add_f32_e32 v22, v62, v22
	v_exp_f32_e32 v66, v24
	v_sub_f32_e32 v24, v67, v20
	v_add_f32_e32 v22, v63, v22
	v_exp_f32_e32 v67, v24
	v_sub_f32_e32 v16, v16, v20
	v_add_f32_e32 v22, v64, v22
	v_exp_f32_e32 v78, v16
	v_sub_f32_e32 v17, v17, v20
	v_add_f32_e32 v22, v65, v22
	v_exp_f32_e32 v79, v17
	v_sub_f32_e32 v17, v18, v20
	v_add_f32_e32 v22, v66, v22
	v_exp_f32_e32 v107, v17
	v_sub_f32_e32 v17, v19, v20
	v_add_f32_e32 v22, v67, v22
	v_exp_f32_e32 v19, v17
	v_add_f32_e32 v16, v78, v22
	v_add_f32_e32 v16, v79, v16
	v_add_f32_e32 v16, v107, v16
	v_add_f32_e32 v16, v19, v16
	ds_bpermute_b32 v17, v212, v16
	v_cvt_pk_bf16_f32 v36, v21, v23
	v_cvt_pk_bf16_f32 v37, v52, v53
	v_cvt_pk_bf16_f32 v38, v48, v49
	v_cvt_pk_bf16_f32 v39, v50, v51
	s_waitcnt lgkmcnt(0)
	v_add_f32_e32 v16, v16, v17
	ds_bpermute_b32 v17, v176, v16
	v_cvt_pk_bf16_f32 v32, v40, v41
	v_cvt_pk_bf16_f32 v33, v42, v43
	v_cvt_pk_bf16_f32 v34, v54, v55
	v_cvt_pk_bf16_f32 v35, v70, v35
	s_waitcnt lgkmcnt(0)
	v_add_f32_e32 v16, v16, v17
	v_fma_f32 v17, v69, s2, -v20
	v_exp_f32_e32 v17, v17
	v_cvt_pk_bf16_f32 v28, v28, v29
	v_cvt_pk_bf16_f32 v29, v30, v31
	v_cvt_pk_bf16_f32 v30, v71, v72
	v_cvt_pk_bf16_f32 v31, v73, v74
	v_cvt_pk_bf16_f32 v24, v44, v45
	s_nop 0
	v_add_f32_e32 v69, v17, v16
	v_div_scale_f32 v40, s[0:1], v69, v69, 1.0
	v_rcp_f32_e32 v41, v40
	v_cvt_pk_bf16_f32 v25, v46, v47
	v_cvt_pk_bf16_f32 v26, v75, v76
	v_cvt_pk_bf16_f32 v27, v77, v27
	v_cvt_pk_bf16_f32 v20, v56, v57
	v_cvt_pk_bf16_f32 v21, v58, v59
	s_nop 0
	v_fma_f32 v42, -v40, v41, 1.0
	v_fmac_f32_e32 v41, v42, v41
	v_div_scale_f32 v42, vcc, 1.0, v69, 1.0
	v_mul_f32_e32 v43, v42, v41
	v_fma_f32 v44, -v40, v43, v42
	v_fmac_f32_e32 v43, v44, v41
	v_fma_f32 v40, -v40, v43, v42
	v_cvt_pk_bf16_f32 v22, v60, v61
	v_cvt_pk_bf16_f32 v23, v62, v63
	v_cvt_pk_bf16_f32 v16, v64, v65
	v_cvt_pk_bf16_f32 v17, v66, v67
	v_cvt_pk_bf16_f32 v18, v78, v79
	v_cvt_pk_bf16_f32 v19, v107, v19
	v_div_fmas_f32 v40, v40, v41, v43
	s_waitcnt lgkmcnt(0)
; #define LAS __attribute__((address_space(3)))
; __device__ __forceinline__ float quad_sum(float s) { s += __shfl_xor(s, 16); s += __shfl_xor(s, 32); return s; }
; __device__ __forceinline__ float sq4(const f32x4 a) { return (a[0] * a[0] + a[1] * a[1]) + (a[2] * a[2] + a[3] * a[3]); }
; #define LAS __attribute__((address_space(3)))
; __device__ __forceinline__ unsigned pk2(float lo, float hi) { return pg8::cvt_pk_bf16(lo, hi); }
; __device__ __forceinline__ f32x4 mfma16(bf16x8 a, bf16x8 b, f32x4 c) { return __builtin_amdgcn_mfma_f32_16x16x32_bf16(a, b, c, 0, 0, 0); }
; template <int NKT, int VSTR, bool SINK>
; __device__ __forceinline__ void attn_core(LAS const unsigned char* kb_, LAS const unsigned char* vb_, bf16x8 q0, bf16x8 q1, float sk, unsigned mskbits, int fr, f32x4 (&o)[4]) {
;     ...
; #pragma unroll
;     for (int dt = 0; dt < 4; ++dt) {
;         f32x4 acc = (f32x4){0.f, 0.f, 0.f, 0.f};
; #pragma unroll
;         for (int kb = 0; kb < NKT / 2; ++kb) {
;             const bf16x8 vf = *(LAS const bf16x8*)(vb_ + dt * 16 * VSTR + kb * 64);
;             acc = mfma16(vf, pf[kb], acc);
;         }
;         o[dt] = acc * inv;
;     }
; template <bool DO_SWA, bool DO_MEM>
; __device__ __forceinline__ void attn_unit(const Args& a, unsigned char* ws, LAS unsigned char* lds, int l, int tid_in, int lane_in, int wave, int unit) {
;     ...
; #pragma unroll
;                 for (int dt = 0; dt < 4; ++dt) { ssq += pg8::sq4(o[dt]); osv[hh][dt] = (v2u){pk2(o[dt][0], o[dt][1]), pk2(o[dt][2], o[dt][3])}; }
;             }
;             ssq = pg8::quad_sum(ssq);
;             if (fq == 0) red_a[g * 64 + qs * 16 + fr] = ssq;
	ds_read_b128 v[112:115], v106 offset:55296
	ds_read_b128 v[116:119], v106 offset:55360
	ds_read_b128 v[120:123], v106 offset:61760
	ds_read_b128 v[124:127], v105 offset:12864
	ds_read_b128 v[128:131], v106 offset:55424
	ds_read_b128 v[132:135], v106 offset:55488
	ds_read_b128 v[136:139], v106 offset:55552
	ds_read_b128 v[140:143], v106 offset:55616
	ds_read_b128 v[144:147], v106 offset:61696
	ds_read_b128 v[160:163], v106 offset:61824
	ds_read_b128 v[164:167], v106 offset:61888
	ds_read_b128 v[168:171], v106 offset:61952
	ds_read_b128 v[172:175], v106 offset:62016
	ds_read_b128 v[180:183], v105 offset:12800
	s_waitcnt lgkmcnt(13)
	v_mfma_f32_16x16x32_bf16 v[42:45], v[112:115], v[36:39], 0
	ds_read_b128 v[196:199], v105 offset:12928
	v_div_fixup_f32 v40, v40, v69, 1.0
	s_waitcnt lgkmcnt(13)
	v_mfma_f32_16x16x32_bf16 v[42:45], v[116:119], v[32:35], v[42:45]
	ds_read_b128 v[200:203], v105 offset:12992
	s_waitcnt lgkmcnt(11)
	v_mfma_f32_16x16x32_bf16 v[42:45], v[128:131], v[28:31], v[42:45]
	ds_read_b128 v[204:207], v105 offset:13056
	ds_read_b128 v[224:227], v105 offset:13120
	s_waitcnt lgkmcnt(12)
	v_mfma_f32_16x16x32_bf16 v[42:45], v[132:135], v[24:27], v[42:45]
	ds_read_b128 v[228:231], v105 offset:19200
	s_waitcnt lgkmcnt(12)
	v_mfma_f32_16x16x32_bf16 v[42:45], v[136:139], v[20:23], v[42:45]
	ds_read_b128 v[232:235], v105 offset:19264
	s_waitcnt lgkmcnt(12)
	v_mfma_f32_16x16x32_bf16 v[44:47], v[140:143], v[16:19], v[42:45]
	s_nop 7
	v_pk_mul_f32 v[42:43], v[46:47], v[40:41] op_sel_hi:[1,0]
	ds_read_b128 v[236:239], v105 offset:19328
	s_waitcnt lgkmcnt(12)
	v_mfma_f32_16x16x32_bf16 v[46:49], v[144:147], v[36:39], 0
	v_mul_f32_e64 v44, v44, v40
	v_mul_f32_e64 v45, v45, v40
	v_mfma_f32_16x16x32_bf16 v[46:49], v[120:123], v[32:35], v[46:49]
	ds_read_b128 v[240:243], v105 offset:19392
	s_waitcnt lgkmcnt(12)
	v_mfma_f32_16x16x32_bf16 v[46:49], v[160:163], v[28:31], v[46:49]
	ds_read_b128 v[244:247], v105 offset:19456
	s_waitcnt lgkmcnt(12)
	v_mfma_f32_16x16x32_bf16 v[46:49], v[164:167], v[24:27], v[46:49]
	ds_read_b128 v[112:115], v105 offset:19520
	s_waitcnt lgkmcnt(12)
	v_mfma_f32_16x16x32_bf16 v[46:49], v[168:171], v[20:23], v[46:49]
	s_waitcnt lgkmcnt(11)
	v_mfma_f32_16x16x32_bf16 v[48:51], v[172:175], v[16:19], v[46:49]
	s_nop 7
	v_pk_mul_f32 v[46:47], v[50:51], v[40:41] op_sel_hi:[1,0]
	s_waitcnt lgkmcnt(10)
	v_mfma_f32_16x16x32_bf16 v[50:53], v[180:183], v[36:39], 0
	v_mul_f32_e64 v48, v48, v40
	v_mul_f32_e64 v49, v49, v40
	v_mfma_f32_16x16x32_bf16 v[50:53], v[124:127], v[32:35], v[50:53]
	s_waitcnt lgkmcnt(9)
	v_mfma_f32_16x16x32_bf16 v[50:53], v[196:199], v[28:31], v[50:53]
	s_waitcnt lgkmcnt(8)
	v_mfma_f32_16x16x32_bf16 v[50:53], v[200:203], v[24:27], v[50:53]
	s_waitcnt lgkmcnt(7)
	v_mfma_f32_16x16x32_bf16 v[50:53], v[204:207], v[20:23], v[50:53]
	s_waitcnt lgkmcnt(6)
	v_mfma_f32_16x16x32_bf16 v[50:53], v[224:227], v[16:19], v[50:53]
	s_nop 7
	v_pk_mul_f32 v[54:55], v[40:41], v[52:53] op_sel_hi:[0,1]
	v_pk_mul_f32 v[56:57], v[40:41], v[50:51] op_sel_hi:[0,1]
	s_waitcnt lgkmcnt(5)
	v_mfma_f32_16x16x32_bf16 v[36:39], v[228:231], v[36:39], 0
	s_waitcnt lgkmcnt(4)
	v_mfma_f32_16x16x32_bf16 v[32:35], v[232:235], v[32:35], v[36:39]
	s_waitcnt lgkmcnt(3)
	v_mfma_f32_16x16x32_bf16 v[28:31], v[236:239], v[28:31], v[32:35]
	s_waitcnt lgkmcnt(2)
	v_mfma_f32_16x16x32_bf16 v[24:27], v[240:243], v[24:27], v[28:31]
	s_waitcnt lgkmcnt(1)
	v_mfma_f32_16x16x32_bf16 v[20:23], v[244:247], v[20:23], v[24:27]
	v_cvt_pk_bf16_f32 v106, v44, v45
	v_cvt_pk_bf16_f32 v105, v42, v43
	s_waitcnt lgkmcnt(0)
	v_mfma_f32_16x16x32_bf16 v[16:19], v[112:115], v[16:19], v[20:23]
	s_nop 2
	v_mul_f32_e32 v20, v45, v45
	v_mul_f32_e32 v21, v43, v43
	v_fmac_f32_e32 v20, v44, v44
	v_fmac_f32_e32 v21, v42, v42
	v_add_f32_e32 v20, v20, v21
	v_mul_f32_e32 v21, v49, v49
	v_mul_f32_e32 v22, v47, v47
	v_fmac_f32_e32 v21, v48, v48
	v_fmac_f32_e32 v22, v46, v46
	v_add_f32_e32 v20, v68, v20
	v_add_f32_e32 v21, v21, v22
	v_add_f32_e32 v20, v21, v20
	v_mul_f32_e32 v21, v57, v57
	v_mul_f32_e32 v22, v55, v55
	v_fmac_f32_e32 v21, v56, v56
	v_fmac_f32_e32 v22, v54, v54
	v_pk_mul_f32 v[18:19], v[40:41], v[18:19] op_sel_hi:[0,1]
	v_pk_mul_f32 v[16:17], v[40:41], v[16:17] op_sel_hi:[0,1]
	v_add_f32_e32 v21, v21, v22
	v_add_f32_e32 v20, v21, v20
	v_mul_f32_e32 v21, v17, v17
	v_mul_f32_e32 v22, v19, v19
	v_fmac_f32_e32 v21, v16, v16
	v_fmac_f32_e32 v22, v18, v18
	v_add_f32_e32 v21, v21, v22
	v_add_f32_e32 v20, v20, v21
	v_cvt_pk_bf16_f32 v112, v48, v49
	v_cvt_pk_bf16_f32 v107, v46, v47
	v_cvt_pk_bf16_f32 v114, v56, v57
	v_cvt_pk_bf16_f32 v113, v54, v55
	v_cvt_pk_bf16_f32 v116, v16, v17
	ds_bpermute_b32 v16, v212, v20
	v_cvt_pk_bf16_f32 v115, v18, v19
	s_waitcnt lgkmcnt(0)
	v_add_f32_e32 v16, v20, v16
	ds_bpermute_b32 v17, v176, v16
	s_and_saveexec_b64 s[0:1], s[36:37]
	s_cbranch_execz .LBB0_292
	v_readlane_b32 s2, v251, 30
	s_waitcnt lgkmcnt(0)
	v_add_f32_e32 v16, v16, v17
	v_lshl_add_u32 v18, v210, 2, s2
	ds_write_b32 v18, v16
